# ph_prep: q/k norm weight vectors fetched once per token group into path-private registers instead of 18 dependent load+wait round trips in each output stage (both layers)
# baseline (speedup 1.0000x reference)
; __device__ __forceinline__ void ph_prep(bf16_t* Z, const bf16_t* WUQ, const bf16_t* WUKV, const bf16_t* D64, const float* qkq, const float* qkk,
;                                         bf16_t* Q, bf16_t* Kb, bf16_t* Vb, bf16_t* F1lat, bf16_t* F1ctx, unsigned char* lds_) { PH_IDS;
;     ...
;         int rowc[3], rl[3]; bool valid[3];
; #pragma unroll
;         for (int tt = 0; tt < 3; ++tt) { const int o = 16 * (3 * pass3 + tt) + c16; valid[tt] = o < 72; rl[tt] = valid[tt] ? o : 71; rowc[tt] = row0 + rl[tt]; }
;         if (wid < 4) {
;     ...
;                     const int row = rowc[tt]; const bool lat = row < RL; const int b = row_batch(row), t = lat ? (row & 2047) : ((row - RL) & 255), ki = lat ? 256 + t : t;
;                     if (pass == 0) {
;                         float s1 = ssq[tt]; s1 += __shfl_xor(s1, 16); s1 += __shfl_xor(s1, 32);
;                         rstd[tt] = rsqrtf(s1 * (1.f / 128) + EPS);
;                         float kr[2][4];
; #pragma unroll
;                         for (int e = 0; e < 2; ++e) { const fa::u32x2 w = *(const LAS fa::u32x2*)(sm + O_KV + rl[tt] * P_KV + (128 + 16 * e + 4 * kq) * 2);
;                             kr[e][0] = __uint_as_float(w.x << 16); kr[e][1] = __uint_as_float(w.x & 0xffff0000u); kr[e][2] = __uint_as_float(w.y << 16); kr[e][3] = __uint_as_float(w.y & 0xffff0000u); }
;                         float ss = 0.f;
; #pragma unroll
;                         for (int nt = 0; nt < 4; ++nt)
; #pragma unroll
;                             for (int r = 0; r < 4; ++r) { acc[nt][tt][r] *= rstd[tt]; ss += acc[nt][tt][r] * acc[nt][tt][r]; }
; #pragma unroll
;                         for (int e = 0; e < 2; ++e)
; #pragma unroll
;                             for (int r = 0; r < 4; ++r) ss += kr[e][r] * kr[e][r];
;                         ss += __shfl_xor(ss, 16); ss += __shfl_xor(ss, 32);
;                         const float fac = rsqrtf(ss * (1.f / 96) + EPS);
;                         bf16_t* ko = Kb + ((size_t)(b * 4 + h) * 2304 + ki) * 96 + 4 * kq;
; #pragma unroll
;                         for (int nt = 0; nt < 6; ++nt) {
;                             const f32x4 w = *(const f32x4*)(qkk + 16 * nt + 4 * kq);
;                             float v[4];
; #pragma unroll
;                             for (int r = 0; r < 4; ++r) v[r] = (nt < 4 ? acc[nt < 4 ? nt : 0][tt][r] : kr[nt < 4 ? 0 : nt - 4][r]) * fac * w[r];
.LBB0_491:
	s_add_i32 s59, s60, 16
	v_or_b32_e32 v18, s59, v158
	v_cmp_gt_u32_e64 s[10:11], s43, v18
	s_add_i32 s58, s60, 32
	v_or_b32_e32 v198, s60, v158
	v_cndmask_b32_e64 v199, v176, v18, s[10:11]
	v_or_b32_e32 v18, s58, v158
	v_cmp_gt_u32_e64 s[8:9], s43, v18
	v_add_u32_e32 v192, s57, v198
	v_add_u32_e32 v188, s57, v199
	v_cndmask_b32_e64 v200, v176, v18, s[8:9]
	v_add_u32_e32 v184, s57, v200
	v_add_u32_e32 v18, 0xffffc000, v192
	v_and_b32_e32 v19, 63, v192
	v_add_u32_e32 v20, 0xffffc000, v188
	v_and_b32_e32 v21, 63, v188
	v_add_u32_e32 v22, 0xffffc000, v184
	v_and_b32_e32 v23, 63, v184
	v_mov_b32_e32 v180, v197
	v_mov_b32_e32 v181, v196
	v_mov_b32_e32 v182, v195
	s_and_b64 vcc, exec, s[22:23]
	v_cmp_gt_i32_e64 s[12:13], s50, v192
	v_ashrrev_i32_e32 v193, 11, v192
	v_cmp_gt_i32_e64 s[14:15], s50, v188
	v_ashrrev_i32_e32 v189, 11, v188
	v_cmp_gt_i32_e64 s[16:17], s50, v184
	v_ashrrev_i32_e32 v185, 11, v184
	v_lshrrev_b32_e32 v194, 8, v18
	v_cvt_f32_ubyte0_e32 v191, v19
	v_lshrrev_b32_e32 v190, 8, v20
	v_cvt_f32_ubyte0_e32 v187, v21
	v_lshrrev_b32_e32 v186, 8, v22
	v_cvt_f32_ubyte0_e32 v183, v23
	s_mov_b64 s[18:19], -1
	s_cbranch_vccz .LBB0_571
	global_load_dwordx4 v[2:5], v[108:109], off
	global_load_dwordx4 v[6:9], v[108:109], off offset:64
	global_load_dwordx4 v[10:13], v[108:109], off offset:128
	global_load_dwordx4 v[14:17], v[108:109], off offset:192
	global_load_dwordx4 v[126:129], v[108:109], off offset:256
	global_load_dwordx4 v[130:133], v[108:109], off offset:320
	v_cndmask_b32_e64 v19, v177, v178, s[12:13]
	v_and_b32_e32 v22, v19, v192
	v_cndmask_b32_e64 v18, v194, v193, s[12:13]
	v_add_u32_e32 v19, 0x100, v22
	v_cndmask_b32_e64 v100, v22, v19, s[12:13]
	v_lshl_add_u32 v18, v18, 2, s42
	v_mad_i64_i32 v[18:19], s[18:19], v18, s51, v[100:101]
	v_lshlrev_b64 v[20:21], 7, v[18:19]
	v_mad_u64_u32 v[140:141], s[18:19], v18, s52, v[106:107]
	v_lshrrev_b32_e32 v18, 6, v22
	v_cvt_f32_ubyte0_e32 v18, v18
	v_mad_i32_i24 v141, v19, s52, v141
	v_mul_f32_e32 v19, v167, v18
	v_mul_f32_e32 v19, 0.15915494, v19
	v_cos_f32_e32 v204, v19
	v_sin_f32_e32 v205, v19
	v_mul_f32_e32 v19, v166, v18
	v_mul_f32_e32 v19, 0.15915494, v19
	v_cos_f32_e32 v206, v19
	v_sin_f32_e32 v207, v19
	v_mul_f32_e32 v19, v165, v18
	v_mul_f32_e32 v18, v164, v18
	v_mul_f32_e32 v18, 0.15915494, v18
	v_cos_f32_e32 v210, v18
	v_sin_f32_e32 v211, v18
	v_mul_f32_e32 v18, v164, v191
	v_mul_f32_e32 v18, 0.15915494, v18
	v_cos_f32_e32 v212, v18
	v_sin_f32_e32 v213, v18
	v_mul_f32_e32 v18, v165, v191
	v_mul_f32_e32 v18, 0.15915494, v18
	v_cos_f32_e32 v214, v18
	v_sin_f32_e32 v215, v18
	v_mul_f32_e32 v18, v166, v191
	v_mul_f32_e32 v19, 0.15915494, v19
	v_mul_f32_e32 v18, 0.15915494, v18
	v_cos_f32_e32 v208, v19
	v_sin_f32_e32 v209, v19
	v_cos_f32_e32 v216, v18
	v_sin_f32_e32 v217, v18
	v_mul_f32_e32 v18, v167, v191
	v_cndmask_b32_e64 v19, v177, v178, s[14:15]
	v_mul_f32_e32 v18, 0.15915494, v18
	v_and_b32_e32 v22, v19, v188
	v_cos_f32_e32 v218, v18
	v_sin_f32_e32 v219, v18
	v_cndmask_b32_e64 v18, v190, v189, s[14:15]
	v_add_u32_e32 v19, 0x100, v22
	v_cndmask_b32_e64 v100, v22, v19, s[14:15]
	v_lshl_add_u32 v18, v18, 2, s42
	v_mad_i64_i32 v[18:19], s[18:19], v18, s51, v[100:101]
	v_lshl_add_u64 v[138:139], v[104:105], 0, v[20:21]
	v_lshlrev_b64 v[20:21], 7, v[18:19]
	v_mad_u64_u32 v[144:145], s[18:19], v18, s52, v[106:107]
	v_lshrrev_b32_e32 v18, 6, v22
	v_cvt_f32_ubyte0_e32 v18, v18
	v_mad_i32_i24 v145, v19, s52, v145
	v_mul_f32_e32 v19, v167, v18
	v_mul_f32_e32 v19, 0.15915494, v19
	v_cos_f32_e32 v220, v19
	v_sin_f32_e32 v221, v19
	v_mul_f32_e32 v19, v166, v18
	v_mul_f32_e32 v19, 0.15915494, v19
	v_cos_f32_e32 v222, v19
	v_sin_f32_e32 v223, v19
	v_mul_f32_e32 v19, v165, v18
	v_mul_f32_e32 v18, v164, v18
	v_mul_f32_e32 v18, 0.15915494, v18
	v_cos_f32_e32 v226, v18
	v_sin_f32_e32 v227, v18
	v_mul_f32_e32 v18, v164, v187
	v_mul_f32_e32 v18, 0.15915494, v18
	v_cos_f32_e32 v228, v18
	v_sin_f32_e32 v229, v18
	v_mul_f32_e32 v18, v165, v187
	v_mul_f32_e32 v18, 0.15915494, v18
	v_cos_f32_e32 v230, v18
	v_sin_f32_e32 v231, v18
	v_mul_f32_e32 v18, v166, v187
	v_mul_f32_e32 v19, 0.15915494, v19
	v_mul_f32_e32 v18, 0.15915494, v18
	v_cos_f32_e32 v224, v19
	v_sin_f32_e32 v225, v19
	v_cos_f32_e32 v232, v18
	v_sin_f32_e32 v233, v18
	v_mul_f32_e32 v18, v167, v187
	v_cndmask_b32_e64 v19, v177, v178, s[16:17]
	v_mul_f32_e32 v18, 0.15915494, v18
	v_and_b32_e32 v22, v19, v184
	v_cos_f32_e32 v234, v18
	v_sin_f32_e32 v235, v18
	v_cndmask_b32_e64 v18, v186, v185, s[16:17]
	v_add_u32_e32 v19, 0x100, v22
	v_cndmask_b32_e64 v100, v22, v19, s[16:17]
	v_lshl_add_u32 v18, v18, 2, s42
	v_mad_i64_i32 v[18:19], s[18:19], v18, s51, v[100:101]
	v_lshl_add_u64 v[142:143], v[104:105], 0, v[20:21]
	v_lshlrev_b64 v[20:21], 7, v[18:19]
	v_mad_u64_u32 v[148:149], s[18:19], v18, s52, v[106:107]
	v_lshrrev_b32_e32 v18, 6, v22
	v_cvt_f32_ubyte0_e32 v18, v18
	v_mad_i32_i24 v149, v19, s52, v149
	v_mul_f32_e32 v19, v167, v18
	v_mul_f32_e32 v19, 0.15915494, v19
	v_cos_f32_e32 v100, v19
	v_sin_f32_e32 v236, v19
	v_mul_f32_e32 v19, v166, v18
	v_mul_f32_e32 v19, 0.15915494, v19
	v_cos_f32_e32 v237, v19
	v_sin_f32_e32 v238, v19
	v_mul_f32_e32 v19, v165, v18
	v_mul_f32_e32 v18, v164, v18
	v_mul_f32_e32 v18, 0.15915494, v18
	v_cos_f32_e32 v241, v18
	v_sin_f32_e32 v242, v18
	v_mul_f32_e32 v18, v164, v183
	v_mul_f32_e32 v18, 0.15915494, v18
	v_cos_f32_e32 v243, v18
	v_sin_f32_e32 v244, v18
	v_mul_f32_e32 v18, v165, v183
	v_mul_f32_e32 v18, 0.15915494, v18
	v_cos_f32_e32 v245, v18
	v_sin_f32_e32 v246, v18
	v_mul_f32_e32 v18, v166, v183
	v_mul_f32_e32 v18, 0.15915494, v18
	v_cos_f32_e32 v247, v18
	v_sin_f32_e32 v248, v18
	v_mul_f32_e32 v18, v167, v183
	v_mul_f32_e32 v19, 0.15915494, v19
	v_mul_f32_e32 v18, 0.15915494, v18
	v_mul_u32_u24_e32 v201, 0x150, v198
	v_mul_u32_u24_e32 v202, 0x150, v199
	v_mul_u32_u24_e32 v203, 0x150, v200
	v_lshl_add_u64 v[146:147], v[104:105], 0, v[20:21]
	v_cos_f32_e32 v239, v19
	v_sin_f32_e32 v240, v19
	v_cos_f32_e32 v249, v18
	v_sin_f32_e32 v250, v18
	s_mov_b32 s61, 0
	s_mov_b64 s[36:37], -1
	v_mov_b32_e32 v251, 0
	v_mov_b32_e32 v252, 0
	v_mov_b32_e32 v253, 0
	v_mov_b32_e32 v197, v180
	v_mov_b32_e32 v196, v181
	v_mov_b32_e32 v195, v182
	s_branch .LBB0_495

; __device__ __forceinline__ void ph_prep(bf16_t* Z, const bf16_t* WUQ, const bf16_t* WUKV, const bf16_t* D64, const float* qkq, const float* qkk,
;                                         bf16_t* Q, bf16_t* Kb, bf16_t* Vb, bf16_t* F1lat, bf16_t* F1ctx, unsigned char* lds_) { PH_IDS;
;     ...
;                     if (pass == 0) {
.LBB0_515:
	s_andn2_b64 vcc, exec, s[18:19]
	s_cbranch_vccnz .LBB0_517
; #define LAS __attribute__((address_space(3)))
; __device__ __forceinline__ void ph_prep(bf16_t* Z, const bf16_t* WUQ, const bf16_t* WUKV, const bf16_t* D64, const float* qkq, const float* qkk,
;                                         bf16_t* Q, bf16_t* Kb, bf16_t* Vb, bf16_t* F1lat, bf16_t* F1ctx, unsigned char* lds_) { PH_IDS;
;     ...
;                         float s1 = ssq[tt]; s1 += __shfl_xor(s1, 16); s1 += __shfl_xor(s1, 32);
;                         rstd[tt] = rsqrtf(s1 * (1.f / 128) + EPS);
;                         float kr[2][4];
; #pragma unroll
;                         for (int e = 0; e < 2; ++e) { const fa::u32x2 w = *(const LAS fa::u32x2*)(sm + O_KV + rl[tt] * P_KV + (128 + 16 * e + 4 * kq) * 2);
;                             kr[e][0] = __uint_as_float(w.x << 16); kr[e][1] = __uint_as_float(w.x & 0xffff0000u); kr[e][2] = __uint_as_float(w.y << 16); kr[e][3] = __uint_as_float(w.y & 0xffff0000u); }
;                         float ss = 0.f;
; #pragma unroll
;                         for (int nt = 0; nt < 4; ++nt)
; #pragma unroll
;                             for (int r = 0; r < 4; ++r) { acc[nt][tt][r] *= rstd[tt]; ss += acc[nt][tt][r] * acc[nt][tt][r]; }
; #pragma unroll
;                         for (int e = 0; e < 2; ++e)
; #pragma unroll
;                             for (int r = 0; r < 4; ++r) ss += kr[e][r] * kr[e][r];
;                         ss += __shfl_xor(ss, 16); ss += __shfl_xor(ss, 32);
;                         const float fac = rsqrtf(ss * (1.f / 96) + EPS);
;                         bf16_t* ko = Kb + ((size_t)(b * 4 + h) * 2304 + ki) * 96 + 4 * kq;
; #pragma unroll
;                         for (int nt = 0; nt < 6; ++nt) {
;                             const f32x4 w = *(const f32x4*)(qkk + 16 * nt + 4 * kq);
;                             float v[4];
; #pragma unroll
;                             for (int r = 0; r < 4; ++r) v[r] = (nt < 4 ? acc[nt < 4 ? nt : 0][tt][r] : kr[nt < 4 ? 0 : nt - 4][r]) * fac * w[r];
;                             if (nt >= 4) rope16(v, kq, nt == 4 ? (float)(t >> 6) : (float)(t & 63), lat);
;                             fa::u32x2 o; o.x = fa::pk2(v[0], v[1]); o.y = fa::pk2(v[2], v[3]);
;                             if (valid[tt]) *(fa::u32x2*)(ko + 16 * nt) = o;
;                         }
	v_and_b32_e32 v67, 64, v179
	v_xor_b32_e32 v66, 16, v179
	v_add_u32_e32 v67, 64, v67
	v_cmp_lt_i32_e32 vcc, v66, v67
	v_xor_b32_e32 v68, 32, v179
	v_add_u32_e32 v70, v163, v201
	v_cndmask_b32_e32 v66, v179, v66, vcc
	v_lshlrev_b32_e32 v74, 2, v66
	ds_bpermute_b32 v66, v74, v253
	v_cmp_lt_i32_e32 vcc, v68, v67
	ds_read2_b64 v[70:73], v70 offset0:32 offset1:36
	s_waitcnt lgkmcnt(1)
	v_add_f32_e32 v66, v253, v66
	v_cndmask_b32_e32 v67, v179, v68, vcc
	v_lshlrev_b32_e32 v75, 2, v67
	ds_bpermute_b32 v67, v75, v66
	s_waitcnt lgkmcnt(0)
	v_add_f32_e32 v66, v66, v67
	v_fmamk_f32 v66, v66, 0x3c000000, v175
	v_mul_f32_e32 v67, 0x4b800000, v66
	v_cmp_gt_f32_e32 vcc, s53, v66
	s_nop 1
	v_cndmask_b32_e32 v66, v66, v67, vcc
	v_rsq_f32_e32 v76, v66
	v_mov_b64_e32 v[66:67], v[2:3]
	v_mov_b64_e32 v[68:69], v[4:5]
	v_mul_f32_e32 v77, 0x45800000, v76
	v_cndmask_b32_e32 v195, v76, v77, vcc
	v_mul_f32_e32 v63, v63, v195
	v_mul_f32_e32 v62, v62, v195
	v_mul_f32_e32 v76, v63, v63
	v_fmac_f32_e32 v76, v62, v62
	v_mul_f32_e32 v64, v64, v195
	v_fmac_f32_e32 v76, v64, v64
	v_mul_f32_e32 v65, v65, v195
	v_fmac_f32_e32 v76, v65, v65
	v_mul_f32_e32 v77, v58, v195
	v_fmac_f32_e32 v76, v77, v77
	v_mul_f32_e32 v78, v59, v195
	v_fmac_f32_e32 v76, v78, v78
	v_mul_f32_e32 v79, v60, v195
	v_fmac_f32_e32 v76, v79, v79
	v_mul_f32_e32 v80, v61, v195
	v_fmac_f32_e32 v76, v80, v80
	v_mul_f32_e32 v81, v54, v195
	v_fmac_f32_e32 v76, v81, v81
	v_mul_f32_e32 v82, v55, v195
	v_fmac_f32_e32 v76, v82, v82
	v_mul_f32_e32 v83, v56, v195
	v_fmac_f32_e32 v76, v83, v83
	v_mul_f32_e32 v84, v57, v195
	v_fmac_f32_e32 v76, v84, v84
	v_mul_f32_e32 v85, v50, v195
	v_fmac_f32_e32 v76, v85, v85
	v_mul_f32_e32 v86, v51, v195
	v_fmac_f32_e32 v76, v86, v86
	v_mul_f32_e32 v87, v52, v195
	v_fmac_f32_e32 v76, v87, v87
	v_mul_f32_e32 v88, v53, v195
	v_and_b32_e32 v54, 0xffff0000, v70
	v_lshlrev_b32_e32 v55, 16, v70
	v_fmac_f32_e32 v76, v88, v88
	v_pk_mul_f32 v[50:51], v[54:55], v[54:55]
	v_and_b32_e32 v56, 0xffff0000, v71
	v_add_f32_e32 v51, v51, v76
	v_lshlrev_b32_e32 v57, 16, v71
	v_add_f32_e32 v52, v50, v51
	v_pk_mul_f32 v[50:51], v[56:57], v[56:57]
	v_and_b32_e32 v58, 0xffff0000, v72
	v_add_f32_e32 v51, v51, v52
	v_lshlrev_b32_e32 v59, 16, v72
	v_add_f32_e32 v52, v50, v51
	v_pk_mul_f32 v[50:51], v[58:59], v[58:59]
	v_and_b32_e32 v60, 0xffff0000, v73
	v_add_f32_e32 v51, v51, v52
	v_lshlrev_b32_e32 v61, 16, v73
	v_add_f32_e32 v52, v50, v51
	v_pk_mul_f32 v[50:51], v[60:61], v[60:61]
	s_nop 0
	v_add_f32_e32 v51, v51, v52
	v_add_f32_e32 v50, v50, v51
	ds_bpermute_b32 v51, v74, v50
	s_waitcnt lgkmcnt(0)
	v_add_f32_e32 v50, v50, v51
	ds_bpermute_b32 v51, v75, v50
	s_waitcnt lgkmcnt(0)
	v_add_f32_e32 v50, v50, v51
	v_fmamk_f32 v50, v50, 0x3c2aaaab, v175
	v_mul_f32_e32 v51, 0x4b800000, v50
	v_cmp_gt_f32_e32 vcc, s53, v50
	s_nop 1
	v_cndmask_b32_e32 v50, v50, v51, vcc
	v_rsq_f32_e32 v50, v50
	s_nop 0
	v_mul_f32_e32 v51, 0x45800000, v50
	v_cndmask_b32_e32 v70, v50, v51, vcc
	v_mul_f32_e32 v50, v62, v70
	v_mul_f32_e32 v51, v63, v70
	v_mul_f32_e32 v50, v66, v50
	v_mul_f32_e32 v51, v67, v51
	v_mul_f32_e32 v52, v64, v70
	v_mul_f32_e32 v53, v65, v70
	v_mul_f32_e32 v52, v68, v52
	v_mul_f32_e32 v53, v69, v53
	v_cvt_pk_bf16_f32 v50, v50, v51
	v_cvt_pk_bf16_f32 v51, v52, v53
	global_store_dwordx2 v[140:141], v[50:51], off
	v_mov_b64_e32 v[50:51], v[6:7]
	v_mov_b64_e32 v[52:53], v[8:9]
	v_mul_f32_e32 v62, v77, v70
	v_mul_f32_e32 v63, v78, v70
	v_mul_f32_e32 v64, v79, v70
	v_mul_f32_e32 v65, v80, v70
	v_mul_f32_e32 v55, v70, v55
	v_mul_f32_e32 v54, v70, v54
	v_mul_f32_e32 v57, v70, v57
	v_mul_f32_e32 v56, v70, v56
	v_mul_f32_e32 v50, v50, v62
	v_mul_f32_e32 v51, v51, v63
	v_mul_f32_e32 v52, v52, v64
	v_mul_f32_e32 v53, v53, v65
	v_cvt_pk_bf16_f32 v50, v50, v51
	v_cvt_pk_bf16_f32 v51, v52, v53
	global_store_dwordx2 v[140:141], v[50:51], off offset:32
	v_mov_b64_e32 v[50:51], v[10:11]
	v_mov_b64_e32 v[52:53], v[12:13]
	v_mul_f32_e32 v62, v81, v70
	v_mul_f32_e32 v63, v82, v70
	v_mul_f32_e32 v64, v83, v70
	v_mul_f32_e32 v65, v84, v70
	v_mul_f32_e32 v50, v50, v62
	v_mul_f32_e32 v51, v51, v63
	v_mul_f32_e32 v52, v52, v64
	v_mul_f32_e32 v53, v53, v65
	v_cvt_pk_bf16_f32 v50, v50, v51
	v_cvt_pk_bf16_f32 v51, v52, v53
	global_store_dwordx2 v[140:141], v[50:51], off offset:64
	v_mov_b64_e32 v[50:51], v[14:15]
	v_mov_b64_e32 v[52:53], v[16:17]
	v_mul_f32_e32 v62, v85, v70
	v_mul_f32_e32 v63, v86, v70
	v_mul_f32_e32 v64, v87, v70
	v_mul_f32_e32 v65, v88, v70
	v_mul_f32_e32 v50, v50, v62
	v_mul_f32_e32 v51, v51, v63
	v_mul_f32_e32 v52, v52, v64
	v_mul_f32_e32 v53, v53, v65
	v_cvt_pk_bf16_f32 v50, v50, v51
	v_cvt_pk_bf16_f32 v51, v52, v53
	global_store_dwordx2 v[140:141], v[50:51], off offset:96
	v_mov_b64_e32 v[50:51], v[126:127]
	v_mov_b64_e32 v[52:53], v[128:129]
	v_mul_f32_e32 v50, v50, v55
	v_mul_f32_e32 v51, v51, v54
	v_mul_f32_e32 v52, v52, v57
	v_mul_f32_e32 v53, v53, v56
	ds_bpermute_b32 v56, v75, v51
	ds_bpermute_b32 v57, v75, v50
	ds_bpermute_b32 v54, v75, v53
	ds_bpermute_b32 v55, v75, v52
	s_waitcnt lgkmcnt(3)
	v_mul_f32_e32 v56, v209, v56
	s_waitcnt lgkmcnt(2)
	v_mul_f32_e32 v57, v211, v57
	s_waitcnt lgkmcnt(1)
	v_mul_f32_e32 v54, v205, v54
	s_waitcnt lgkmcnt(0)
	v_mul_f32_e32 v55, v207, v55
	v_cndmask_b32_e64 v56, v56, -v56, s[4:5]
	v_cndmask_b32_e64 v57, v57, -v57, s[4:5]
	v_cndmask_b32_e64 v54, v54, -v54, s[4:5]
	v_cndmask_b32_e64 v55, v55, -v55, s[4:5]
	v_fmac_f32_e32 v56, v208, v51
	v_fmac_f32_e32 v57, v210, v50
	v_fmac_f32_e32 v54, v204, v53
	v_fmac_f32_e32 v55, v206, v52
	v_cndmask_b32_e64 v51, v51, v56, s[12:13]
	v_cndmask_b32_e64 v50, v50, v57, s[12:13]
	v_cndmask_b32_e64 v53, v53, v54, s[12:13]
	v_cndmask_b32_e64 v52, v52, v55, s[12:13]
	v_cvt_pk_bf16_f32 v50, v50, v51
	v_cvt_pk_bf16_f32 v51, v52, v53
	global_store_dwordx2 v[140:141], v[50:51], off offset:128
	v_mov_b64_e32 v[50:51], v[130:131]
	v_mov_b64_e32 v[52:53], v[132:133]
	v_mul_f32_e32 v54, v70, v59
	v_mul_f32_e32 v55, v70, v58
	v_mul_f32_e32 v56, v70, v61
	v_mul_f32_e32 v57, v70, v60
	v_mul_f32_e32 v50, v50, v54
	v_mul_f32_e32 v51, v51, v55
	v_mul_f32_e32 v52, v52, v56
	v_mul_f32_e32 v53, v53, v57
	ds_bpermute_b32 v54, v75, v50
	ds_bpermute_b32 v55, v75, v51
	ds_bpermute_b32 v56, v75, v52
	ds_bpermute_b32 v57, v75, v53
	s_waitcnt lgkmcnt(3)
	v_mul_f32_e32 v54, v213, v54
	s_waitcnt lgkmcnt(2)
	v_mul_f32_e32 v55, v215, v55
	s_waitcnt lgkmcnt(1)
	v_mul_f32_e32 v56, v217, v56
	s_waitcnt lgkmcnt(0)
	v_mul_f32_e32 v57, v219, v57
	v_cndmask_b32_e64 v54, v54, -v54, s[4:5]
	v_cndmask_b32_e64 v55, v55, -v55, s[4:5]
	v_cndmask_b32_e64 v56, v56, -v56, s[4:5]
	v_cndmask_b32_e64 v57, v57, -v57, s[4:5]
	v_fmac_f32_e32 v54, v212, v50
	v_fmac_f32_e32 v55, v214, v51
	v_fmac_f32_e32 v56, v216, v52
	v_fmac_f32_e32 v57, v218, v53
	v_cndmask_b32_e64 v50, v50, v54, s[12:13]
	v_cndmask_b32_e64 v51, v51, v55, s[12:13]
	v_cndmask_b32_e64 v52, v52, v56, s[12:13]
	v_cndmask_b32_e64 v53, v53, v57, s[12:13]
	v_cvt_pk_bf16_f32 v50, v50, v51
	v_cvt_pk_bf16_f32 v51, v52, v53
	global_store_dwordx2 v[140:141], v[50:51], off offset:160

; #define LAS __attribute__((address_space(3)))
; __device__ __forceinline__ void ph_prep(bf16_t* Z, const bf16_t* WUQ, const bf16_t* WUKV, const bf16_t* D64, const float* qkq, const float* qkk,
;                                         bf16_t* Q, bf16_t* Kb, bf16_t* Vb, bf16_t* F1lat, bf16_t* F1ctx, unsigned char* lds_) { PH_IDS;
;     ...
;                     const int row = rowc[tt]; const bool lat = row < RL; const int b = row_batch(row), t = lat ? (row & 2047) : ((row - RL) & 255), ki = lat ? 256 + t : t;
;                     if (pass == 0) {
;                         float s1 = ssq[tt]; s1 += __shfl_xor(s1, 16); s1 += __shfl_xor(s1, 32);
;                         rstd[tt] = rsqrtf(s1 * (1.f / 128) + EPS);
;                         float kr[2][4];
; #pragma unroll
;                         for (int e = 0; e < 2; ++e) { const fa::u32x2 w = *(const LAS fa::u32x2*)(sm + O_KV + rl[tt] * P_KV + (128 + 16 * e + 4 * kq) * 2);
;                             kr[e][0] = __uint_as_float(w.x << 16); kr[e][1] = __uint_as_float(w.x & 0xffff0000u); kr[e][2] = __uint_as_float(w.y << 16); kr[e][3] = __uint_as_float(w.y & 0xffff0000u); }
;                         float ss = 0.f;
; #pragma unroll
;                         for (int nt = 0; nt < 4; ++nt)
; #pragma unroll
;                             for (int r = 0; r < 4; ++r) { acc[nt][tt][r] *= rstd[tt]; ss += acc[nt][tt][r] * acc[nt][tt][r]; }
; #pragma unroll
;                         for (int e = 0; e < 2; ++e)
; #pragma unroll
;                             for (int r = 0; r < 4; ++r) ss += kr[e][r] * kr[e][r];
;                         ss += __shfl_xor(ss, 16); ss += __shfl_xor(ss, 32);
;                         const float fac = rsqrtf(ss * (1.f / 96) + EPS);
;                         bf16_t* ko = Kb + ((size_t)(b * 4 + h) * 2304 + ki) * 96 + 4 * kq;
; #pragma unroll
;                         for (int nt = 0; nt < 6; ++nt) {
;                             const f32x4 w = *(const f32x4*)(qkk + 16 * nt + 4 * kq);
;                             float v[4];
; #pragma unroll
;                             for (int r = 0; r < 4; ++r) v[r] = (nt < 4 ? acc[nt < 4 ? nt : 0][tt][r] : kr[nt < 4 ? 0 : nt - 4][r]) * fac * w[r];
;                             if (nt >= 4) rope16(v, kq, nt == 4 ? (float)(t >> 6) : (float)(t & 63), lat);
;                             fa::u32x2 o; o.x = fa::pk2(v[0], v[1]); o.y = fa::pk2(v[2], v[3]);
.LBB0_527:
	s_and_b64 vcc, exec, s[36:37]
	s_cbranch_vccz .LBB0_548
	v_mov_b64_e32 v[58:59], v[2:3]
	v_mov_b64_e32 v[60:61], v[4:5]
	v_and_b32_e32 v51, 64, v179
	v_xor_b32_e32 v50, 16, v179
	v_add_u32_e32 v51, 64, v51
	v_cmp_lt_i32_e32 vcc, v50, v51
	v_xor_b32_e32 v52, 32, v179
	s_nop 0
	v_cndmask_b32_e32 v50, v179, v50, vcc
	v_lshlrev_b32_e32 v66, 2, v50
	ds_bpermute_b32 v50, v66, v252
	v_cmp_lt_i32_e32 vcc, v52, v51
	s_waitcnt lgkmcnt(0)
	v_add_f32_e32 v53, v252, v50
	v_cndmask_b32_e32 v50, v179, v52, vcc
	v_lshlrev_b32_e32 v50, 2, v50
	ds_bpermute_b32 v51, v50, v53
	s_waitcnt lgkmcnt(0)
	v_add_f32_e32 v51, v53, v51
	v_fmamk_f32 v51, v51, 0x3c000000, v175
	v_mul_f32_e32 v52, 0x4b800000, v51
	v_cmp_gt_f32_e32 vcc, s53, v51
	s_nop 1
	v_cndmask_b32_e32 v51, v51, v52, vcc
	v_rsq_f32_e32 v51, v51
	v_add_u32_e32 v52, v163, v202
	ds_read2_b64 v[62:65], v52 offset0:32 offset1:36
	v_mul_f32_e32 v52, 0x45800000, v51
	v_cndmask_b32_e32 v196, v51, v52, vcc
	v_mul_f32_e32 v68, v47, v196
	v_mul_f32_e32 v67, v46, v196
	v_mul_f32_e32 v69, v68, v68
	v_fmac_f32_e32 v69, v67, v67
	v_mul_f32_e32 v70, v48, v196
	v_fmac_f32_e32 v69, v70, v70
	v_mul_f32_e32 v71, v49, v196
	v_fmac_f32_e32 v69, v71, v71
	v_mul_f32_e32 v54, v42, v196
	v_fmac_f32_e32 v69, v54, v54
	v_mul_f32_e32 v55, v43, v196
	v_fmac_f32_e32 v69, v55, v55
	v_mul_f32_e32 v56, v44, v196
	v_fmac_f32_e32 v69, v56, v56
	v_mul_f32_e32 v57, v45, v196
	v_fmac_f32_e32 v69, v57, v57
	v_mul_f32_e32 v49, v38, v196
	v_fmac_f32_e32 v69, v49, v49
	v_mul_f32_e32 v51, v39, v196
	v_fmac_f32_e32 v69, v51, v51
	v_mul_f32_e32 v52, v40, v196
	v_fmac_f32_e32 v69, v52, v52
	v_mul_f32_e32 v53, v41, v196
	v_fmac_f32_e32 v69, v53, v53
	v_mul_f32_e32 v45, v34, v196
	v_fmac_f32_e32 v69, v45, v45
	v_mul_f32_e32 v46, v35, v196
	v_fmac_f32_e32 v69, v46, v46
	v_mul_f32_e32 v47, v36, v196
	v_fmac_f32_e32 v69, v47, v47
	v_mul_f32_e32 v48, v37, v196
	s_waitcnt lgkmcnt(0)
	v_and_b32_e32 v38, 0xffff0000, v62
	v_lshlrev_b32_e32 v39, 16, v62
	v_fmac_f32_e32 v69, v48, v48
	v_pk_mul_f32 v[34:35], v[38:39], v[38:39]
	v_and_b32_e32 v40, 0xffff0000, v63
	v_add_f32_e32 v35, v35, v69
	v_lshlrev_b32_e32 v41, 16, v63
	v_add_f32_e32 v36, v34, v35
	v_pk_mul_f32 v[34:35], v[40:41], v[40:41]
	s_nop 0
	v_add_f32_e32 v35, v35, v36
	v_add_f32_e32 v42, v34, v35
	v_and_b32_e32 v34, 0xffff0000, v64
	v_lshlrev_b32_e32 v35, 16, v64
	v_pk_mul_f32 v[36:37], v[34:35], v[34:35]
	s_nop 0
	v_add_f32_e32 v37, v37, v42
	v_add_f32_e32 v44, v36, v37
	v_and_b32_e32 v36, 0xffff0000, v65
	v_lshlrev_b32_e32 v37, 16, v65
	v_pk_mul_f32 v[42:43], v[36:37], v[36:37]
	s_nop 0
	v_add_f32_e32 v43, v43, v44
	v_add_f32_e32 v42, v42, v43
	ds_bpermute_b32 v43, v66, v42
	s_waitcnt lgkmcnt(0)
	v_add_f32_e32 v42, v42, v43
	ds_bpermute_b32 v43, v50, v42
	s_waitcnt lgkmcnt(0)
	v_add_f32_e32 v42, v42, v43
	v_fmamk_f32 v42, v42, 0x3c2aaaab, v175
	v_mul_f32_e32 v43, 0x4b800000, v42
	v_cmp_gt_f32_e32 vcc, s53, v42
	s_nop 1
	v_cndmask_b32_e32 v42, v42, v43, vcc
	v_rsq_f32_e32 v42, v42
	s_nop 0
	v_mul_f32_e32 v43, 0x45800000, v42
	v_cndmask_b32_e32 v44, v42, v43, vcc
	v_mul_f32_e32 v42, v67, v44
	v_mul_f32_e32 v43, v68, v44
	v_mul_f32_e32 v42, v58, v42
	v_mul_f32_e32 v43, v59, v43
	v_mul_f32_e32 v58, v70, v44
	v_mul_f32_e32 v59, v71, v44
	v_mul_f32_e32 v58, v60, v58
	v_mul_f32_e32 v59, v61, v59
	v_cvt_pk_bf16_f32 v42, v42, v43
	v_cvt_pk_bf16_f32 v43, v58, v59
	s_and_saveexec_b64 s[36:37], s[10:11]
	s_cbranch_execz .LBB0_530
	global_store_dwordx2 v[144:145], v[42:43], off
.LBB0_530:
	s_or_b64 exec, exec, s[36:37]
	v_mov_b64_e32 v[58:59], v[6:7]
	v_mov_b64_e32 v[60:61], v[8:9]
	v_mul_f32_e32 v42, v54, v44
	v_mul_f32_e32 v43, v55, v44
	v_mul_f32_e32 v54, v56, v44
	v_mul_f32_e32 v55, v57, v44
	v_mul_f32_e32 v42, v42, v58
	v_mul_f32_e32 v43, v43, v59
	v_mul_f32_e32 v54, v54, v60
	v_mul_f32_e32 v55, v55, v61
	v_cvt_pk_bf16_f32 v42, v42, v43
	v_cvt_pk_bf16_f32 v43, v54, v55
	s_and_saveexec_b64 s[36:37], s[10:11]
	s_cbranch_execz .LBB0_532
	global_store_dwordx2 v[144:145], v[42:43], off offset:32
; __device__ __forceinline__ unsigned pk2(float lo, float hi) { unsigned r; asm volatile("v_cvt_pk_bf16_f32 %0, %1, %2" : "=v"(r) : "v"(lo), "v"(hi)); return r; }
; __device__ __forceinline__ void ph_prep(bf16_t* Z, const bf16_t* WUQ, const bf16_t* WUKV, const bf16_t* D64, const float* qkq, const float* qkk,
;                                         bf16_t* Q, bf16_t* Kb, bf16_t* Vb, bf16_t* F1lat, bf16_t* F1ctx, unsigned char* lds_) { PH_IDS;
;     ...
; #pragma unroll
;                         for (int nt = 0; nt < 6; ++nt) {
;                             const f32x4 w = *(const f32x4*)(qkk + 16 * nt + 4 * kq);
;                             float v[4];
; #pragma unroll
;                             for (int r = 0; r < 4; ++r) v[r] = (nt < 4 ? acc[nt < 4 ? nt : 0][tt][r] : kr[nt < 4 ? 0 : nt - 4][r]) * fac * w[r];
;                             if (nt >= 4) rope16(v, kq, nt == 4 ? (float)(t >> 6) : (float)(t & 63), lat);
;                             fa::u32x2 o; o.x = fa::pk2(v[0], v[1]); o.y = fa::pk2(v[2], v[3]);
;                             if (valid[tt]) *(fa::u32x2*)(ko + 16 * nt) = o;
;                         }
.LBB0_532:
	s_or_b64 exec, exec, s[36:37]
	v_mov_b64_e32 v[54:55], v[10:11]
	v_mov_b64_e32 v[56:57], v[12:13]
	v_mul_f32_e32 v42, v49, v44
	v_mul_f32_e32 v43, v51, v44
	v_mul_f32_e32 v49, v52, v44
	v_mul_f32_e32 v51, v53, v44
	v_mul_f32_e32 v42, v42, v54
	v_mul_f32_e32 v43, v43, v55
	v_mul_f32_e32 v49, v49, v56
	v_mul_f32_e32 v51, v51, v57
	v_cvt_pk_bf16_f32 v42, v42, v43
	v_cvt_pk_bf16_f32 v43, v49, v51
	s_and_saveexec_b64 s[36:37], s[10:11]
	s_cbranch_execz .LBB0_534
	global_store_dwordx2 v[144:145], v[42:43], off offset:64
.LBB0_534:
	s_or_b64 exec, exec, s[36:37]
	v_mov_b64_e32 v[52:53], v[14:15]
	v_mov_b64_e32 v[54:55], v[16:17]
	v_mul_f32_e32 v42, v45, v44
	v_mul_f32_e32 v43, v46, v44
	v_mul_f32_e32 v45, v47, v44
	v_mul_f32_e32 v46, v48, v44
	v_mul_f32_e32 v42, v42, v52
	v_mul_f32_e32 v43, v43, v53
	v_mul_f32_e32 v45, v45, v54
	v_mul_f32_e32 v46, v46, v55
	v_cvt_pk_bf16_f32 v42, v42, v43
	v_cvt_pk_bf16_f32 v43, v45, v46
	s_and_saveexec_b64 s[36:37], s[10:11]
	s_cbranch_execz .LBB0_536
	global_store_dwordx2 v[144:145], v[42:43], off offset:96
.LBB0_536:
	s_or_b64 exec, exec, s[36:37]
	v_mov_b64_e32 v[46:47], v[126:127]
	v_mov_b64_e32 v[48:49], v[128:129]
	v_mul_f32_e32 v39, v44, v39
	v_mul_f32_e32 v38, v44, v38
	v_mul_f32_e32 v41, v44, v41
	v_mul_f32_e32 v40, v44, v40
	v_mul_f32_e32 v39, v39, v46
	v_mul_f32_e32 v38, v38, v47
	v_mul_f32_e32 v41, v41, v48
	v_mul_f32_e32 v40, v40, v49
	ds_bpermute_b32 v45, v50, v38
	ds_bpermute_b32 v46, v50, v39
	ds_bpermute_b32 v42, v50, v40
	ds_bpermute_b32 v43, v50, v41
	s_waitcnt lgkmcnt(3)
	v_mul_f32_e32 v45, v225, v45
	s_waitcnt lgkmcnt(2)
	v_mul_f32_e32 v46, v227, v46
	s_waitcnt lgkmcnt(1)
	v_mul_f32_e32 v42, v221, v42
	s_waitcnt lgkmcnt(0)
	v_mul_f32_e32 v43, v223, v43
	v_cndmask_b32_e64 v45, v45, -v45, s[4:5]
	v_cndmask_b32_e64 v46, v46, -v46, s[4:5]
	v_cndmask_b32_e64 v42, v42, -v42, s[4:5]
	v_cndmask_b32_e64 v43, v43, -v43, s[4:5]
	v_fmac_f32_e32 v45, v224, v38
	v_fmac_f32_e32 v46, v226, v39
	v_fmac_f32_e32 v42, v220, v40
	v_fmac_f32_e32 v43, v222, v41
	v_cndmask_b32_e64 v38, v38, v45, s[14:15]
	v_cndmask_b32_e64 v39, v39, v46, s[14:15]
	v_cndmask_b32_e64 v40, v40, v42, s[14:15]
	v_cndmask_b32_e64 v41, v41, v43, s[14:15]
	v_cvt_pk_bf16_f32 v38, v39, v38
	v_cvt_pk_bf16_f32 v39, v41, v40
	s_and_saveexec_b64 s[36:37], s[10:11]
	s_cbranch_execz .LBB0_538
	global_store_dwordx2 v[144:145], v[38:39], off offset:128
.LBB0_538:
	s_or_b64 exec, exec, s[36:37]
	v_mov_b64_e32 v[38:39], v[130:131]
	v_mov_b64_e32 v[40:41], v[132:133]
	v_mul_f32_e32 v35, v44, v35
	v_mul_f32_e32 v34, v44, v34
	v_mul_f32_e32 v37, v44, v37
	v_mul_f32_e32 v36, v44, v36
	v_mul_f32_e32 v35, v35, v38
	v_mul_f32_e32 v34, v34, v39
	v_mul_f32_e32 v37, v37, v40
	v_mul_f32_e32 v36, v36, v41
	ds_bpermute_b32 v38, v50, v35
	ds_bpermute_b32 v39, v50, v34
	ds_bpermute_b32 v40, v50, v37
	ds_bpermute_b32 v41, v50, v36
	s_waitcnt lgkmcnt(3)
	v_mul_f32_e32 v38, v229, v38
	s_waitcnt lgkmcnt(2)
	v_mul_f32_e32 v39, v231, v39
	s_waitcnt lgkmcnt(1)
	v_mul_f32_e32 v40, v233, v40
	s_waitcnt lgkmcnt(0)
	v_mul_f32_e32 v41, v235, v41
	v_cndmask_b32_e64 v38, v38, -v38, s[4:5]
	v_cndmask_b32_e64 v39, v39, -v39, s[4:5]
	v_cndmask_b32_e64 v40, v40, -v40, s[4:5]
	v_cndmask_b32_e64 v41, v41, -v41, s[4:5]
	v_fmac_f32_e32 v38, v228, v35
	v_fmac_f32_e32 v39, v230, v34
	v_fmac_f32_e32 v40, v232, v37
	v_fmac_f32_e32 v41, v234, v36
	v_cndmask_b32_e64 v35, v35, v38, s[14:15]
	v_cndmask_b32_e64 v34, v34, v39, s[14:15]
	v_cndmask_b32_e64 v37, v37, v40, s[14:15]
	v_cndmask_b32_e64 v36, v36, v41, s[14:15]
	v_cvt_pk_bf16_f32 v34, v35, v34
	v_cvt_pk_bf16_f32 v35, v37, v36
	s_and_saveexec_b64 s[36:37], s[10:11]
	s_cbranch_execz .LBB0_540
	global_store_dwordx2 v[144:145], v[34:35], off offset:160

; #define LAS __attribute__((address_space(3)))
; __device__ __forceinline__ void ph_prep(bf16_t* Z, const bf16_t* WUQ, const bf16_t* WUKV, const bf16_t* D64, const float* qkq, const float* qkk,
;                                         bf16_t* Q, bf16_t* Kb, bf16_t* Vb, bf16_t* F1lat, bf16_t* F1ctx, unsigned char* lds_) { PH_IDS;
;     ...
;                     const int row = rowc[tt]; const bool lat = row < RL; const int b = row_batch(row), t = lat ? (row & 2047) : ((row - RL) & 255), ki = lat ? 256 + t : t;
;                     if (pass == 0) {
;                         float s1 = ssq[tt]; s1 += __shfl_xor(s1, 16); s1 += __shfl_xor(s1, 32);
;                         rstd[tt] = rsqrtf(s1 * (1.f / 128) + EPS);
;                         float kr[2][4];
; #pragma unroll
;                         for (int e = 0; e < 2; ++e) { const fa::u32x2 w = *(const LAS fa::u32x2*)(sm + O_KV + rl[tt] * P_KV + (128 + 16 * e + 4 * kq) * 2);
;                             kr[e][0] = __uint_as_float(w.x << 16); kr[e][1] = __uint_as_float(w.x & 0xffff0000u); kr[e][2] = __uint_as_float(w.y << 16); kr[e][3] = __uint_as_float(w.y & 0xffff0000u); }
;                         float ss = 0.f;
; #pragma unroll
;                         for (int nt = 0; nt < 4; ++nt)
; #pragma unroll
;                             for (int r = 0; r < 4; ++r) { acc[nt][tt][r] *= rstd[tt]; ss += acc[nt][tt][r] * acc[nt][tt][r]; }
; #pragma unroll
;                         for (int e = 0; e < 2; ++e)
; #pragma unroll
;                             for (int r = 0; r < 4; ++r) ss += kr[e][r] * kr[e][r];
;                         ss += __shfl_xor(ss, 16); ss += __shfl_xor(ss, 32);
;                         const float fac = rsqrtf(ss * (1.f / 96) + EPS);
;                         bf16_t* ko = Kb + ((size_t)(b * 4 + h) * 2304 + ki) * 96 + 4 * kq;
; #pragma unroll
;                         for (int nt = 0; nt < 6; ++nt) {
;                             const f32x4 w = *(const f32x4*)(qkk + 16 * nt + 4 * kq);
;                             float v[4];
; #pragma unroll
;                             for (int r = 0; r < 4; ++r) v[r] = (nt < 4 ? acc[nt < 4 ? nt : 0][tt][r] : kr[nt < 4 ? 0 : nt - 4][r]) * fac * w[r];
;                             if (nt >= 4) rope16(v, kq, nt == 4 ? (float)(t >> 6) : (float)(t & 63), lat);
;                             fa::u32x2 o; o.x = fa::pk2(v[0], v[1]); o.y = fa::pk2(v[2], v[3]);
.LBB0_558:
	v_mov_b64_e32 v[42:43], v[2:3]
	v_mov_b64_e32 v[44:45], v[4:5]
	v_and_b32_e32 v35, 64, v179
	v_xor_b32_e32 v34, 16, v179
	v_add_u32_e32 v35, 64, v35
	v_cmp_lt_i32_e32 vcc, v34, v35
	v_xor_b32_e32 v36, 32, v179
	s_nop 0
	v_cndmask_b32_e32 v34, v179, v34, vcc
	v_lshlrev_b32_e32 v50, 2, v34
	ds_bpermute_b32 v34, v50, v251
	v_cmp_lt_i32_e32 vcc, v36, v35
	s_waitcnt lgkmcnt(0)
	v_add_f32_e32 v37, v251, v34
	v_cndmask_b32_e32 v34, v179, v36, vcc
	v_lshlrev_b32_e32 v34, 2, v34
	ds_bpermute_b32 v35, v34, v37
	s_waitcnt lgkmcnt(0)
	v_add_f32_e32 v35, v37, v35
	v_fmamk_f32 v35, v35, 0x3c000000, v175
	v_mul_f32_e32 v36, 0x4b800000, v35
	v_cmp_gt_f32_e32 vcc, s53, v35
	s_nop 1
	v_cndmask_b32_e32 v35, v35, v36, vcc
	v_rsq_f32_e32 v35, v35
	v_add_u32_e32 v36, v163, v203
	ds_read2_b64 v[46:49], v36 offset0:32 offset1:36
	v_mul_f32_e32 v36, 0x45800000, v35
	v_cndmask_b32_e32 v197, v35, v36, vcc
	v_mul_f32_e32 v52, v31, v197
	v_mul_f32_e32 v51, v30, v197
	v_mul_f32_e32 v53, v52, v52
	v_fmac_f32_e32 v53, v51, v51
	v_mul_f32_e32 v54, v32, v197
	v_fmac_f32_e32 v53, v54, v54
	v_mul_f32_e32 v55, v33, v197
	v_fmac_f32_e32 v53, v55, v55
	v_mul_f32_e32 v38, v26, v197
	v_fmac_f32_e32 v53, v38, v38
	v_mul_f32_e32 v39, v27, v197
	v_fmac_f32_e32 v53, v39, v39
	v_mul_f32_e32 v40, v28, v197
	v_fmac_f32_e32 v53, v40, v40
	v_mul_f32_e32 v41, v29, v197
	v_fmac_f32_e32 v53, v41, v41
	v_mul_f32_e32 v33, v22, v197
	v_fmac_f32_e32 v53, v33, v33
	v_mul_f32_e32 v35, v23, v197
	v_fmac_f32_e32 v53, v35, v35
	v_mul_f32_e32 v36, v24, v197
	v_fmac_f32_e32 v53, v36, v36
	v_mul_f32_e32 v37, v25, v197
	v_fmac_f32_e32 v53, v37, v37
	v_mul_f32_e32 v29, v18, v197
	v_fmac_f32_e32 v53, v29, v29
	v_mul_f32_e32 v30, v19, v197
	v_fmac_f32_e32 v53, v30, v30
	v_mul_f32_e32 v31, v20, v197
	v_fmac_f32_e32 v53, v31, v31
	v_mul_f32_e32 v32, v21, v197
	s_waitcnt lgkmcnt(0)
	v_and_b32_e32 v22, 0xffff0000, v46
	v_lshlrev_b32_e32 v23, 16, v46
	v_fmac_f32_e32 v53, v32, v32
	v_pk_mul_f32 v[18:19], v[22:23], v[22:23]
	v_and_b32_e32 v24, 0xffff0000, v47
	v_add_f32_e32 v19, v19, v53
	v_lshlrev_b32_e32 v25, 16, v47
	v_add_f32_e32 v20, v18, v19
	v_pk_mul_f32 v[18:19], v[24:25], v[24:25]
	s_nop 0
	v_add_f32_e32 v19, v19, v20
	v_add_f32_e32 v26, v18, v19
	v_and_b32_e32 v18, 0xffff0000, v48
	v_lshlrev_b32_e32 v19, 16, v48
	v_pk_mul_f32 v[20:21], v[18:19], v[18:19]
	s_nop 0
	v_add_f32_e32 v21, v21, v26
	v_add_f32_e32 v28, v20, v21
	v_and_b32_e32 v20, 0xffff0000, v49
	v_lshlrev_b32_e32 v21, 16, v49
	v_pk_mul_f32 v[26:27], v[20:21], v[20:21]
	s_nop 0
	v_add_f32_e32 v27, v27, v28
	v_add_f32_e32 v26, v26, v27
	ds_bpermute_b32 v27, v50, v26
	s_waitcnt lgkmcnt(0)
	v_add_f32_e32 v26, v26, v27
	ds_bpermute_b32 v27, v34, v26
	s_waitcnt lgkmcnt(0)
	v_add_f32_e32 v26, v26, v27
	v_fmamk_f32 v26, v26, 0x3c2aaaab, v175
	v_mul_f32_e32 v27, 0x4b800000, v26
	v_cmp_gt_f32_e32 vcc, s53, v26
	s_nop 1
	v_cndmask_b32_e32 v26, v26, v27, vcc
	v_rsq_f32_e32 v26, v26
	s_nop 0
	v_mul_f32_e32 v27, 0x45800000, v26
	v_cndmask_b32_e32 v28, v26, v27, vcc
	v_mul_f32_e32 v26, v51, v28
	v_mul_f32_e32 v27, v52, v28
	v_mul_f32_e32 v26, v42, v26
	v_mul_f32_e32 v27, v43, v27
	v_mul_f32_e32 v42, v54, v28
	v_mul_f32_e32 v43, v55, v28
	v_mul_f32_e32 v42, v44, v42
	v_mul_f32_e32 v43, v45, v43
	v_cvt_pk_bf16_f32 v26, v26, v27
	v_cvt_pk_bf16_f32 v27, v42, v43
	s_and_saveexec_b64 s[18:19], s[8:9]
	s_cbranch_execz .LBB0_560
	global_store_dwordx2 v[148:149], v[26:27], off
.LBB0_560:
	s_or_b64 exec, exec, s[18:19]
	v_mov_b64_e32 v[42:43], v[6:7]
	v_mov_b64_e32 v[44:45], v[8:9]
	v_mul_f32_e32 v26, v38, v28
	v_mul_f32_e32 v27, v39, v28
	v_mul_f32_e32 v38, v40, v28
	v_mul_f32_e32 v39, v41, v28
	v_mul_f32_e32 v26, v26, v42
	v_mul_f32_e32 v27, v27, v43
	v_mul_f32_e32 v38, v38, v44
	v_mul_f32_e32 v39, v39, v45
	v_cvt_pk_bf16_f32 v26, v26, v27
	v_cvt_pk_bf16_f32 v27, v38, v39
	s_and_saveexec_b64 s[18:19], s[8:9]
	s_cbranch_execz .LBB0_562
	global_store_dwordx2 v[148:149], v[26:27], off offset:32
; __device__ __forceinline__ unsigned pk2(float lo, float hi) { unsigned r; asm volatile("v_cvt_pk_bf16_f32 %0, %1, %2" : "=v"(r) : "v"(lo), "v"(hi)); return r; }
; __device__ __forceinline__ void ph_prep(bf16_t* Z, const bf16_t* WUQ, const bf16_t* WUKV, const bf16_t* D64, const float* qkq, const float* qkk,
;                                         bf16_t* Q, bf16_t* Kb, bf16_t* Vb, bf16_t* F1lat, bf16_t* F1ctx, unsigned char* lds_) { PH_IDS;
;     ...
; #pragma unroll
;                         for (int nt = 0; nt < 6; ++nt) {
;                             const f32x4 w = *(const f32x4*)(qkk + 16 * nt + 4 * kq);
;                             float v[4];
; #pragma unroll
;                             for (int r = 0; r < 4; ++r) v[r] = (nt < 4 ? acc[nt < 4 ? nt : 0][tt][r] : kr[nt < 4 ? 0 : nt - 4][r]) * fac * w[r];
;                             if (nt >= 4) rope16(v, kq, nt == 4 ? (float)(t >> 6) : (float)(t & 63), lat);
;                             fa::u32x2 o; o.x = fa::pk2(v[0], v[1]); o.y = fa::pk2(v[2], v[3]);
;                             if (valid[tt]) *(fa::u32x2*)(ko + 16 * nt) = o;
;                         }
.LBB0_562:
	s_or_b64 exec, exec, s[18:19]
	v_mov_b64_e32 v[38:39], v[10:11]
	v_mov_b64_e32 v[40:41], v[12:13]
	v_mul_f32_e32 v26, v33, v28
	v_mul_f32_e32 v27, v35, v28
	v_mul_f32_e32 v33, v36, v28
	v_mul_f32_e32 v35, v37, v28
	v_mul_f32_e32 v26, v26, v38
	v_mul_f32_e32 v27, v27, v39
	v_mul_f32_e32 v33, v33, v40
	v_mul_f32_e32 v35, v35, v41
	v_cvt_pk_bf16_f32 v26, v26, v27
	v_cvt_pk_bf16_f32 v27, v33, v35
	s_and_saveexec_b64 s[18:19], s[8:9]
	s_cbranch_execz .LBB0_564
	global_store_dwordx2 v[148:149], v[26:27], off offset:64
.LBB0_564:
	s_or_b64 exec, exec, s[18:19]
	v_mov_b64_e32 v[36:37], v[14:15]
	v_mov_b64_e32 v[38:39], v[16:17]
	v_mul_f32_e32 v26, v29, v28
	v_mul_f32_e32 v27, v30, v28
	v_mul_f32_e32 v29, v31, v28
	v_mul_f32_e32 v30, v32, v28
	v_mul_f32_e32 v26, v26, v36
	v_mul_f32_e32 v27, v27, v37
	v_mul_f32_e32 v29, v29, v38
	v_mul_f32_e32 v30, v30, v39
	v_cvt_pk_bf16_f32 v26, v26, v27
	v_cvt_pk_bf16_f32 v27, v29, v30
	s_and_saveexec_b64 s[18:19], s[8:9]
	s_cbranch_execz .LBB0_566
	global_store_dwordx2 v[148:149], v[26:27], off offset:96
.LBB0_566:
	s_or_b64 exec, exec, s[18:19]
	v_mov_b64_e32 v[30:31], v[126:127]
	v_mov_b64_e32 v[32:33], v[128:129]
	v_mul_f32_e32 v23, v28, v23
	v_mul_f32_e32 v22, v28, v22
	v_mul_f32_e32 v25, v28, v25
	v_mul_f32_e32 v24, v28, v24
	v_mul_f32_e32 v23, v23, v30
	v_mul_f32_e32 v22, v22, v31
	v_mul_f32_e32 v25, v25, v32
	v_mul_f32_e32 v24, v24, v33
	ds_bpermute_b32 v29, v34, v22
	ds_bpermute_b32 v30, v34, v23
	ds_bpermute_b32 v26, v34, v24
	ds_bpermute_b32 v27, v34, v25
	s_waitcnt lgkmcnt(3)
	v_mul_f32_e32 v29, v240, v29
	s_waitcnt lgkmcnt(2)
	v_mul_f32_e32 v30, v242, v30
	s_waitcnt lgkmcnt(1)
	v_mul_f32_e32 v26, v236, v26
	s_waitcnt lgkmcnt(0)
	v_mul_f32_e32 v27, v238, v27
	v_cndmask_b32_e64 v29, v29, -v29, s[4:5]
	v_cndmask_b32_e64 v30, v30, -v30, s[4:5]
	v_cndmask_b32_e64 v26, v26, -v26, s[4:5]
	v_cndmask_b32_e64 v27, v27, -v27, s[4:5]
	v_fmac_f32_e32 v29, v239, v22
	v_fmac_f32_e32 v30, v241, v23
	v_fmac_f32_e32 v26, v100, v24
	v_fmac_f32_e32 v27, v237, v25
	v_cndmask_b32_e64 v22, v22, v29, s[16:17]
	v_cndmask_b32_e64 v23, v23, v30, s[16:17]
	v_cndmask_b32_e64 v24, v24, v26, s[16:17]
	v_cndmask_b32_e64 v25, v25, v27, s[16:17]
	v_cvt_pk_bf16_f32 v22, v23, v22
	v_cvt_pk_bf16_f32 v23, v25, v24
	s_and_saveexec_b64 s[18:19], s[8:9]
	s_cbranch_execz .LBB0_568
	global_store_dwordx2 v[148:149], v[22:23], off offset:128
.LBB0_568:
	s_or_b64 exec, exec, s[18:19]
	v_mov_b64_e32 v[22:23], v[130:131]
	v_mov_b64_e32 v[24:25], v[132:133]
	v_mul_f32_e32 v19, v28, v19
	v_mul_f32_e32 v18, v28, v18
	v_mul_f32_e32 v21, v28, v21
	v_mul_f32_e32 v20, v28, v20
	v_mul_f32_e32 v19, v19, v22
	v_mul_f32_e32 v18, v18, v23
	v_mul_f32_e32 v21, v21, v24
	v_mul_f32_e32 v20, v20, v25
	ds_bpermute_b32 v22, v34, v19
	ds_bpermute_b32 v23, v34, v18
	ds_bpermute_b32 v24, v34, v21
	ds_bpermute_b32 v25, v34, v20
	s_waitcnt lgkmcnt(3)
	v_mul_f32_e32 v22, v244, v22
	s_waitcnt lgkmcnt(2)
	v_mul_f32_e32 v23, v246, v23
	s_waitcnt lgkmcnt(1)
	v_mul_f32_e32 v24, v248, v24
	s_waitcnt lgkmcnt(0)
	v_mul_f32_e32 v25, v250, v25
	v_cndmask_b32_e64 v22, v22, -v22, s[4:5]
	v_cndmask_b32_e64 v23, v23, -v23, s[4:5]
	v_cndmask_b32_e64 v24, v24, -v24, s[4:5]
	v_cndmask_b32_e64 v25, v25, -v25, s[4:5]
	v_fmac_f32_e32 v22, v243, v19
	v_fmac_f32_e32 v23, v245, v18
	v_fmac_f32_e32 v24, v247, v21
	v_fmac_f32_e32 v25, v249, v20
	v_cndmask_b32_e64 v19, v19, v22, s[16:17]
	v_cndmask_b32_e64 v18, v18, v23, s[16:17]
	v_cndmask_b32_e64 v21, v21, v24, s[16:17]
	v_cndmask_b32_e64 v20, v20, v25, s[16:17]
	v_cvt_pk_bf16_f32 v18, v19, v18
	v_cvt_pk_bf16_f32 v19, v21, v20
	s_and_saveexec_b64 s[18:19], s[8:9]
	s_cbranch_execz .LBB0_493
	global_store_dwordx2 v[148:149], v[18:19], off offset:160
	s_branch .LBB0_493

; __device__ __forceinline__ float bf2f(bf16_t v) { return __uint_as_float(((unsigned)v) << 16); }
; #define LAS __attribute__((address_space(3)))
; __device__ __forceinline__ void ph_prep(bf16_t* Z, const bf16_t* WUQ, const bf16_t* WUKV, const bf16_t* D64, const float* qkq, const float* qkk,
;                                         bf16_t* Q, bf16_t* Kb, bf16_t* Vb, bf16_t* F1lat, bf16_t* F1ctx, unsigned char* lds_) { PH_IDS;
;     ...
;             f32x4 acc[6][3]; float ssq[3];
; #pragma unroll
;             for (int tt = 0; tt < 3; ++tt) { ssq[tt] = 0.f;
; #pragma unroll
;                 for (int nt = 0; nt < 6; ++nt) acc[nt][tt] = (f32x4){0.f, 0.f, 0.f, 0.f}; }
; #pragma unroll 4
;             for (int ks = 0; ks < 8; ++ks) {
;                 bf16x8 bq[3], aw[6];
; #pragma unroll
;                 for (int tt = 0; tt < 3; ++tt) { bq[tt] = *(const LAS bf16x8*)(sm + O_QC + rl[tt] * P_QC + (32 * ks + 8 * kq) * 2);
; #pragma unroll
;                     for (int e = 0; e < 8; ++e) { const float f = bf2f((bf16_t)bq[tt][e]); ssq[tt] += f * f; } }
; #pragma unroll
;                 for (int nt = 0; nt < 6; ++nt) aw[nt] = *(const bf16x8*)(WUQ + (size_t)(h * 96 + 16 * nt + c16) * 256 + 32 * ks + 8 * kq);
; #pragma unroll
;                 for (int nt = 0; nt < 6; ++nt)
; #pragma unroll
;                     for (int tt = 0; tt < 3; ++tt) acc[nt][tt] = __builtin_amdgcn_mfma_f32_16x16x32_bf16(aw[nt], bq[tt], acc[nt][tt], 0, 0, 0);
;             }
;     ...
;                     const f32x4 w = *(const f32x4*)(qkq + 16 * nt + 4 * kq);
.LBB0_571:
	s_and_b64 vcc, exec, s[18:19]
	s_cbranch_vccz .LBB0_599
	global_load_dwordx4 v[224:227], v[112:113], off
	global_load_dwordx4 v[228:231], v[112:113], off offset:64
	global_load_dwordx4 v[232:235], v[112:113], off offset:128
	global_load_dwordx4 v[236:239], v[112:113], off offset:192
	global_load_dwordx4 v[240:243], v[112:113], off offset:256
	global_load_dwordx4 v[244:247], v[112:113], off offset:320
	v_mov_b32_e32 v143, 0
	v_mul_u32_u24_e32 v141, 0x210, v198
	v_mul_u32_u24_e32 v142, 0x210, v199
	v_mul_u32_u24_e32 v140, 0x210, v200
	s_mov_b64 s[12:13], 0
	v_mov_b32_e32 v100, v174
	v_mov_b32_e32 v70, 0
	v_mov_b32_e32 v71, v143
	v_mov_b32_e32 v72, v143
	v_mov_b32_e32 v73, v143
	v_mov_b32_e32 v22, 0
	v_mov_b32_e32 v23, v143
	v_mov_b32_e32 v24, v143
	v_mov_b32_e32 v25, v143
	v_mov_b32_e32 v46, 0
	v_mov_b32_e32 v47, v143
	v_mov_b32_e32 v48, v143
	v_mov_b32_e32 v49, v143
	v_mov_b32_e32 v74, 0
	v_mov_b32_e32 v75, v143
	v_mov_b32_e32 v76, v143
	v_mov_b32_e32 v77, v143
	v_mov_b32_e32 v30, 0
	v_mov_b32_e32 v31, v143
	v_mov_b32_e32 v32, v143
	v_mov_b32_e32 v33, v143
	v_mov_b32_e32 v54, 0
	v_mov_b32_e32 v55, v143
	v_mov_b32_e32 v56, v143
	v_mov_b32_e32 v57, v143
	v_mov_b32_e32 v78, 0
	v_mov_b32_e32 v79, v143
	v_mov_b32_e32 v80, v143
	v_mov_b32_e32 v81, v143
	v_mov_b32_e32 v34, 0
	v_mov_b32_e32 v35, v143
	v_mov_b32_e32 v36, v143
	v_mov_b32_e32 v37, v143
	v_mov_b32_e32 v58, 0
	v_mov_b32_e32 v59, v143
	v_mov_b32_e32 v60, v143
	v_mov_b32_e32 v61, v143
	v_mov_b32_e32 v82, 0
	v_mov_b32_e32 v83, v143
	v_mov_b32_e32 v84, v143
	v_mov_b32_e32 v85, v143
	v_mov_b32_e32 v38, 0
	v_mov_b32_e32 v39, v143
	v_mov_b32_e32 v40, v143
	v_mov_b32_e32 v41, v143
	v_mov_b32_e32 v62, 0
	v_mov_b32_e32 v63, v143
	v_mov_b32_e32 v64, v143
	v_mov_b32_e32 v65, v143
	v_mov_b32_e32 v86, 0
	v_mov_b32_e32 v87, v143
	v_mov_b32_e32 v88, v143
	v_mov_b32_e32 v89, v143
	v_mov_b32_e32 v50, 0
	v_mov_b32_e32 v51, v143
	v_mov_b32_e32 v52, v143
	v_mov_b32_e32 v53, v143
	v_mov_b32_e32 v26, 0
	v_mov_b32_e32 v27, v143
	v_mov_b32_e32 v28, v143
	v_mov_b32_e32 v29, v143
	v_mov_b32_e32 v66, 0
	v_mov_b32_e32 v67, v143
	v_mov_b32_e32 v68, v143
	v_mov_b32_e32 v69, v143
	v_mov_b32_e32 v42, 0
	v_mov_b32_e32 v43, v143
	v_mov_b32_e32 v44, v143
	v_mov_b32_e32 v45, v143
	v_mov_b32_e32 v18, 0
	v_mov_b32_e32 v19, v143
	v_mov_b32_e32 v20, v143
	v_mov_b32_e32 v21, v143
	v_mov_b32_e32 v94, 0
	v_mov_b32_e32 v95, v143
.LBB0_573:
	v_add_u32_e32 v195, v100, v141
	ds_read_b128 v[90:93], v195
	v_add_u32_e32 v222, v100, v142
	ds_read_b128 v[144:147], v222
	v_add_u32_e32 v223, v100, v140
	ds_read_b128 v[148:151], v223
	s_waitcnt lgkmcnt(2)
	v_lshlrev_b32_e32 v96, 16, v90
	v_fmac_f32_e32 v143, v96, v96
	v_and_b32_e32 v96, 0xffff0000, v90
	v_lshlrev_b32_e32 v97, 16, v91
	v_pk_mul_f32 v[96:97], v[96:97], v[96:97]
	v_lshl_add_u64 v[156:157], v[132:133], 0, s[12:13]
	v_add_f32_e32 v96, v96, v143
	v_add_f32_e32 v138, v97, v96
	v_and_b32_e32 v96, 0xffff0000, v91
	v_lshlrev_b32_e32 v97, 16, v92
	v_pk_mul_f32 v[96:97], v[96:97], v[96:97]
	v_lshl_add_u64 v[204:205], v[130:131], 0, s[12:13]
	v_add_f32_e32 v96, v96, v138
	v_add_f32_e32 v138, v97, v96
	v_and_b32_e32 v96, 0xffff0000, v92
	v_lshlrev_b32_e32 v97, 16, v93
	v_pk_mul_f32 v[96:97], v[96:97], v[96:97]
	v_lshl_add_u64 v[208:209], v[128:129], 0, s[12:13]
	v_add_f32_e32 v96, v96, v138
	v_add_f32_e32 v143, v97, v96
	v_and_b32_e32 v96, 0xffff0000, v93
	v_fmac_f32_e32 v143, v96, v96
	s_waitcnt lgkmcnt(1)
	v_lshlrev_b32_e32 v97, 16, v144
	s_waitcnt lgkmcnt(0)
	v_lshlrev_b32_e32 v96, 16, v148
	v_pk_fma_f32 v[94:95], v[96:97], v[96:97], v[94:95]
	v_and_b32_e32 v97, 0xffff0000, v144
	v_and_b32_e32 v96, 0xffff0000, v148
	v_pk_fma_f32 v[94:95], v[96:97], v[96:97], v[94:95]
	v_lshlrev_b32_e32 v97, 16, v145
	v_lshlrev_b32_e32 v96, 16, v149
	v_pk_fma_f32 v[94:95], v[96:97], v[96:97], v[94:95]
	v_and_b32_e32 v97, 0xffff0000, v145
	v_and_b32_e32 v96, 0xffff0000, v149
	v_pk_fma_f32 v[94:95], v[96:97], v[96:97], v[94:95]
	v_lshlrev_b32_e32 v97, 16, v146
	v_lshlrev_b32_e32 v96, 16, v150
	v_pk_fma_f32 v[94:95], v[96:97], v[96:97], v[94:95]
	v_and_b32_e32 v97, 0xffff0000, v146
	v_and_b32_e32 v96, 0xffff0000, v150
	v_pk_fma_f32 v[94:95], v[96:97], v[96:97], v[94:95]
	v_lshlrev_b32_e32 v97, 16, v147
	v_lshlrev_b32_e32 v96, 16, v151
	v_pk_fma_f32 v[94:95], v[96:97], v[96:97], v[94:95]
	v_and_b32_e32 v97, 0xffff0000, v147
	v_and_b32_e32 v96, 0xffff0000, v151
	v_pk_fma_f32 v[94:95], v[96:97], v[96:97], v[94:95]
	v_lshl_add_u64 v[96:97], v[136:137], 0, s[12:13]
	v_add_co_u32_e32 v96, vcc, s54, v96
	v_lshl_add_u64 v[138:139], v[134:135], 0, s[12:13]
	s_nop 0
	v_addc_co_u32_e32 v97, vcc, 0, v97, vcc
	v_add_co_u32_e32 v138, vcc, s54, v138
	v_lshl_add_u64 v[212:213], v[126:127], 0, s[12:13]
	s_nop 0
	v_addc_co_u32_e32 v139, vcc, 0, v139, vcc
	v_add_co_u32_e32 v156, vcc, s54, v156
	global_load_dwordx4 v[152:155], v[96:97], off
	global_load_dwordx4 v[196:199], v[138:139], off
	v_addc_co_u32_e32 v157, vcc, 0, v157, vcc
	v_add_co_u32_e32 v216, vcc, s54, v204
	global_load_dwordx4 v[200:203], v[156:157], off
	s_nop 0
	v_addc_co_u32_e32 v217, vcc, 0, v205, vcc
	v_add_co_u32_e32 v218, vcc, s54, v208
	global_load_dwordx4 v[204:207], v[216:217], off
	s_nop 0
	v_addc_co_u32_e32 v219, vcc, 0, v209, vcc
	v_add_co_u32_e32 v220, vcc, s54, v212
	global_load_dwordx4 v[208:211], v[218:219], off
	s_nop 0
	v_addc_co_u32_e32 v221, vcc, 0, v213, vcc
	global_load_dwordx4 v[212:215], v[220:221], off
	s_add_u32 s12, s12, 0x100
	s_addc_u32 s13, s13, 0
	v_add_u32_e32 v100, 0x100, v100
	s_cmpk_eq_i32 s12, 0x200
	s_waitcnt vmcnt(5)
	v_mfma_f32_16x16x32_bf16 v[86:89], v[152:155], v[90:93], v[86:89]
	s_waitcnt vmcnt(4)
; __device__ __forceinline__ float bf2f(bf16_t v) { return __uint_as_float(((unsigned)v) << 16); }
; #define LAS __attribute__((address_space(3)))
; __device__ __forceinline__ void ph_prep(bf16_t* Z, const bf16_t* WUQ, const bf16_t* WUKV, const bf16_t* D64, const float* qkq, const float* qkk,
;                                         bf16_t* Q, bf16_t* Kb, bf16_t* Vb, bf16_t* F1lat, bf16_t* F1ctx, unsigned char* lds_) { PH_IDS;
;     ...
;             for (int ks = 0; ks < 8; ++ks) {
;                 bf16x8 bq[3], aw[6];
; #pragma unroll
;                 for (int tt = 0; tt < 3; ++tt) { bq[tt] = *(const LAS bf16x8*)(sm + O_QC + rl[tt] * P_QC + (32 * ks + 8 * kq) * 2);
; #pragma unroll
;                     for (int e = 0; e < 8; ++e) { const float f = bf2f((bf16_t)bq[tt][e]); ssq[tt] += f * f; } }
; #pragma unroll
;                 for (int nt = 0; nt < 6; ++nt) aw[nt] = *(const bf16x8*)(WUQ + (size_t)(h * 96 + 16 * nt + c16) * 256 + 32 * ks + 8 * kq);
; #pragma unroll
;                 for (int nt = 0; nt < 6; ++nt)
; #pragma unroll
;                     for (int tt = 0; tt < 3; ++tt) acc[nt][tt] = __builtin_amdgcn_mfma_f32_16x16x32_bf16(aw[nt], bq[tt], acc[nt][tt], 0, 0, 0);
;             }
	v_mfma_f32_16x16x32_bf16 v[82:85], v[196:199], v[90:93], v[82:85]
	s_waitcnt vmcnt(3)
	v_mfma_f32_16x16x32_bf16 v[78:81], v[200:203], v[90:93], v[78:81]
	s_waitcnt vmcnt(2)
	v_mfma_f32_16x16x32_bf16 v[74:77], v[204:207], v[90:93], v[74:77]
	s_waitcnt vmcnt(1)
	v_mfma_f32_16x16x32_bf16 v[70:73], v[208:211], v[90:93], v[70:73]
	s_waitcnt vmcnt(0)
	v_mfma_f32_16x16x32_bf16 v[66:69], v[212:215], v[90:93], v[66:69]
	ds_read_b128 v[90:93], v195 offset:64
	v_mfma_f32_16x16x32_bf16 v[62:65], v[152:155], v[144:147], v[62:65]
	v_mfma_f32_16x16x32_bf16 v[58:61], v[196:199], v[144:147], v[58:61]
	v_mfma_f32_16x16x32_bf16 v[54:57], v[200:203], v[144:147], v[54:57]
	v_mfma_f32_16x16x32_bf16 v[46:49], v[204:207], v[144:147], v[46:49]
	v_mfma_f32_16x16x32_bf16 v[50:53], v[208:211], v[144:147], v[50:53]
	v_mfma_f32_16x16x32_bf16 v[42:45], v[212:215], v[144:147], v[42:45]
	s_waitcnt lgkmcnt(0)
	v_lshlrev_b32_e32 v144, 16, v90
	v_fmac_f32_e32 v143, v144, v144
	v_and_b32_e32 v144, 0xffff0000, v90
	v_lshlrev_b32_e32 v145, 16, v91
	v_pk_mul_f32 v[144:145], v[144:145], v[144:145]
	v_mfma_f32_16x16x32_bf16 v[38:41], v[152:155], v[148:151], v[38:41]
	v_add_f32_e32 v143, v144, v143
	v_add_f32_e32 v143, v145, v143
	v_and_b32_e32 v144, 0xffff0000, v91
	v_lshlrev_b32_e32 v145, 16, v92
	v_pk_mul_f32 v[144:145], v[144:145], v[144:145]
	v_mfma_f32_16x16x32_bf16 v[34:37], v[196:199], v[148:151], v[34:37]
	v_add_f32_e32 v143, v144, v143
	v_add_f32_e32 v143, v145, v143
	v_and_b32_e32 v144, 0xffff0000, v92
	v_lshlrev_b32_e32 v145, 16, v93
	v_pk_mul_f32 v[144:145], v[144:145], v[144:145]
	v_mfma_f32_16x16x32_bf16 v[30:33], v[200:203], v[148:151], v[30:33]
	v_add_f32_e32 v143, v144, v143
	v_add_f32_e32 v143, v145, v143
	v_and_b32_e32 v144, 0xffff0000, v93
	v_mfma_f32_16x16x32_bf16 v[22:25], v[204:207], v[148:151], v[22:25]
	v_fmac_f32_e32 v143, v144, v144
	v_mfma_f32_16x16x32_bf16 v[26:29], v[208:211], v[148:151], v[26:29]
	v_mfma_f32_16x16x32_bf16 v[18:21], v[212:215], v[148:151], v[18:21]
	ds_read_b128 v[144:147], v222 offset:64
	ds_read_b128 v[148:151], v223 offset:64
	s_waitcnt lgkmcnt(1)
	v_lshlrev_b32_e32 v153, 16, v144
	s_waitcnt lgkmcnt(0)
	v_lshlrev_b32_e32 v152, 16, v148
	v_pk_fma_f32 v[94:95], v[152:153], v[152:153], v[94:95]
	v_and_b32_e32 v153, 0xffff0000, v144
	v_and_b32_e32 v152, 0xffff0000, v148
	v_pk_fma_f32 v[94:95], v[152:153], v[152:153], v[94:95]
	v_lshlrev_b32_e32 v153, 16, v145
	v_lshlrev_b32_e32 v152, 16, v149
	v_pk_fma_f32 v[94:95], v[152:153], v[152:153], v[94:95]
	v_and_b32_e32 v153, 0xffff0000, v145
	v_and_b32_e32 v152, 0xffff0000, v149
	v_pk_fma_f32 v[94:95], v[152:153], v[152:153], v[94:95]
	v_lshlrev_b32_e32 v153, 16, v146
	v_lshlrev_b32_e32 v152, 16, v150
	v_pk_fma_f32 v[94:95], v[152:153], v[152:153], v[94:95]
	v_and_b32_e32 v153, 0xffff0000, v146
	v_and_b32_e32 v152, 0xffff0000, v150
	v_pk_fma_f32 v[94:95], v[152:153], v[152:153], v[94:95]
	v_lshlrev_b32_e32 v153, 16, v147
	v_lshlrev_b32_e32 v152, 16, v151
	v_pk_fma_f32 v[94:95], v[152:153], v[152:153], v[94:95]
	v_and_b32_e32 v153, 0xffff0000, v147
	v_and_b32_e32 v152, 0xffff0000, v151
	v_pk_fma_f32 v[94:95], v[152:153], v[152:153], v[94:95]
	global_load_dwordx4 v[152:155], v[96:97], off offset:64
	global_load_dwordx4 v[196:199], v[138:139], off offset:64
	global_load_dwordx4 v[200:203], v[156:157], off offset:64
	global_load_dwordx4 v[204:207], v[216:217], off offset:64
	global_load_dwordx4 v[208:211], v[218:219], off offset:64
	global_load_dwordx4 v[212:215], v[220:221], off offset:64
	s_waitcnt vmcnt(5)
	v_mfma_f32_16x16x32_bf16 v[86:89], v[152:155], v[90:93], v[86:89]
	s_waitcnt vmcnt(4)
	v_mfma_f32_16x16x32_bf16 v[82:85], v[196:199], v[90:93], v[82:85]
	s_waitcnt vmcnt(3)
	v_mfma_f32_16x16x32_bf16 v[78:81], v[200:203], v[90:93], v[78:81]
	s_waitcnt vmcnt(2)
	v_mfma_f32_16x16x32_bf16 v[74:77], v[204:207], v[90:93], v[74:77]
	s_waitcnt vmcnt(1)
	v_mfma_f32_16x16x32_bf16 v[70:73], v[208:211], v[90:93], v[70:73]
	s_waitcnt vmcnt(0)
	v_mfma_f32_16x16x32_bf16 v[66:69], v[212:215], v[90:93], v[66:69]
	ds_read_b128 v[90:93], v195 offset:128
	v_mfma_f32_16x16x32_bf16 v[62:65], v[152:155], v[144:147], v[62:65]
	v_mfma_f32_16x16x32_bf16 v[58:61], v[196:199], v[144:147], v[58:61]
	v_mfma_f32_16x16x32_bf16 v[54:57], v[200:203], v[144:147], v[54:57]
	v_mfma_f32_16x16x32_bf16 v[46:49], v[204:207], v[144:147], v[46:49]
	v_mfma_f32_16x16x32_bf16 v[50:53], v[208:211], v[144:147], v[50:53]
	v_mfma_f32_16x16x32_bf16 v[42:45], v[212:215], v[144:147], v[42:45]
	s_waitcnt lgkmcnt(0)
	v_lshlrev_b32_e32 v144, 16, v90
	v_fmac_f32_e32 v143, v144, v144
	v_and_b32_e32 v144, 0xffff0000, v90
	v_lshlrev_b32_e32 v145, 16, v91
	v_pk_mul_f32 v[144:145], v[144:145], v[144:145]
	v_mfma_f32_16x16x32_bf16 v[38:41], v[152:155], v[148:151], v[38:41]
	v_add_f32_e32 v143, v144, v143
	v_add_f32_e32 v143, v145, v143
	v_and_b32_e32 v144, 0xffff0000, v91
	v_lshlrev_b32_e32 v145, 16, v92
	v_pk_mul_f32 v[144:145], v[144:145], v[144:145]
	v_mfma_f32_16x16x32_bf16 v[34:37], v[196:199], v[148:151], v[34:37]
	v_add_f32_e32 v143, v144, v143
	v_add_f32_e32 v143, v145, v143
	v_and_b32_e32 v144, 0xffff0000, v92
	v_lshlrev_b32_e32 v145, 16, v93
	v_pk_mul_f32 v[144:145], v[144:145], v[144:145]
	v_mfma_f32_16x16x32_bf16 v[30:33], v[200:203], v[148:151], v[30:33]
	v_add_f32_e32 v143, v144, v143
	v_add_f32_e32 v143, v145, v143
	v_and_b32_e32 v144, 0xffff0000, v93
	v_mfma_f32_16x16x32_bf16 v[22:25], v[204:207], v[148:151], v[22:25]
	v_fmac_f32_e32 v143, v144, v144
	v_mfma_f32_16x16x32_bf16 v[26:29], v[208:211], v[148:151], v[26:29]
	v_mfma_f32_16x16x32_bf16 v[18:21], v[212:215], v[148:151], v[18:21]
	ds_read_b128 v[144:147], v222 offset:128
	ds_read_b128 v[148:151], v223 offset:128
	s_waitcnt lgkmcnt(1)
; __device__ __forceinline__ float bf2f(bf16_t v) { return __uint_as_float(((unsigned)v) << 16); }
; #define LAS __attribute__((address_space(3)))
; __device__ __forceinline__ void ph_prep(bf16_t* Z, const bf16_t* WUQ, const bf16_t* WUKV, const bf16_t* D64, const float* qkq, const float* qkk,
;                                         bf16_t* Q, bf16_t* Kb, bf16_t* Vb, bf16_t* F1lat, bf16_t* F1ctx, unsigned char* lds_) { PH_IDS;
;     ...
;             for (int ks = 0; ks < 8; ++ks) {
;                 bf16x8 bq[3], aw[6];
; #pragma unroll
;                 for (int tt = 0; tt < 3; ++tt) { bq[tt] = *(const LAS bf16x8*)(sm + O_QC + rl[tt] * P_QC + (32 * ks + 8 * kq) * 2);
; #pragma unroll
;                     for (int e = 0; e < 8; ++e) { const float f = bf2f((bf16_t)bq[tt][e]); ssq[tt] += f * f; } }
; #pragma unroll
;                 for (int nt = 0; nt < 6; ++nt) aw[nt] = *(const bf16x8*)(WUQ + (size_t)(h * 96 + 16 * nt + c16) * 256 + 32 * ks + 8 * kq);
; #pragma unroll
;                 for (int nt = 0; nt < 6; ++nt)
; #pragma unroll
;                     for (int tt = 0; tt < 3; ++tt) acc[nt][tt] = __builtin_amdgcn_mfma_f32_16x16x32_bf16(aw[nt], bq[tt], acc[nt][tt], 0, 0, 0);
;             }
	v_lshlrev_b32_e32 v153, 16, v144
	s_waitcnt lgkmcnt(0)
	v_lshlrev_b32_e32 v152, 16, v148
	v_pk_fma_f32 v[94:95], v[152:153], v[152:153], v[94:95]
	v_and_b32_e32 v153, 0xffff0000, v144
	v_and_b32_e32 v152, 0xffff0000, v148
	v_pk_fma_f32 v[94:95], v[152:153], v[152:153], v[94:95]
	v_lshlrev_b32_e32 v153, 16, v145
	v_lshlrev_b32_e32 v152, 16, v149
	v_pk_fma_f32 v[94:95], v[152:153], v[152:153], v[94:95]
	v_and_b32_e32 v153, 0xffff0000, v145
	v_and_b32_e32 v152, 0xffff0000, v149
	v_pk_fma_f32 v[94:95], v[152:153], v[152:153], v[94:95]
	v_lshlrev_b32_e32 v153, 16, v146
	v_lshlrev_b32_e32 v152, 16, v150
	v_pk_fma_f32 v[94:95], v[152:153], v[152:153], v[94:95]
	v_and_b32_e32 v153, 0xffff0000, v146
	v_and_b32_e32 v152, 0xffff0000, v150
	v_pk_fma_f32 v[94:95], v[152:153], v[152:153], v[94:95]
	v_lshlrev_b32_e32 v153, 16, v147
	v_lshlrev_b32_e32 v152, 16, v151
	v_pk_fma_f32 v[94:95], v[152:153], v[152:153], v[94:95]
	v_and_b32_e32 v153, 0xffff0000, v147
	v_and_b32_e32 v152, 0xffff0000, v151
	v_pk_fma_f32 v[94:95], v[152:153], v[152:153], v[94:95]
	global_load_dwordx4 v[152:155], v[96:97], off offset:128
	global_load_dwordx4 v[196:199], v[138:139], off offset:128
	global_load_dwordx4 v[200:203], v[156:157], off offset:128
	global_load_dwordx4 v[204:207], v[216:217], off offset:128
	global_load_dwordx4 v[208:211], v[218:219], off offset:128
	global_load_dwordx4 v[212:215], v[220:221], off offset:128
	s_waitcnt vmcnt(5)
	v_mfma_f32_16x16x32_bf16 v[86:89], v[152:155], v[90:93], v[86:89]
	s_waitcnt vmcnt(4)
	v_mfma_f32_16x16x32_bf16 v[82:85], v[196:199], v[90:93], v[82:85]
	s_waitcnt vmcnt(3)
	v_mfma_f32_16x16x32_bf16 v[78:81], v[200:203], v[90:93], v[78:81]
	s_waitcnt vmcnt(2)
	v_mfma_f32_16x16x32_bf16 v[74:77], v[204:207], v[90:93], v[74:77]
	s_waitcnt vmcnt(1)
	v_mfma_f32_16x16x32_bf16 v[70:73], v[208:211], v[90:93], v[70:73]
	s_waitcnt vmcnt(0)
	v_mfma_f32_16x16x32_bf16 v[66:69], v[212:215], v[90:93], v[66:69]
	ds_read_b128 v[90:93], v195 offset:192
	v_mfma_f32_16x16x32_bf16 v[62:65], v[152:155], v[144:147], v[62:65]
	v_mfma_f32_16x16x32_bf16 v[58:61], v[196:199], v[144:147], v[58:61]
	v_mfma_f32_16x16x32_bf16 v[54:57], v[200:203], v[144:147], v[54:57]
	v_mfma_f32_16x16x32_bf16 v[46:49], v[204:207], v[144:147], v[46:49]
	v_mfma_f32_16x16x32_bf16 v[50:53], v[208:211], v[144:147], v[50:53]
	v_mfma_f32_16x16x32_bf16 v[42:45], v[212:215], v[144:147], v[42:45]
	s_waitcnt lgkmcnt(0)
	v_lshlrev_b32_e32 v144, 16, v90
	v_fmac_f32_e32 v143, v144, v144
	v_and_b32_e32 v144, 0xffff0000, v90
	v_lshlrev_b32_e32 v145, 16, v91
	v_pk_mul_f32 v[144:145], v[144:145], v[144:145]
	v_mfma_f32_16x16x32_bf16 v[38:41], v[152:155], v[148:151], v[38:41]
	v_add_f32_e32 v143, v144, v143
	v_add_f32_e32 v143, v145, v143
	v_and_b32_e32 v144, 0xffff0000, v91
	v_lshlrev_b32_e32 v145, 16, v92
	v_pk_mul_f32 v[144:145], v[144:145], v[144:145]
	v_mfma_f32_16x16x32_bf16 v[34:37], v[196:199], v[148:151], v[34:37]
	v_add_f32_e32 v143, v144, v143
	v_add_f32_e32 v143, v145, v143
	v_and_b32_e32 v144, 0xffff0000, v92
	v_lshlrev_b32_e32 v145, 16, v93
	v_pk_mul_f32 v[144:145], v[144:145], v[144:145]
	v_mfma_f32_16x16x32_bf16 v[30:33], v[200:203], v[148:151], v[30:33]
	v_add_f32_e32 v143, v144, v143
	v_add_f32_e32 v143, v145, v143
	v_and_b32_e32 v144, 0xffff0000, v93
	v_mfma_f32_16x16x32_bf16 v[22:25], v[204:207], v[148:151], v[22:25]
	v_fmac_f32_e32 v143, v144, v144
	v_mfma_f32_16x16x32_bf16 v[26:29], v[208:211], v[148:151], v[26:29]
	v_mfma_f32_16x16x32_bf16 v[18:21], v[212:215], v[148:151], v[18:21]
	ds_read_b128 v[144:147], v222 offset:192
	ds_read_b128 v[148:151], v223 offset:192
	s_waitcnt lgkmcnt(1)
	v_lshlrev_b32_e32 v153, 16, v144
	s_waitcnt lgkmcnt(0)
	v_lshlrev_b32_e32 v152, 16, v148
	v_pk_fma_f32 v[94:95], v[152:153], v[152:153], v[94:95]
	v_and_b32_e32 v153, 0xffff0000, v144
	v_and_b32_e32 v152, 0xffff0000, v148
	v_pk_fma_f32 v[94:95], v[152:153], v[152:153], v[94:95]
	v_lshlrev_b32_e32 v153, 16, v145
	v_lshlrev_b32_e32 v152, 16, v149
	v_pk_fma_f32 v[94:95], v[152:153], v[152:153], v[94:95]
	v_and_b32_e32 v153, 0xffff0000, v145
	v_and_b32_e32 v152, 0xffff0000, v149
	v_pk_fma_f32 v[94:95], v[152:153], v[152:153], v[94:95]
	v_lshlrev_b32_e32 v153, 16, v146
	v_lshlrev_b32_e32 v152, 16, v150
	v_pk_fma_f32 v[94:95], v[152:153], v[152:153], v[94:95]
	v_and_b32_e32 v153, 0xffff0000, v146
	v_and_b32_e32 v152, 0xffff0000, v150
	v_pk_fma_f32 v[94:95], v[152:153], v[152:153], v[94:95]
	v_lshlrev_b32_e32 v153, 16, v147
	v_lshlrev_b32_e32 v152, 16, v151
	v_pk_fma_f32 v[94:95], v[152:153], v[152:153], v[94:95]
	v_and_b32_e32 v153, 0xffff0000, v147
	v_and_b32_e32 v152, 0xffff0000, v151
	v_pk_fma_f32 v[94:95], v[152:153], v[152:153], v[94:95]
	global_load_dwordx4 v[152:155], v[96:97], off offset:192
	global_load_dwordx4 v[196:199], v[138:139], off offset:192
	global_load_dwordx4 v[200:203], v[156:157], off offset:192
	global_load_dwordx4 v[204:207], v[216:217], off offset:192
	global_load_dwordx4 v[208:211], v[218:219], off offset:192
	global_load_dwordx4 v[212:215], v[220:221], off offset:192
	s_waitcnt vmcnt(5)
	v_mfma_f32_16x16x32_bf16 v[86:89], v[152:155], v[90:93], v[86:89]
	v_mfma_f32_16x16x32_bf16 v[62:65], v[152:155], v[144:147], v[62:65]
	v_mfma_f32_16x16x32_bf16 v[38:41], v[152:155], v[148:151], v[38:41]
	s_waitcnt vmcnt(4)
	v_mfma_f32_16x16x32_bf16 v[82:85], v[196:199], v[90:93], v[82:85]
	v_mfma_f32_16x16x32_bf16 v[58:61], v[196:199], v[144:147], v[58:61]
	v_mfma_f32_16x16x32_bf16 v[34:37], v[196:199], v[148:151], v[34:37]
	s_waitcnt vmcnt(3)
	v_mfma_f32_16x16x32_bf16 v[78:81], v[200:203], v[90:93], v[78:81]
	v_mfma_f32_16x16x32_bf16 v[54:57], v[200:203], v[144:147], v[54:57]
	v_mfma_f32_16x16x32_bf16 v[30:33], v[200:203], v[148:151], v[30:33]
	s_waitcnt vmcnt(2)
	v_mfma_f32_16x16x32_bf16 v[74:77], v[204:207], v[90:93], v[74:77]
	v_mfma_f32_16x16x32_bf16 v[46:49], v[204:207], v[144:147], v[46:49]
	v_mfma_f32_16x16x32_bf16 v[22:25], v[204:207], v[148:151], v[22:25]
	s_waitcnt vmcnt(1)
	v_mfma_f32_16x16x32_bf16 v[70:73], v[208:211], v[90:93], v[70:73]
	v_mfma_f32_16x16x32_bf16 v[50:53], v[208:211], v[144:147], v[50:53]
	v_mfma_f32_16x16x32_bf16 v[26:29], v[208:211], v[148:151], v[26:29]
	s_waitcnt vmcnt(0)
	v_mfma_f32_16x16x32_bf16 v[66:69], v[212:215], v[90:93], v[66:69]
	v_mfma_f32_16x16x32_bf16 v[42:45], v[212:215], v[144:147], v[42:45]
	v_mfma_f32_16x16x32_bf16 v[18:21], v[212:215], v[148:151], v[18:21]
	s_cbranch_scc0 .LBB0_573
; __device__ __forceinline__ unsigned pk2(float lo, float hi) { unsigned r; asm volatile("v_cvt_pk_bf16_f32 %0, %1, %2" : "=v"(r) : "v"(lo), "v"(hi)); return r; }
; __device__ __forceinline__ void ph_prep(bf16_t* Z, const bf16_t* WUQ, const bf16_t* WUKV, const bf16_t* D64, const float* qkq, const float* qkk,
;                                         bf16_t* Q, bf16_t* Kb, bf16_t* Vb, bf16_t* F1lat, bf16_t* F1ctx, unsigned char* lds_) { PH_IDS;
;     ...
;             for (int tt = 0; tt < 3; ++tt) {
;                 float s1 = ssq[tt]; s1 += __shfl_xor(s1, 16); s1 += __shfl_xor(s1, 32);
;                 const float rstd = rsqrtf(s1 * (1.f / 256) + EPS);
;                 float ss = 0.f;
; #pragma unroll
;                 for (int nt = 0; nt < 6; ++nt)
; #pragma unroll
;                     for (int r = 0; r < 4; ++r) ss += acc[nt][tt][r] * acc[nt][tt][r];
;                 ss += __shfl_xor(ss, 16); ss += __shfl_xor(ss, 32);
;                 const float fac = rstd * rsqrtf(rstd * rstd * ss * (1.f / 96) + EPS) * 0.14724727430627066f;
;                 const int row = rowc[tt]; const bool lat = row < RL; const int b = row_batch(row), t = lat ? (row & 2047) : ((row - RL) & 255), qi = lat ? t : 2048 + t;
;                 bf16_t* qo = Q + ((size_t)(b * 4 + h) * 2304 + qi) * 96 + 4 * kq;
; #pragma unroll
;                 for (int nt = 0; nt < 6; ++nt) {
;                     const f32x4 w = *(const f32x4*)(qkq + 16 * nt + 4 * kq);
;                     float v[4];
; #pragma unroll
;                     for (int r = 0; r < 4; ++r) v[r] = acc[nt][tt][r] * fac * w[r];
;                     if (nt >= 4) rope16(v, kq, nt == 4 ? (float)(t >> 6) : (float)(t & 63), lat);
;                     fa::u32x2 o; o.x = fa::pk2(v[0], v[1]); o.y = fa::pk2(v[2], v[3]);
;                     if (valid[tt]) *(fa::u32x2*)(qo + 16 * nt) = o;
;                 }
	v_mov_b64_e32 v[144:145], v[224:225]
	v_mov_b64_e32 v[146:147], v[226:227]
	v_mul_f32_e32 v150, v87, v87
	v_fmac_f32_e32 v150, v86, v86
	v_fmac_f32_e32 v150, v88, v88
	v_fmac_f32_e32 v150, v89, v89
	v_fmac_f32_e32 v150, v82, v82
	v_fmac_f32_e32 v150, v83, v83
	v_fmac_f32_e32 v150, v84, v84
	v_fmac_f32_e32 v150, v85, v85
	v_fmac_f32_e32 v150, v78, v78
	v_and_b32_e32 v91, 64, v179
	v_fmac_f32_e32 v150, v79, v79
	v_xor_b32_e32 v90, 16, v179
	v_add_u32_e32 v91, 64, v91
	v_fmac_f32_e32 v150, v80, v80
	v_cmp_lt_i32_e64 s[12:13], v90, v91
	v_fmac_f32_e32 v150, v81, v81
	v_xor_b32_e32 v100, 32, v179
	v_cndmask_b32_e64 v90, v179, v90, s[12:13]
	v_fmac_f32_e32 v150, v74, v74
	v_cmp_lt_i32_e64 s[12:13], v100, v91
	v_lshlrev_b32_e32 v91, 2, v90
	v_fmac_f32_e32 v150, v75, v75
	ds_bpermute_b32 v153, v91, v143
	v_fmac_f32_e32 v150, v76, v76
	v_pk_mul_f32 v[96:97], v[70:71], v[70:71]
	v_fmac_f32_e32 v150, v77, v77
	v_add_f32_e32 v96, v96, v150
	v_pk_mul_f32 v[92:93], v[72:73], v[72:73]
	v_add_f32_e32 v96, v97, v96
	v_cndmask_b32_e64 v100, v179, v100, s[12:13]
	v_add_f32_e32 v92, v92, v96
	v_pk_mul_f32 v[148:149], v[66:67], v[66:67]
	v_lshlrev_b32_e32 v90, 2, v100
	s_waitcnt lgkmcnt(0)
	v_add_f32_e32 v143, v143, v153
	v_add_f32_e32 v92, v93, v92
	ds_bpermute_b32 v153, v90, v143
	v_add_f32_e32 v92, v148, v92
	v_pk_mul_f32 v[138:139], v[68:69], v[68:69]
	v_add_f32_e32 v92, v149, v92
	v_add_f32_e32 v92, v138, v92
	v_add_f32_e32 v92, v139, v92
	ds_bpermute_b32 v93, v91, v92
	s_waitcnt lgkmcnt(1)
	v_add_f32_e32 v143, v143, v153
	v_fmamk_f32 v143, v143, 0x3b800000, v175
	v_mul_f32_e32 v96, 0x4b800000, v143
	v_cmp_gt_f32_e64 s[12:13], s53, v143
	v_cmp_gt_i32_e32 vcc, s50, v192
	s_waitcnt lgkmcnt(0)
	v_add_f32_e32 v97, v92, v93
	v_cndmask_b32_e64 v96, v143, v96, s[12:13]
	v_cndmask_b32_e32 v152, v177, v178, vcc
	v_rsq_f32_e32 v96, v96
	v_and_b32_e32 v152, v152, v192
	ds_bpermute_b32 v138, v90, v97
	v_cndmask_b32_e32 v151, v194, v193, vcc
	v_or_b32_e32 v100, 0x800, v152
	v_lshl_add_u32 v151, v151, 2, s29
	v_cndmask_b32_e32 v100, v100, v152, vcc
	v_mad_i64_i32 v[92:93], s[14:15], v151, s51, v[100:101]
	v_mul_f32_e32 v100, 0x45800000, v96
	v_cndmask_b32_e64 v100, v96, v100, s[12:13]
	v_mul_f32_e32 v96, v100, v100
	s_waitcnt lgkmcnt(0)
	v_add_f32_e32 v97, v97, v138
	v_mul_f32_e32 v96, v97, v96
	v_fmamk_f32 v96, v96, 0x3c2aaaab, v175
	v_mul_f32_e32 v97, 0x4b800000, v96
	v_cmp_gt_f32_e64 s[12:13], s53, v96
	s_nop 1
	v_cndmask_b32_e64 v96, v96, v97, s[12:13]
	v_rsq_f32_e32 v138, v96
	v_mad_u64_u32 v[96:97], s[14:15], v92, s52, v[110:111]
	v_mad_i32_i24 v97, v93, s52, v97
	v_mul_f32_e32 v92, 0x45800000, v138
	v_cndmask_b32_e64 v92, v138, v92, s[12:13]
	v_mul_f32_e32 v92, v100, v92
	v_mul_f32_e32 v92, 0x3e16c7fd, v92
	v_mul_f32_e32 v86, v86, v92
	v_mul_f32_e32 v87, v87, v92
	v_mul_f32_e32 v86, v144, v86
	v_mul_f32_e32 v87, v145, v87
	v_mul_f32_e32 v88, v88, v92
	v_mul_f32_e32 v89, v89, v92
	v_mul_f32_e32 v88, v146, v88
	v_mul_f32_e32 v89, v147, v89
	v_cvt_pk_bf16_f32 v86, v86, v87
	v_cvt_pk_bf16_f32 v87, v88, v89
	global_store_dwordx2 v[96:97], v[86:87], off
	v_mov_b64_e32 v[86:87], v[228:229]
	v_mov_b64_e32 v[88:89], v[230:231]
	v_mul_f32_e32 v82, v82, v92
	v_mul_f32_e32 v83, v83, v92
	v_mul_f32_e32 v84, v84, v92
	v_mul_f32_e32 v85, v85, v92
	v_mul_f32_e32 v78, v78, v92
	v_mul_f32_e32 v79, v79, v92
	v_mul_f32_e32 v80, v80, v92
	v_mul_f32_e32 v81, v81, v92
	v_mul_f32_e32 v74, v74, v92
	v_mul_f32_e32 v75, v75, v92
	v_mul_f32_e32 v76, v76, v92
	v_mul_f32_e32 v77, v77, v92
	v_mul_f32_e32 v70, v70, v92
	v_mul_f32_e32 v71, v71, v92
	v_mul_f32_e32 v72, v72, v92
	v_mul_f32_e32 v73, v73, v92
	v_mul_f32_e32 v66, v66, v92
	v_mul_f32_e32 v67, v67, v92
	v_mul_f32_e32 v68, v68, v92
	v_mul_f32_e32 v69, v69, v92
	v_mul_f32_e32 v82, v86, v82
	v_mul_f32_e32 v83, v87, v83
	v_mul_f32_e32 v84, v88, v84
	v_mul_f32_e32 v85, v89, v85
	v_cvt_pk_bf16_f32 v82, v82, v83
	v_cvt_pk_bf16_f32 v83, v84, v85
	global_store_dwordx2 v[96:97], v[82:83], off offset:32
	v_mov_b64_e32 v[82:83], v[232:233]
	v_mov_b64_e32 v[84:85], v[234:235]
	v_mul_f32_e32 v78, v82, v78
	v_mul_f32_e32 v79, v83, v79
	v_mul_f32_e32 v80, v84, v80
	v_mul_f32_e32 v81, v85, v81
	v_cvt_pk_bf16_f32 v78, v78, v79
	v_cvt_pk_bf16_f32 v79, v80, v81
	global_store_dwordx2 v[96:97], v[78:79], off offset:64
	v_mov_b64_e32 v[78:79], v[236:237]
	v_mov_b64_e32 v[80:81], v[238:239]
	v_mul_f32_e32 v74, v78, v74
	v_mul_f32_e32 v75, v79, v75
	v_mul_f32_e32 v76, v80, v76
	v_mul_f32_e32 v77, v81, v77
	v_cvt_pk_bf16_f32 v74, v74, v75
	v_cvt_pk_bf16_f32 v75, v76, v77
	global_store_dwordx2 v[96:97], v[74:75], off offset:96
	v_mov_b64_e32 v[74:75], v[240:241]
	v_mov_b64_e32 v[76:77], v[242:243]
	v_lshrrev_b32_e32 v78, 6, v152
	v_cvt_f32_ubyte0_e32 v78, v78
	v_mul_f32_e32 v79, v167, v78
	v_mul_f32_e32 v80, v166, v78
	v_mul_f32_e32 v81, v165, v78
	v_mul_f32_e32 v78, v164, v78
	v_mul_f32_e32 v81, 0.15915494, v81
	v_mul_f32_e32 v78, 0.15915494, v78
	v_mul_f32_e32 v79, 0.15915494, v79
	v_mul_f32_e32 v80, 0.15915494, v80
	v_cos_f32_e32 v84, v81
	v_sin_f32_e32 v81, v81
	v_cos_f32_e32 v85, v78
	v_sin_f32_e32 v78, v78
	v_cos_f32_e32 v82, v79
	v_sin_f32_e32 v79, v79
	v_cos_f32_e32 v83, v80
	v_sin_f32_e32 v80, v80
	v_mul_f32_e32 v70, v74, v70
	v_mul_f32_e32 v71, v75, v71
	v_mul_f32_e32 v72, v76, v72
	v_mul_f32_e32 v73, v77, v73
	ds_bpermute_b32 v76, v90, v71
	ds_bpermute_b32 v77, v90, v70
	ds_bpermute_b32 v74, v90, v73
	ds_bpermute_b32 v75, v90, v72
	s_waitcnt lgkmcnt(3)
	v_mul_f32_e32 v76, v81, v76
	s_waitcnt lgkmcnt(2)
	v_mul_f32_e32 v77, v78, v77
	s_waitcnt lgkmcnt(1)
	v_mul_f32_e32 v74, v79, v74
	s_waitcnt lgkmcnt(0)
; __device__ __forceinline__ unsigned pk2(float lo, float hi) { unsigned r; asm volatile("v_cvt_pk_bf16_f32 %0, %1, %2" : "=v"(r) : "v"(lo), "v"(hi)); return r; }
; __device__ __forceinline__ void ph_prep(bf16_t* Z, const bf16_t* WUQ, const bf16_t* WUKV, const bf16_t* D64, const float* qkq, const float* qkk,
;                                         bf16_t* Q, bf16_t* Kb, bf16_t* Vb, bf16_t* F1lat, bf16_t* F1ctx, unsigned char* lds_) { PH_IDS;
;     ...
;             for (int tt = 0; tt < 3; ++tt) {
;                 float s1 = ssq[tt]; s1 += __shfl_xor(s1, 16); s1 += __shfl_xor(s1, 32);
;                 const float rstd = rsqrtf(s1 * (1.f / 256) + EPS);
;                 float ss = 0.f;
; #pragma unroll
;                 for (int nt = 0; nt < 6; ++nt)
; #pragma unroll
;                     for (int r = 0; r < 4; ++r) ss += acc[nt][tt][r] * acc[nt][tt][r];
;                 ss += __shfl_xor(ss, 16); ss += __shfl_xor(ss, 32);
;                 const float fac = rstd * rsqrtf(rstd * rstd * ss * (1.f / 96) + EPS) * 0.14724727430627066f;
;                 const int row = rowc[tt]; const bool lat = row < RL; const int b = row_batch(row), t = lat ? (row & 2047) : ((row - RL) & 255), qi = lat ? t : 2048 + t;
;                 bf16_t* qo = Q + ((size_t)(b * 4 + h) * 2304 + qi) * 96 + 4 * kq;
; #pragma unroll
;                 for (int nt = 0; nt < 6; ++nt) {
;                     const f32x4 w = *(const f32x4*)(qkq + 16 * nt + 4 * kq);
;                     float v[4];
; #pragma unroll
;                     for (int r = 0; r < 4; ++r) v[r] = acc[nt][tt][r] * fac * w[r];
;                     if (nt >= 4) rope16(v, kq, nt == 4 ? (float)(t >> 6) : (float)(t & 63), lat);
;                     fa::u32x2 o; o.x = fa::pk2(v[0], v[1]); o.y = fa::pk2(v[2], v[3]);
;                     if (valid[tt]) *(fa::u32x2*)(qo + 16 * nt) = o;
;                 }
	v_mul_f32_e32 v75, v80, v75
	v_cndmask_b32_e64 v76, v76, -v76, s[4:5]
	v_cndmask_b32_e64 v77, v77, -v77, s[4:5]
	v_cndmask_b32_e64 v74, v74, -v74, s[4:5]
	v_cndmask_b32_e64 v75, v75, -v75, s[4:5]
	v_fmac_f32_e32 v76, v84, v71
	v_fmac_f32_e32 v77, v85, v70
	v_fmac_f32_e32 v74, v82, v73
	v_fmac_f32_e32 v75, v83, v72
	v_cndmask_b32_e32 v71, v71, v76, vcc
	v_cndmask_b32_e32 v70, v70, v77, vcc
	v_cndmask_b32_e32 v73, v73, v74, vcc
	v_cndmask_b32_e32 v72, v72, v75, vcc
	v_cvt_pk_bf16_f32 v70, v70, v71
	v_cvt_pk_bf16_f32 v71, v72, v73
	global_store_dwordx2 v[96:97], v[70:71], off offset:128
	v_mov_b64_e32 v[70:71], v[244:245]
	v_mov_b64_e32 v[72:73], v[246:247]
	v_mul_f32_e32 v76, v165, v191
	v_mul_f32_e32 v77, v164, v191
	v_mul_f32_e32 v74, v167, v191
	v_mul_f32_e32 v75, v166, v191
	v_mul_f32_e32 v76, 0.15915494, v76
	v_mul_f32_e32 v77, 0.15915494, v77
	v_mul_f32_e32 v74, 0.15915494, v74
	v_mul_f32_e32 v75, 0.15915494, v75
	v_cos_f32_e32 v80, v76
	v_sin_f32_e32 v76, v76
	v_cos_f32_e32 v81, v77
	v_sin_f32_e32 v77, v77
	v_cos_f32_e32 v78, v74
	v_sin_f32_e32 v74, v74
	v_cos_f32_e32 v79, v75
	v_sin_f32_e32 v75, v75
	ds_bpermute_b32 v82, v91, v95
	v_mul_f32_e32 v66, v66, v70
	v_mul_f32_e32 v67, v67, v71
	v_mul_f32_e32 v68, v68, v72
	v_mul_f32_e32 v69, v69, v73
	ds_bpermute_b32 v72, v90, v67
	ds_bpermute_b32 v73, v90, v66
	ds_bpermute_b32 v70, v90, v69
	ds_bpermute_b32 v71, v90, v68
	s_waitcnt lgkmcnt(3)
	v_mul_f32_e32 v72, v76, v72
	s_waitcnt lgkmcnt(2)
	v_mul_f32_e32 v73, v77, v73
	s_waitcnt lgkmcnt(1)
	v_mul_f32_e32 v70, v74, v70
	s_waitcnt lgkmcnt(0)
	v_mul_f32_e32 v71, v75, v71
	v_cndmask_b32_e64 v72, v72, -v72, s[4:5]
	v_cndmask_b32_e64 v73, v73, -v73, s[4:5]
	v_cndmask_b32_e64 v70, v70, -v70, s[4:5]
	v_cndmask_b32_e64 v71, v71, -v71, s[4:5]
	v_fmac_f32_e32 v72, v80, v67
	v_fmac_f32_e32 v73, v81, v66
	v_fmac_f32_e32 v70, v78, v69
	v_fmac_f32_e32 v71, v79, v68
	v_cndmask_b32_e32 v67, v67, v72, vcc
	v_cndmask_b32_e32 v66, v66, v73, vcc
	v_cndmask_b32_e32 v69, v69, v70, vcc
	v_cndmask_b32_e32 v68, v68, v71, vcc
	v_cvt_pk_bf16_f32 v66, v66, v67
	v_cvt_pk_bf16_f32 v67, v68, v69
	global_store_dwordx2 v[96:97], v[66:67], off offset:160
	v_mov_b64_e32 v[70:71], v[224:225]
	v_mov_b64_e32 v[72:73], v[226:227]
	v_mul_f32_e32 v68, v63, v63
	v_fmac_f32_e32 v68, v62, v62
	v_fmac_f32_e32 v68, v64, v64
	v_fmac_f32_e32 v68, v65, v65
	v_fmac_f32_e32 v68, v58, v58
	v_fmac_f32_e32 v68, v59, v59
	v_fmac_f32_e32 v68, v60, v60
	v_fmac_f32_e32 v68, v61, v61
	v_fmac_f32_e32 v68, v54, v54
	v_fmac_f32_e32 v68, v55, v55
	v_fmac_f32_e32 v68, v56, v56
	v_fmac_f32_e32 v68, v57, v57
	v_fmac_f32_e32 v68, v46, v46
	v_fmac_f32_e32 v68, v47, v47
	v_fmac_f32_e32 v68, v48, v48
	v_pk_mul_f32 v[74:75], v[50:51], v[50:51]
	v_cmp_gt_i32_e32 vcc, s50, v188
	v_fmac_f32_e32 v68, v49, v49
	v_add_f32_e32 v68, v74, v68
	v_cndmask_b32_e32 v69, v190, v189, vcc
	v_cndmask_b32_e32 v80, v177, v178, vcc
	v_pk_mul_f32 v[66:67], v[52:53], v[52:53]
	v_lshl_add_u32 v81, v69, 2, s29
	v_and_b32_e32 v69, v80, v188
	v_add_f32_e32 v68, v75, v68
	v_or_b32_e32 v80, 0x800, v69
	v_add_f32_e32 v66, v66, v68
	v_pk_mul_f32 v[78:79], v[42:43], v[42:43]
	v_cndmask_b32_e32 v100, v80, v69, vcc
	v_add_f32_e32 v80, v95, v82
	v_add_f32_e32 v66, v67, v66
	ds_bpermute_b32 v82, v90, v80
	v_add_f32_e32 v66, v78, v66
	v_pk_mul_f32 v[76:77], v[44:45], v[44:45]
	v_add_f32_e32 v66, v79, v66
	v_add_f32_e32 v66, v76, v66
	v_add_f32_e32 v66, v77, v66
	ds_bpermute_b32 v67, v91, v66
	s_waitcnt lgkmcnt(1)
	v_add_f32_e32 v80, v80, v82
	v_fmamk_f32 v80, v80, 0x3b800000, v175
	v_mul_f32_e32 v68, 0x4b800000, v80
	v_cmp_gt_f32_e64 s[12:13], s53, v80
	s_waitcnt lgkmcnt(0)
	v_add_f32_e32 v66, v66, v67
	ds_bpermute_b32 v67, v90, v66
	v_cndmask_b32_e64 v68, v80, v68, s[12:13]
	v_rsq_f32_e32 v68, v68
	v_mad_i64_i32 v[74:75], s[14:15], v81, s51, v[100:101]
	s_waitcnt lgkmcnt(0)
	v_add_f32_e32 v66, v66, v67
	v_mul_f32_e32 v76, 0x45800000, v68
	v_cndmask_b32_e64 v68, v68, v76, s[12:13]
	v_mul_f32_e32 v76, v68, v68
	v_mul_f32_e32 v66, v66, v76
	v_fmamk_f32 v66, v66, 0x3c2aaaab, v175
	v_mul_f32_e32 v67, 0x4b800000, v66
	v_cmp_gt_f32_e64 s[12:13], s53, v66
	s_nop 1
	v_cndmask_b32_e64 v66, v66, v67, s[12:13]
	v_rsq_f32_e32 v76, v66
	v_mad_u64_u32 v[66:67], s[14:15], v74, s52, v[110:111]
	v_mad_i32_i24 v67, v75, s52, v67
	v_mul_f32_e32 v74, 0x45800000, v76
	v_cndmask_b32_e64 v74, v76, v74, s[12:13]
	v_mul_f32_e32 v68, v68, v74
	v_mul_f32_e32 v68, 0x3e16c7fd, v68
	v_mul_f32_e32 v62, v62, v68
	v_mul_f32_e32 v63, v63, v68
	v_mul_f32_e32 v64, v64, v68
	v_mul_f32_e32 v65, v65, v68
	v_mul_f32_e32 v62, v70, v62
	v_mul_f32_e32 v63, v71, v63
	v_mul_f32_e32 v64, v72, v64
	v_mul_f32_e32 v65, v73, v65
	v_cvt_pk_bf16_f32 v62, v62, v63
	v_cvt_pk_bf16_f32 v63, v64, v65
	s_and_saveexec_b64 s[12:13], s[10:11]
	s_cbranch_execz .LBB0_576
	global_store_dwordx2 v[66:67], v[62:63], off
.LBB0_576:
	s_or_b64 exec, exec, s[12:13]
	v_mov_b64_e32 v[62:63], v[228:229]
	v_mov_b64_e32 v[64:65], v[230:231]
	v_mul_f32_e32 v58, v58, v68
	v_mul_f32_e32 v59, v59, v68
	v_mul_f32_e32 v60, v60, v68
	v_mul_f32_e32 v61, v61, v68
	v_mul_f32_e32 v58, v58, v62
	v_mul_f32_e32 v59, v59, v63
	v_mul_f32_e32 v60, v60, v64
	v_mul_f32_e32 v61, v61, v65
	v_cvt_pk_bf16_f32 v58, v58, v59
	v_cvt_pk_bf16_f32 v59, v60, v61
	s_and_saveexec_b64 s[12:13], s[10:11]
	s_cbranch_execz .LBB0_578
	global_store_dwordx2 v[66:67], v[58:59], off offset:32
; __device__ __forceinline__ unsigned pk2(float lo, float hi) { unsigned r; asm volatile("v_cvt_pk_bf16_f32 %0, %1, %2" : "=v"(r) : "v"(lo), "v"(hi)); return r; }
; __device__ __forceinline__ void ph_prep(bf16_t* Z, const bf16_t* WUQ, const bf16_t* WUKV, const bf16_t* D64, const float* qkq, const float* qkk,
;                                         bf16_t* Q, bf16_t* Kb, bf16_t* Vb, bf16_t* F1lat, bf16_t* F1ctx, unsigned char* lds_) { PH_IDS;
;     ...
;                 for (int nt = 0; nt < 6; ++nt) {
;                     const f32x4 w = *(const f32x4*)(qkq + 16 * nt + 4 * kq);
;                     float v[4];
; #pragma unroll
;                     for (int r = 0; r < 4; ++r) v[r] = acc[nt][tt][r] * fac * w[r];
;                     if (nt >= 4) rope16(v, kq, nt == 4 ? (float)(t >> 6) : (float)(t & 63), lat);
;                     fa::u32x2 o; o.x = fa::pk2(v[0], v[1]); o.y = fa::pk2(v[2], v[3]);
;                     if (valid[tt]) *(fa::u32x2*)(qo + 16 * nt) = o;
;                 }
.LBB0_578:
	s_or_b64 exec, exec, s[12:13]
	v_mov_b64_e32 v[58:59], v[232:233]
	v_mov_b64_e32 v[60:61], v[234:235]
	v_mul_f32_e32 v54, v54, v68
	v_mul_f32_e32 v55, v55, v68
	v_mul_f32_e32 v56, v56, v68
	v_mul_f32_e32 v57, v57, v68
	v_mul_f32_e32 v54, v54, v58
	v_mul_f32_e32 v55, v55, v59
	v_mul_f32_e32 v56, v56, v60
	v_mul_f32_e32 v57, v57, v61
	v_cvt_pk_bf16_f32 v54, v54, v55
	v_cvt_pk_bf16_f32 v55, v56, v57
	s_and_saveexec_b64 s[12:13], s[10:11]
	s_cbranch_execz .LBB0_580
	global_store_dwordx2 v[66:67], v[54:55], off offset:64
.LBB0_580:
	s_or_b64 exec, exec, s[12:13]
	v_mov_b64_e32 v[54:55], v[236:237]
	v_mov_b64_e32 v[56:57], v[238:239]
	v_mul_f32_e32 v46, v46, v68
	v_mul_f32_e32 v47, v47, v68
	v_mul_f32_e32 v48, v48, v68
	v_mul_f32_e32 v49, v49, v68
	v_mul_f32_e32 v46, v46, v54
	v_mul_f32_e32 v47, v47, v55
	v_mul_f32_e32 v48, v48, v56
	v_mul_f32_e32 v49, v49, v57
	v_cvt_pk_bf16_f32 v46, v46, v47
	v_cvt_pk_bf16_f32 v47, v48, v49
	s_and_saveexec_b64 s[12:13], s[10:11]
	s_cbranch_execz .LBB0_582
	global_store_dwordx2 v[66:67], v[46:47], off offset:96
.LBB0_582:
	s_or_b64 exec, exec, s[12:13]
	v_mov_b64_e32 v[46:47], v[240:241]
	v_mov_b64_e32 v[48:49], v[242:243]
	v_lshrrev_b32_e32 v54, 6, v69
	v_mul_f32_e32 v50, v50, v68
	v_mul_f32_e32 v51, v51, v68
	v_cvt_f32_ubyte0_e32 v54, v54
	v_mul_f32_e32 v52, v52, v68
	v_mul_f32_e32 v53, v53, v68
	v_mul_f32_e32 v55, v167, v54
	v_mul_f32_e32 v56, v166, v54
	v_mul_f32_e32 v57, v165, v54
	v_mul_f32_e32 v54, v164, v54
	v_mul_f32_e32 v57, 0.15915494, v57
	v_mul_f32_e32 v54, 0.15915494, v54
	v_mul_f32_e32 v55, 0.15915494, v55
	v_mul_f32_e32 v56, 0.15915494, v56
	v_cos_f32_e32 v60, v57
	v_sin_f32_e32 v57, v57
	v_cos_f32_e32 v61, v54
	v_sin_f32_e32 v54, v54
	v_cos_f32_e32 v58, v55
	v_sin_f32_e32 v55, v55
	v_cos_f32_e32 v59, v56
	v_sin_f32_e32 v56, v56
	v_mul_f32_e32 v46, v50, v46
	v_mul_f32_e32 v47, v51, v47
	v_mul_f32_e32 v48, v52, v48
	v_mul_f32_e32 v49, v53, v49
	ds_bpermute_b32 v52, v90, v47
	ds_bpermute_b32 v53, v90, v46
	ds_bpermute_b32 v50, v90, v49
	ds_bpermute_b32 v51, v90, v48
	s_waitcnt lgkmcnt(3)
	v_mul_f32_e32 v52, v57, v52
	s_waitcnt lgkmcnt(2)
	v_mul_f32_e32 v53, v54, v53
	s_waitcnt lgkmcnt(1)
	v_mul_f32_e32 v50, v55, v50
	s_waitcnt lgkmcnt(0)
	v_mul_f32_e32 v51, v56, v51
	v_cndmask_b32_e64 v52, v52, -v52, s[4:5]
	v_cndmask_b32_e64 v53, v53, -v53, s[4:5]
	v_cndmask_b32_e64 v50, v50, -v50, s[4:5]
	v_cndmask_b32_e64 v51, v51, -v51, s[4:5]
	v_fmac_f32_e32 v52, v60, v47
	v_fmac_f32_e32 v53, v61, v46
	v_fmac_f32_e32 v50, v58, v49
	v_fmac_f32_e32 v51, v59, v48
	v_cndmask_b32_e32 v47, v47, v52, vcc
	v_cndmask_b32_e32 v46, v46, v53, vcc
	v_cndmask_b32_e32 v49, v49, v50, vcc
	v_cndmask_b32_e32 v48, v48, v51, vcc
	v_cvt_pk_bf16_f32 v46, v46, v47
	v_cvt_pk_bf16_f32 v47, v48, v49
	s_and_saveexec_b64 s[12:13], s[10:11]
	s_cbranch_execz .LBB0_584
	global_store_dwordx2 v[66:67], v[46:47], off offset:128
.LBB0_584:
	s_or_b64 exec, exec, s[12:13]
	v_mov_b64_e32 v[46:47], v[244:245]
	v_mov_b64_e32 v[48:49], v[246:247]
	v_mul_f32_e32 v42, v42, v68
	v_mul_f32_e32 v43, v43, v68
	v_mul_f32_e32 v44, v44, v68
	v_mul_f32_e32 v45, v45, v68
	v_mul_f32_e32 v52, v165, v187
	v_mul_f32_e32 v53, v164, v187
	v_mul_f32_e32 v50, v167, v187
	v_mul_f32_e32 v51, v166, v187
	v_mul_f32_e32 v52, 0.15915494, v52
	v_mul_f32_e32 v53, 0.15915494, v53
	v_mul_f32_e32 v50, 0.15915494, v50
	v_mul_f32_e32 v51, 0.15915494, v51
	v_cos_f32_e32 v56, v52
	v_sin_f32_e32 v52, v52
	v_cos_f32_e32 v57, v53
	v_sin_f32_e32 v53, v53
	v_cos_f32_e32 v54, v50
	v_sin_f32_e32 v50, v50
	v_cos_f32_e32 v55, v51
	v_sin_f32_e32 v51, v51
	v_mul_f32_e32 v42, v42, v46
	v_mul_f32_e32 v43, v43, v47
	v_mul_f32_e32 v44, v44, v48
	v_mul_f32_e32 v45, v45, v49
	ds_bpermute_b32 v48, v90, v43
	ds_bpermute_b32 v49, v90, v42
	ds_bpermute_b32 v46, v90, v45
	ds_bpermute_b32 v47, v90, v44
	s_waitcnt lgkmcnt(3)
	v_mul_f32_e32 v48, v52, v48
	s_waitcnt lgkmcnt(2)
	v_mul_f32_e32 v49, v53, v49
	s_waitcnt lgkmcnt(1)
	v_mul_f32_e32 v46, v50, v46
	s_waitcnt lgkmcnt(0)
	v_mul_f32_e32 v47, v51, v47
	v_cndmask_b32_e64 v48, v48, -v48, s[4:5]
	v_cndmask_b32_e64 v49, v49, -v49, s[4:5]
	v_cndmask_b32_e64 v46, v46, -v46, s[4:5]
	v_cndmask_b32_e64 v47, v47, -v47, s[4:5]
	v_fmac_f32_e32 v48, v56, v43
	v_fmac_f32_e32 v49, v57, v42
	v_fmac_f32_e32 v46, v54, v45
	v_fmac_f32_e32 v47, v55, v44
	v_cndmask_b32_e32 v43, v43, v48, vcc
	v_cndmask_b32_e32 v42, v42, v49, vcc
	v_cndmask_b32_e32 v45, v45, v46, vcc
	v_cndmask_b32_e32 v44, v44, v47, vcc
	v_cvt_pk_bf16_f32 v42, v42, v43
	v_cvt_pk_bf16_f32 v43, v44, v45
	s_and_saveexec_b64 s[12:13], s[10:11]
	s_cbranch_execz .LBB0_586
	global_store_dwordx2 v[66:67], v[42:43], off offset:160
; __device__ __forceinline__ unsigned pk2(float lo, float hi) { unsigned r; asm volatile("v_cvt_pk_bf16_f32 %0, %1, %2" : "=v"(r) : "v"(lo), "v"(hi)); return r; }
; __device__ __forceinline__ void ph_prep(bf16_t* Z, const bf16_t* WUQ, const bf16_t* WUKV, const bf16_t* D64, const float* qkq, const float* qkk,
;                                         bf16_t* Q, bf16_t* Kb, bf16_t* Vb, bf16_t* F1lat, bf16_t* F1ctx, unsigned char* lds_) { PH_IDS;
;     ...
;             for (int tt = 0; tt < 3; ++tt) {
;                 float s1 = ssq[tt]; s1 += __shfl_xor(s1, 16); s1 += __shfl_xor(s1, 32);
;                 const float rstd = rsqrtf(s1 * (1.f / 256) + EPS);
;                 float ss = 0.f;
; #pragma unroll
;                 for (int nt = 0; nt < 6; ++nt)
; #pragma unroll
;                     for (int r = 0; r < 4; ++r) ss += acc[nt][tt][r] * acc[nt][tt][r];
;                 ss += __shfl_xor(ss, 16); ss += __shfl_xor(ss, 32);
;                 const float fac = rstd * rsqrtf(rstd * rstd * ss * (1.f / 96) + EPS) * 0.14724727430627066f;
;                 const int row = rowc[tt]; const bool lat = row < RL; const int b = row_batch(row), t = lat ? (row & 2047) : ((row - RL) & 255), qi = lat ? t : 2048 + t;
;                 bf16_t* qo = Q + ((size_t)(b * 4 + h) * 2304 + qi) * 96 + 4 * kq;
; #pragma unroll
;                 for (int nt = 0; nt < 6; ++nt) {
;                     const f32x4 w = *(const f32x4*)(qkq + 16 * nt + 4 * kq);
;                     float v[4];
; #pragma unroll
;                     for (int r = 0; r < 4; ++r) v[r] = acc[nt][tt][r] * fac * w[r];
;                     if (nt >= 4) rope16(v, kq, nt == 4 ? (float)(t >> 6) : (float)(t & 63), lat);
;                     fa::u32x2 o; o.x = fa::pk2(v[0], v[1]); o.y = fa::pk2(v[2], v[3]);
;                     if (valid[tt]) *(fa::u32x2*)(qo + 16 * nt) = o;
;                 }
.LBB0_586:
	s_or_b64 exec, exec, s[12:13]
	v_mov_b64_e32 v[46:47], v[224:225]
	v_mov_b64_e32 v[48:49], v[226:227]
	v_mul_f32_e32 v56, v39, v39
	v_fmac_f32_e32 v56, v38, v38
	v_fmac_f32_e32 v56, v40, v40
	v_fmac_f32_e32 v56, v41, v41
	v_fmac_f32_e32 v56, v34, v34
	v_fmac_f32_e32 v56, v35, v35
	v_fmac_f32_e32 v56, v36, v36
	v_fmac_f32_e32 v56, v37, v37
	v_fmac_f32_e32 v56, v30, v30
	v_fmac_f32_e32 v56, v31, v31
	v_fmac_f32_e32 v56, v32, v32
	v_fmac_f32_e32 v56, v33, v33
	v_fmac_f32_e32 v56, v22, v22
	v_fmac_f32_e32 v56, v23, v23
	ds_bpermute_b32 v44, v91, v94
	v_fmac_f32_e32 v56, v24, v24
	v_pk_mul_f32 v[50:51], v[26:27], v[26:27]
	v_fmac_f32_e32 v56, v25, v25
	v_cmp_gt_i32_e32 vcc, s50, v184
	v_add_f32_e32 v50, v50, v56
	v_pk_mul_f32 v[42:43], v[28:29], v[28:29]
	v_cndmask_b32_e32 v45, v186, v185, vcc
	v_cndmask_b32_e32 v57, v177, v178, vcc
	v_add_f32_e32 v50, v51, v50
	v_lshl_add_u32 v58, v45, 2, s29
	v_and_b32_e32 v45, v57, v184
	v_add_f32_e32 v42, v42, v50
	v_pk_mul_f32 v[54:55], v[18:19], v[18:19]
	v_or_b32_e32 v57, 0x800, v45
	s_waitcnt lgkmcnt(0)
	v_add_f32_e32 v44, v94, v44
	v_add_f32_e32 v42, v43, v42
	v_cndmask_b32_e32 v100, v57, v45, vcc
	ds_bpermute_b32 v57, v90, v44
	v_add_f32_e32 v42, v54, v42
	v_pk_mul_f32 v[52:53], v[20:21], v[20:21]
	v_add_f32_e32 v42, v55, v42
	v_add_f32_e32 v42, v52, v42
	v_add_f32_e32 v42, v53, v42
	ds_bpermute_b32 v43, v91, v42
	s_waitcnt lgkmcnt(1)
	v_add_f32_e32 v44, v44, v57
	v_fmamk_f32 v44, v44, 0x3b800000, v175
	v_mul_f32_e32 v50, 0x4b800000, v44
	v_cmp_gt_f32_e64 s[10:11], s53, v44
	s_waitcnt lgkmcnt(0)
	v_add_f32_e32 v42, v42, v43
	ds_bpermute_b32 v43, v90, v42
	v_cndmask_b32_e64 v44, v44, v50, s[10:11]
	v_rsq_f32_e32 v44, v44
	v_mad_i64_i32 v[50:51], s[12:13], v58, s51, v[100:101]
	s_waitcnt lgkmcnt(0)
	v_add_f32_e32 v42, v42, v43
	v_mul_f32_e32 v52, 0x45800000, v44
	v_cndmask_b32_e64 v44, v44, v52, s[10:11]
	v_mul_f32_e32 v52, v44, v44
	v_mul_f32_e32 v42, v42, v52
	v_fmamk_f32 v42, v42, 0x3c2aaaab, v175
	v_mul_f32_e32 v43, 0x4b800000, v42
	v_cmp_gt_f32_e64 s[10:11], s53, v42
	s_nop 1
	v_cndmask_b32_e64 v42, v42, v43, s[10:11]
	v_rsq_f32_e32 v52, v42
	v_mad_u64_u32 v[42:43], s[12:13], v50, s52, v[110:111]
	v_mad_i32_i24 v43, v51, s52, v43
	v_mul_f32_e32 v50, 0x45800000, v52
	v_cndmask_b32_e64 v50, v52, v50, s[10:11]
	v_mul_f32_e32 v44, v44, v50
	v_mul_f32_e32 v44, 0x3e16c7fd, v44
	v_mul_f32_e32 v38, v38, v44
	v_mul_f32_e32 v39, v39, v44
	v_mul_f32_e32 v40, v40, v44
	v_mul_f32_e32 v41, v41, v44
	v_mul_f32_e32 v38, v46, v38
	v_mul_f32_e32 v39, v47, v39
	v_mul_f32_e32 v40, v48, v40
	v_mul_f32_e32 v41, v49, v41
	v_cvt_pk_bf16_f32 v38, v38, v39
	v_cvt_pk_bf16_f32 v39, v40, v41
	s_and_saveexec_b64 s[10:11], s[8:9]
	s_cbranch_execz .LBB0_588
	global_store_dwordx2 v[42:43], v[38:39], off
.LBB0_588:
	s_or_b64 exec, exec, s[10:11]
	v_mov_b64_e32 v[38:39], v[228:229]
	v_mov_b64_e32 v[40:41], v[230:231]
	v_mul_f32_e32 v34, v34, v44
	v_mul_f32_e32 v35, v35, v44
	v_mul_f32_e32 v36, v36, v44
	v_mul_f32_e32 v37, v37, v44
	v_mul_f32_e32 v34, v34, v38
	v_mul_f32_e32 v35, v35, v39
	v_mul_f32_e32 v36, v36, v40
	v_mul_f32_e32 v37, v37, v41
	v_cvt_pk_bf16_f32 v34, v34, v35
	v_cvt_pk_bf16_f32 v35, v36, v37
	s_and_saveexec_b64 s[10:11], s[8:9]
	s_cbranch_execz .LBB0_590
	global_store_dwordx2 v[42:43], v[34:35], off offset:32
.LBB0_590:
	s_or_b64 exec, exec, s[10:11]
	v_mov_b64_e32 v[34:35], v[232:233]
	v_mov_b64_e32 v[36:37], v[234:235]
	v_mul_f32_e32 v30, v30, v44
	v_mul_f32_e32 v31, v31, v44
	v_mul_f32_e32 v32, v32, v44
	v_mul_f32_e32 v33, v33, v44
	v_mul_f32_e32 v30, v30, v34
	v_mul_f32_e32 v31, v31, v35
	v_mul_f32_e32 v32, v32, v36
	v_mul_f32_e32 v33, v33, v37
	v_cvt_pk_bf16_f32 v30, v30, v31
	v_cvt_pk_bf16_f32 v31, v32, v33
	s_and_saveexec_b64 s[10:11], s[8:9]
	s_cbranch_execz .LBB0_592
	global_store_dwordx2 v[42:43], v[30:31], off offset:64
; __device__ __forceinline__ unsigned pk2(float lo, float hi) { unsigned r; asm volatile("v_cvt_pk_bf16_f32 %0, %1, %2" : "=v"(r) : "v"(lo), "v"(hi)); return r; }
; __device__ __forceinline__ void ph_prep(bf16_t* Z, const bf16_t* WUQ, const bf16_t* WUKV, const bf16_t* D64, const float* qkq, const float* qkk,
;                                         bf16_t* Q, bf16_t* Kb, bf16_t* Vb, bf16_t* F1lat, bf16_t* F1ctx, unsigned char* lds_) { PH_IDS;
;     ...
;                 for (int nt = 0; nt < 6; ++nt) {
;                     const f32x4 w = *(const f32x4*)(qkq + 16 * nt + 4 * kq);
;                     float v[4];
; #pragma unroll
;                     for (int r = 0; r < 4; ++r) v[r] = acc[nt][tt][r] * fac * w[r];
;                     if (nt >= 4) rope16(v, kq, nt == 4 ? (float)(t >> 6) : (float)(t & 63), lat);
;                     fa::u32x2 o; o.x = fa::pk2(v[0], v[1]); o.y = fa::pk2(v[2], v[3]);
;                     if (valid[tt]) *(fa::u32x2*)(qo + 16 * nt) = o;
;                 }
.LBB0_592:
	s_or_b64 exec, exec, s[10:11]
	v_mov_b64_e32 v[30:31], v[236:237]
	v_mov_b64_e32 v[32:33], v[238:239]
	v_mul_f32_e32 v22, v22, v44
	v_mul_f32_e32 v23, v23, v44
	v_mul_f32_e32 v24, v24, v44
	v_mul_f32_e32 v25, v25, v44
	v_mul_f32_e32 v22, v22, v30
	v_mul_f32_e32 v23, v23, v31
	v_mul_f32_e32 v24, v24, v32
	v_mul_f32_e32 v25, v25, v33
	v_cvt_pk_bf16_f32 v22, v22, v23
	v_cvt_pk_bf16_f32 v23, v24, v25
	s_and_saveexec_b64 s[10:11], s[8:9]
	s_cbranch_execz .LBB0_594
	global_store_dwordx2 v[42:43], v[22:23], off offset:96
.LBB0_594:
	s_or_b64 exec, exec, s[10:11]
	v_mov_b64_e32 v[22:23], v[240:241]
	v_mov_b64_e32 v[24:25], v[242:243]
	v_lshrrev_b32_e32 v30, 6, v45
	v_mul_f32_e32 v26, v26, v44
	v_mul_f32_e32 v27, v27, v44
	v_cvt_f32_ubyte0_e32 v30, v30
	v_mul_f32_e32 v28, v28, v44
	v_mul_f32_e32 v29, v29, v44
	v_mul_f32_e32 v31, v167, v30
	v_mul_f32_e32 v32, v166, v30
	v_mul_f32_e32 v33, v165, v30
	v_mul_f32_e32 v30, v164, v30
	v_mul_f32_e32 v33, 0.15915494, v33
	v_mul_f32_e32 v30, 0.15915494, v30
	v_mul_f32_e32 v31, 0.15915494, v31
	v_mul_f32_e32 v32, 0.15915494, v32
	v_cos_f32_e32 v36, v33
	v_sin_f32_e32 v33, v33
	v_cos_f32_e32 v37, v30
	v_sin_f32_e32 v30, v30
	v_cos_f32_e32 v34, v31
	v_sin_f32_e32 v31, v31
	v_cos_f32_e32 v35, v32
	v_sin_f32_e32 v32, v32
	v_mul_f32_e32 v22, v26, v22
	v_mul_f32_e32 v23, v27, v23
	v_mul_f32_e32 v24, v28, v24
	v_mul_f32_e32 v25, v29, v25
	ds_bpermute_b32 v28, v90, v23
	ds_bpermute_b32 v29, v90, v22
	ds_bpermute_b32 v26, v90, v25
	ds_bpermute_b32 v27, v90, v24
	s_waitcnt lgkmcnt(3)
	v_mul_f32_e32 v28, v33, v28
	s_waitcnt lgkmcnt(2)
	v_mul_f32_e32 v29, v30, v29
	s_waitcnt lgkmcnt(1)
	v_mul_f32_e32 v26, v31, v26
	s_waitcnt lgkmcnt(0)
	v_mul_f32_e32 v27, v32, v27
	v_cndmask_b32_e64 v28, v28, -v28, s[4:5]
	v_cndmask_b32_e64 v29, v29, -v29, s[4:5]
	v_cndmask_b32_e64 v26, v26, -v26, s[4:5]
	v_cndmask_b32_e64 v27, v27, -v27, s[4:5]
	v_fmac_f32_e32 v28, v36, v23
	v_fmac_f32_e32 v29, v37, v22
	v_fmac_f32_e32 v26, v34, v25
	v_fmac_f32_e32 v27, v35, v24
	v_cndmask_b32_e32 v23, v23, v28, vcc
	v_cndmask_b32_e32 v22, v22, v29, vcc
	v_cndmask_b32_e32 v25, v25, v26, vcc
	v_cndmask_b32_e32 v24, v24, v27, vcc
	v_cvt_pk_bf16_f32 v22, v22, v23
	v_cvt_pk_bf16_f32 v23, v24, v25
	s_and_saveexec_b64 s[10:11], s[8:9]
	s_cbranch_execz .LBB0_596
	global_store_dwordx2 v[42:43], v[22:23], off offset:128
.LBB0_596:
	s_or_b64 exec, exec, s[10:11]
	v_mov_b64_e32 v[22:23], v[244:245]
	v_mov_b64_e32 v[24:25], v[246:247]
	v_mul_f32_e32 v18, v18, v44
	v_mul_f32_e32 v19, v19, v44
	v_mul_f32_e32 v20, v20, v44
	v_mul_f32_e32 v21, v21, v44
	v_mul_f32_e32 v26, v164, v183
	v_mul_f32_e32 v27, v165, v183
	v_mul_f32_e32 v28, v166, v183
	v_mul_f32_e32 v29, v167, v183
	v_mul_f32_e32 v26, 0.15915494, v26
	v_mul_f32_e32 v27, 0.15915494, v27
	v_mul_f32_e32 v28, 0.15915494, v28
	v_mul_f32_e32 v29, 0.15915494, v29
	v_cos_f32_e32 v30, v26
	v_sin_f32_e32 v26, v26
	v_cos_f32_e32 v31, v27
	v_sin_f32_e32 v27, v27
	v_cos_f32_e32 v32, v28
	v_sin_f32_e32 v28, v28
	v_cos_f32_e32 v33, v29
	v_sin_f32_e32 v29, v29
	v_mul_f32_e32 v18, v18, v22
	v_mul_f32_e32 v19, v19, v23
	v_mul_f32_e32 v20, v20, v24
	v_mul_f32_e32 v21, v21, v25
	ds_bpermute_b32 v22, v90, v18
	ds_bpermute_b32 v23, v90, v19
	ds_bpermute_b32 v24, v90, v20
	ds_bpermute_b32 v25, v90, v21
	s_waitcnt lgkmcnt(3)
	v_mul_f32_e32 v22, v26, v22
	s_waitcnt lgkmcnt(2)
	v_mul_f32_e32 v23, v27, v23
	s_waitcnt lgkmcnt(1)
	v_mul_f32_e32 v24, v28, v24
	s_waitcnt lgkmcnt(0)
	v_mul_f32_e32 v25, v29, v25
	v_cndmask_b32_e64 v22, v22, -v22, s[4:5]
	v_cndmask_b32_e64 v23, v23, -v23, s[4:5]
	v_cndmask_b32_e64 v24, v24, -v24, s[4:5]
	v_cndmask_b32_e64 v25, v25, -v25, s[4:5]
	v_fmac_f32_e32 v22, v30, v18
	v_fmac_f32_e32 v23, v31, v19
	v_fmac_f32_e32 v24, v32, v20
	v_fmac_f32_e32 v25, v33, v21
	v_cndmask_b32_e32 v18, v18, v22, vcc
	v_cndmask_b32_e32 v19, v19, v23, vcc
	v_cndmask_b32_e32 v20, v20, v24, vcc
	v_cndmask_b32_e32 v21, v21, v25, vcc
	v_cvt_pk_bf16_f32 v18, v18, v19
	v_cvt_pk_bf16_f32 v19, v20, v21
	s_and_saveexec_b64 s[10:11], s[8:9]
	s_cbranch_execz .LBB0_598
	global_store_dwordx2 v[42:43], v[18:19], off offset:160

; __device__ __forceinline__ void ph_prep(bf16_t* Z, const bf16_t* WUQ, const bf16_t* WUKV, const bf16_t* D64, const float* qkq, const float* qkk,
;                                         bf16_t* Q, bf16_t* Kb, bf16_t* Vb, bf16_t* F1lat, bf16_t* F1ctx, unsigned char* lds_) { PH_IDS;
;     ...
;         int rowc[3], rl[3]; bool valid[3];
; #pragma unroll
;         for (int tt = 0; tt < 3; ++tt) { const int o = 16 * (3 * pass3 + tt) + c16; valid[tt] = o < 72; rl[tt] = valid[tt] ? o : 71; rowc[tt] = row0 + rl[tt]; }
;         if (wid < 4) {
;     ...
;                     const int row = rowc[tt]; const bool lat = row < RL; const int b = row_batch(row), t = lat ? (row & 2047) : ((row - RL) & 255), ki = lat ? 256 + t : t;
;                     if (pass == 0) {
;                         float s1 = ssq[tt]; s1 += __shfl_xor(s1, 16); s1 += __shfl_xor(s1, 32);
;                         rstd[tt] = rsqrtf(s1 * (1.f / 128) + EPS);
;                         float kr[2][4];
; #pragma unroll
;                         for (int e = 0; e < 2; ++e) { const fa::u32x2 w = *(const LAS fa::u32x2*)(sm + O_KV + rl[tt] * P_KV + (128 + 16 * e + 4 * kq) * 2);
;                             kr[e][0] = __uint_as_float(w.x << 16); kr[e][1] = __uint_as_float(w.x & 0xffff0000u); kr[e][2] = __uint_as_float(w.y << 16); kr[e][3] = __uint_as_float(w.y & 0xffff0000u); }
;                         float ss = 0.f;
; #pragma unroll
;                         for (int nt = 0; nt < 4; ++nt)
; #pragma unroll
;                             for (int r = 0; r < 4; ++r) { acc[nt][tt][r] *= rstd[tt]; ss += acc[nt][tt][r] * acc[nt][tt][r]; }
; #pragma unroll
;                         for (int e = 0; e < 2; ++e)
; #pragma unroll
;                             for (int r = 0; r < 4; ++r) ss += kr[e][r] * kr[e][r];
;                         ss += __shfl_xor(ss, 16); ss += __shfl_xor(ss, 32);
;                         const float fac = rsqrtf(ss * (1.f / 96) + EPS);
;                         bf16_t* ko = Kb + ((size_t)(b * 4 + h) * 2304 + ki) * 96 + 4 * kq;
; #pragma unroll
;                         for (int nt = 0; nt < 6; ++nt) {
;                             const f32x4 w = *(const f32x4*)(qkk + 16 * nt + 4 * kq);
;                             float v[4];
; #pragma unroll
;                             for (int r = 0; r < 4; ++r) v[r] = (nt < 4 ? acc[nt < 4 ? nt : 0][tt][r] : kr[nt < 4 ? 0 : nt - 4][r]) * fac * w[r];
.LBB0_2327:
	s_add_i32 s59, s60, 16
	v_or_b32_e32 v18, s59, v158
	v_cmp_gt_u32_e64 s[10:11], s43, v18
	s_add_i32 s58, s60, 32
	v_or_b32_e32 v197, s60, v158
	v_cndmask_b32_e64 v198, v176, v18, s[10:11]
	v_or_b32_e32 v18, s58, v158
	v_cmp_gt_u32_e64 s[8:9], s43, v18
	v_add_u32_e32 v191, s57, v197
	v_add_u32_e32 v187, s57, v198
	v_cndmask_b32_e64 v199, v176, v18, s[8:9]
	v_add_u32_e32 v183, s57, v199
	v_add_u32_e32 v18, 0xffffc000, v191
	v_and_b32_e32 v19, 63, v191
	v_add_u32_e32 v20, 0xffffc000, v187
	v_and_b32_e32 v21, 63, v187
	v_add_u32_e32 v22, 0xffffc000, v183
	v_and_b32_e32 v23, 63, v183
	v_mov_b32_e32 v179, v196
	v_mov_b32_e32 v180, v195
	v_mov_b32_e32 v181, v194
	s_and_b64 vcc, exec, s[22:23]
	v_cmp_gt_i32_e64 s[12:13], s50, v191
	v_ashrrev_i32_e32 v192, 11, v191
	v_cmp_gt_i32_e64 s[14:15], s50, v187
	v_ashrrev_i32_e32 v188, 11, v187
	v_cmp_gt_i32_e64 s[16:17], s50, v183
	v_ashrrev_i32_e32 v184, 11, v183
	v_lshrrev_b32_e32 v193, 8, v18
	v_cvt_f32_ubyte0_e32 v190, v19
	v_lshrrev_b32_e32 v189, 8, v20
	v_cvt_f32_ubyte0_e32 v186, v21
	v_lshrrev_b32_e32 v185, 8, v22
	v_cvt_f32_ubyte0_e32 v182, v23
	s_mov_b64 s[18:19], -1
	s_cbranch_vccz .LBB0_2407
	global_load_dwordx4 v[2:5], v[108:109], off offset:384
	global_load_dwordx4 v[6:9], v[108:109], off offset:448
	global_load_dwordx4 v[10:13], v[108:109], off offset:512
	global_load_dwordx4 v[14:17], v[108:109], off offset:576
	global_load_dwordx4 v[126:129], v[108:109], off offset:640
	global_load_dwordx4 v[130:133], v[108:109], off offset:704
	v_cndmask_b32_e64 v19, v177, v178, s[12:13]
	v_and_b32_e32 v22, v19, v191
	v_cndmask_b32_e64 v18, v193, v192, s[12:13]
	v_add_u32_e32 v19, 0x100, v22
	v_cndmask_b32_e64 v100, v22, v19, s[12:13]
	v_lshl_add_u32 v18, v18, 2, s42
	v_mad_i64_i32 v[18:19], s[18:19], v18, s51, v[100:101]
	v_lshlrev_b64 v[20:21], 7, v[18:19]
	v_mad_u64_u32 v[140:141], s[18:19], v18, s52, v[106:107]
	v_lshrrev_b32_e32 v18, 6, v22
	v_cvt_f32_ubyte0_e32 v18, v18
	v_mad_i32_i24 v141, v19, s52, v141
	v_mul_f32_e32 v19, v167, v18
	v_mul_f32_e32 v19, 0.15915494, v19
	v_cos_f32_e32 v203, v19
	v_sin_f32_e32 v204, v19
	v_mul_f32_e32 v19, v166, v18
	v_mul_f32_e32 v19, 0.15915494, v19
	v_cos_f32_e32 v205, v19
	v_sin_f32_e32 v206, v19
	v_mul_f32_e32 v19, v165, v18
	v_mul_f32_e32 v18, v164, v18
	v_mul_f32_e32 v18, 0.15915494, v18
	v_cos_f32_e32 v209, v18
	v_sin_f32_e32 v210, v18
	v_mul_f32_e32 v18, v164, v190
	v_mul_f32_e32 v18, 0.15915494, v18
	v_cos_f32_e32 v211, v18
	v_sin_f32_e32 v212, v18
	v_mul_f32_e32 v18, v165, v190
	v_mul_f32_e32 v18, 0.15915494, v18
	v_cos_f32_e32 v213, v18
	v_sin_f32_e32 v214, v18
	v_mul_f32_e32 v18, v166, v190
	v_mul_f32_e32 v19, 0.15915494, v19
	v_mul_f32_e32 v18, 0.15915494, v18
	v_cos_f32_e32 v207, v19
	v_sin_f32_e32 v208, v19
	v_cos_f32_e32 v215, v18
	v_sin_f32_e32 v216, v18
	v_mul_f32_e32 v18, v167, v190
	v_cndmask_b32_e64 v19, v177, v178, s[14:15]
	v_mul_f32_e32 v18, 0.15915494, v18
	v_and_b32_e32 v22, v19, v187
	v_cos_f32_e32 v217, v18
	v_sin_f32_e32 v218, v18
	v_cndmask_b32_e64 v18, v189, v188, s[14:15]
	v_add_u32_e32 v19, 0x100, v22
	v_cndmask_b32_e64 v100, v22, v19, s[14:15]
	v_lshl_add_u32 v18, v18, 2, s42
	v_mad_i64_i32 v[18:19], s[18:19], v18, s51, v[100:101]
	v_lshl_add_u64 v[138:139], v[104:105], 0, v[20:21]
	v_lshlrev_b64 v[20:21], 7, v[18:19]
	v_mad_u64_u32 v[144:145], s[18:19], v18, s52, v[106:107]
	v_lshrrev_b32_e32 v18, 6, v22
	v_cvt_f32_ubyte0_e32 v18, v18
	v_mad_i32_i24 v145, v19, s52, v145
	v_mul_f32_e32 v19, v167, v18
	v_mul_f32_e32 v19, 0.15915494, v19
	v_cos_f32_e32 v219, v19
	v_sin_f32_e32 v220, v19
	v_mul_f32_e32 v19, v166, v18
	v_mul_f32_e32 v19, 0.15915494, v19
	v_cos_f32_e32 v221, v19
	v_sin_f32_e32 v222, v19
	v_mul_f32_e32 v19, v165, v18
	v_mul_f32_e32 v18, v164, v18
	v_mul_f32_e32 v18, 0.15915494, v18
	v_cos_f32_e32 v225, v18
	v_sin_f32_e32 v226, v18
	v_mul_f32_e32 v18, v164, v186
	v_mul_f32_e32 v18, 0.15915494, v18
	v_cos_f32_e32 v227, v18
	v_sin_f32_e32 v228, v18
	v_mul_f32_e32 v18, v165, v186
	v_mul_f32_e32 v18, 0.15915494, v18
	v_cos_f32_e32 v229, v18
	v_sin_f32_e32 v230, v18
	v_mul_f32_e32 v18, v166, v186
	v_mul_f32_e32 v19, 0.15915494, v19
	v_mul_f32_e32 v18, 0.15915494, v18
	v_cos_f32_e32 v223, v19
	v_sin_f32_e32 v224, v19
	v_cos_f32_e32 v231, v18
	v_sin_f32_e32 v232, v18
	v_mul_f32_e32 v18, v167, v186
	v_cndmask_b32_e64 v19, v177, v178, s[16:17]
	v_mul_f32_e32 v18, 0.15915494, v18
	v_and_b32_e32 v22, v19, v183
	v_cos_f32_e32 v233, v18
	v_sin_f32_e32 v234, v18
	v_cndmask_b32_e64 v18, v185, v184, s[16:17]
	v_add_u32_e32 v19, 0x100, v22
	v_cndmask_b32_e64 v100, v22, v19, s[16:17]
	v_lshl_add_u32 v18, v18, 2, s42
	v_mad_i64_i32 v[18:19], s[18:19], v18, s51, v[100:101]
	v_lshl_add_u64 v[142:143], v[104:105], 0, v[20:21]
	v_lshlrev_b64 v[20:21], 7, v[18:19]
	v_mad_u64_u32 v[148:149], s[18:19], v18, s52, v[106:107]
	v_lshrrev_b32_e32 v18, 6, v22
	v_cvt_f32_ubyte0_e32 v18, v18
	v_mad_i32_i24 v149, v19, s52, v149
	v_mul_f32_e32 v19, v167, v18
	v_mul_f32_e32 v19, 0.15915494, v19
	v_cos_f32_e32 v100, v19
	v_sin_f32_e32 v235, v19
	v_mul_f32_e32 v19, v166, v18
	v_mul_f32_e32 v19, 0.15915494, v19
	v_cos_f32_e32 v236, v19
	v_sin_f32_e32 v237, v19
	v_mul_f32_e32 v19, v165, v18
	v_mul_f32_e32 v18, v164, v18
	v_mul_f32_e32 v18, 0.15915494, v18
	v_cos_f32_e32 v240, v18
	v_sin_f32_e32 v241, v18
	v_mul_f32_e32 v18, v164, v182
	v_mul_f32_e32 v18, 0.15915494, v18
	v_cos_f32_e32 v242, v18
	v_sin_f32_e32 v243, v18
	v_mul_f32_e32 v18, v165, v182
	v_mul_f32_e32 v18, 0.15915494, v18
	v_cos_f32_e32 v244, v18
	v_sin_f32_e32 v245, v18
	v_mul_f32_e32 v18, v166, v182
	v_mul_f32_e32 v18, 0.15915494, v18
	v_cos_f32_e32 v246, v18
	v_sin_f32_e32 v247, v18
	v_mul_f32_e32 v18, v167, v182
	v_mul_f32_e32 v19, 0.15915494, v19
	v_mul_f32_e32 v18, 0.15915494, v18
	v_mul_u32_u24_e32 v200, 0x150, v197
	v_mul_u32_u24_e32 v201, 0x150, v198
	v_mul_u32_u24_e32 v202, 0x150, v199
	v_lshl_add_u64 v[146:147], v[104:105], 0, v[20:21]
	v_cos_f32_e32 v238, v19
	v_sin_f32_e32 v239, v19
	v_cos_f32_e32 v248, v18
	v_sin_f32_e32 v249, v18
	s_mov_b32 s61, 0
	s_mov_b64 s[36:37], -1
	v_mov_b32_e32 v250, 0
	v_mov_b32_e32 v251, 0
	v_mov_b32_e32 v252, 0
	v_mov_b32_e32 v196, v179
	v_mov_b32_e32 v195, v180
	v_mov_b32_e32 v194, v181
	s_branch .LBB0_2331

; __device__ __forceinline__ void ph_prep(bf16_t* Z, const bf16_t* WUQ, const bf16_t* WUKV, const bf16_t* D64, const float* qkq, const float* qkk,
;                                         bf16_t* Q, bf16_t* Kb, bf16_t* Vb, bf16_t* F1lat, bf16_t* F1ctx, unsigned char* lds_) { PH_IDS;
;     ...
;                     if (pass == 0) {
.LBB0_2351:
	s_andn2_b64 vcc, exec, s[18:19]
	s_cbranch_vccnz .LBB0_2353
; #define LAS __attribute__((address_space(3)))
; __device__ __forceinline__ void ph_prep(bf16_t* Z, const bf16_t* WUQ, const bf16_t* WUKV, const bf16_t* D64, const float* qkq, const float* qkk,
;                                         bf16_t* Q, bf16_t* Kb, bf16_t* Vb, bf16_t* F1lat, bf16_t* F1ctx, unsigned char* lds_) { PH_IDS;
;     ...
;                         float s1 = ssq[tt]; s1 += __shfl_xor(s1, 16); s1 += __shfl_xor(s1, 32);
;                         rstd[tt] = rsqrtf(s1 * (1.f / 128) + EPS);
;                         float kr[2][4];
; #pragma unroll
;                         for (int e = 0; e < 2; ++e) { const fa::u32x2 w = *(const LAS fa::u32x2*)(sm + O_KV + rl[tt] * P_KV + (128 + 16 * e + 4 * kq) * 2);
;                             kr[e][0] = __uint_as_float(w.x << 16); kr[e][1] = __uint_as_float(w.x & 0xffff0000u); kr[e][2] = __uint_as_float(w.y << 16); kr[e][3] = __uint_as_float(w.y & 0xffff0000u); }
;                         float ss = 0.f;
; #pragma unroll
;                         for (int nt = 0; nt < 4; ++nt)
; #pragma unroll
;                             for (int r = 0; r < 4; ++r) { acc[nt][tt][r] *= rstd[tt]; ss += acc[nt][tt][r] * acc[nt][tt][r]; }
; #pragma unroll
;                         for (int e = 0; e < 2; ++e)
; #pragma unroll
;                             for (int r = 0; r < 4; ++r) ss += kr[e][r] * kr[e][r];
;                         ss += __shfl_xor(ss, 16); ss += __shfl_xor(ss, 32);
;                         const float fac = rsqrtf(ss * (1.f / 96) + EPS);
;                         bf16_t* ko = Kb + ((size_t)(b * 4 + h) * 2304 + ki) * 96 + 4 * kq;
; #pragma unroll
;                         for (int nt = 0; nt < 6; ++nt) {
;                             const f32x4 w = *(const f32x4*)(qkk + 16 * nt + 4 * kq);
;                             float v[4];
; #pragma unroll
;                             for (int r = 0; r < 4; ++r) v[r] = (nt < 4 ? acc[nt < 4 ? nt : 0][tt][r] : kr[nt < 4 ? 0 : nt - 4][r]) * fac * w[r];
;                             if (nt >= 4) rope16(v, kq, nt == 4 ? (float)(t >> 6) : (float)(t & 63), lat);
;                             fa::u32x2 o; o.x = fa::pk2(v[0], v[1]); o.y = fa::pk2(v[2], v[3]);
;                             if (valid[tt]) *(fa::u32x2*)(ko + 16 * nt) = o;
;                         }
	v_and_b32_e32 v67, 64, v1
	v_xor_b32_e32 v66, 16, v1
	v_add_u32_e32 v67, 64, v67
	v_cmp_lt_i32_e32 vcc, v66, v67
	v_xor_b32_e32 v68, 32, v1
	v_add_u32_e32 v70, v163, v200
	v_cndmask_b32_e32 v66, v1, v66, vcc
	v_lshlrev_b32_e32 v74, 2, v66
	ds_bpermute_b32 v66, v74, v252
	v_cmp_lt_i32_e32 vcc, v68, v67
	ds_read2_b64 v[70:73], v70 offset0:32 offset1:36
	s_waitcnt lgkmcnt(1)
	v_add_f32_e32 v66, v252, v66
	v_cndmask_b32_e32 v67, v1, v68, vcc
	v_lshlrev_b32_e32 v75, 2, v67
	ds_bpermute_b32 v67, v75, v66
	s_waitcnt lgkmcnt(0)
	v_add_f32_e32 v66, v66, v67
	v_fmamk_f32 v66, v66, 0x3c000000, v175
	v_mul_f32_e32 v67, 0x4b800000, v66
	v_cmp_gt_f32_e32 vcc, s53, v66
	s_nop 1
	v_cndmask_b32_e32 v66, v66, v67, vcc
	v_rsq_f32_e32 v76, v66
	v_mov_b64_e32 v[66:67], v[2:3]
	v_mov_b64_e32 v[68:69], v[4:5]
	v_mul_f32_e32 v77, 0x45800000, v76
	v_cndmask_b32_e32 v194, v76, v77, vcc
	v_mul_f32_e32 v63, v63, v194
	v_mul_f32_e32 v62, v62, v194
	v_mul_f32_e32 v76, v63, v63
	v_fmac_f32_e32 v76, v62, v62
	v_mul_f32_e32 v64, v64, v194
	v_fmac_f32_e32 v76, v64, v64
	v_mul_f32_e32 v65, v65, v194
	v_fmac_f32_e32 v76, v65, v65
	v_mul_f32_e32 v77, v58, v194
	v_fmac_f32_e32 v76, v77, v77
	v_mul_f32_e32 v78, v59, v194
	v_fmac_f32_e32 v76, v78, v78
	v_mul_f32_e32 v79, v60, v194
	v_fmac_f32_e32 v76, v79, v79
	v_mul_f32_e32 v80, v61, v194
	v_fmac_f32_e32 v76, v80, v80
	v_mul_f32_e32 v81, v54, v194
	v_fmac_f32_e32 v76, v81, v81
	v_mul_f32_e32 v82, v55, v194
	v_fmac_f32_e32 v76, v82, v82
	v_mul_f32_e32 v83, v56, v194
	v_fmac_f32_e32 v76, v83, v83
	v_mul_f32_e32 v84, v57, v194
	v_fmac_f32_e32 v76, v84, v84
	v_mul_f32_e32 v85, v50, v194
	v_fmac_f32_e32 v76, v85, v85
	v_mul_f32_e32 v86, v51, v194
	v_fmac_f32_e32 v76, v86, v86
	v_mul_f32_e32 v87, v52, v194
	v_fmac_f32_e32 v76, v87, v87
	v_mul_f32_e32 v88, v53, v194
	v_and_b32_e32 v54, 0xffff0000, v70
	v_lshlrev_b32_e32 v55, 16, v70
	v_fmac_f32_e32 v76, v88, v88
	v_pk_mul_f32 v[50:51], v[54:55], v[54:55]
	v_and_b32_e32 v56, 0xffff0000, v71
	v_add_f32_e32 v51, v51, v76
	v_lshlrev_b32_e32 v57, 16, v71
	v_add_f32_e32 v52, v50, v51
	v_pk_mul_f32 v[50:51], v[56:57], v[56:57]
	v_and_b32_e32 v58, 0xffff0000, v72
	v_add_f32_e32 v51, v51, v52
	v_lshlrev_b32_e32 v59, 16, v72
	v_add_f32_e32 v52, v50, v51
	v_pk_mul_f32 v[50:51], v[58:59], v[58:59]
	v_and_b32_e32 v60, 0xffff0000, v73
	v_add_f32_e32 v51, v51, v52
	v_lshlrev_b32_e32 v61, 16, v73
	v_add_f32_e32 v52, v50, v51
	v_pk_mul_f32 v[50:51], v[60:61], v[60:61]
	s_nop 0
	v_add_f32_e32 v51, v51, v52
	v_add_f32_e32 v50, v50, v51
	ds_bpermute_b32 v51, v74, v50
	s_waitcnt lgkmcnt(0)
	v_add_f32_e32 v50, v50, v51
	ds_bpermute_b32 v51, v75, v50
	s_waitcnt lgkmcnt(0)
	v_add_f32_e32 v50, v50, v51
	v_fmamk_f32 v50, v50, 0x3c2aaaab, v175
	v_mul_f32_e32 v51, 0x4b800000, v50
	v_cmp_gt_f32_e32 vcc, s53, v50
	s_nop 1
	v_cndmask_b32_e32 v50, v50, v51, vcc
	v_rsq_f32_e32 v50, v50
	s_nop 0
	v_mul_f32_e32 v51, 0x45800000, v50
	v_cndmask_b32_e32 v70, v50, v51, vcc
	v_mul_f32_e32 v50, v62, v70
	v_mul_f32_e32 v51, v63, v70
	v_mul_f32_e32 v50, v66, v50
	v_mul_f32_e32 v51, v67, v51
	v_mul_f32_e32 v52, v64, v70
	v_mul_f32_e32 v53, v65, v70
	v_mul_f32_e32 v52, v68, v52
	v_mul_f32_e32 v53, v69, v53
	v_cvt_pk_bf16_f32 v50, v50, v51
	v_cvt_pk_bf16_f32 v51, v52, v53
	global_store_dwordx2 v[140:141], v[50:51], off
	v_mov_b64_e32 v[50:51], v[6:7]
	v_mov_b64_e32 v[52:53], v[8:9]
	v_mul_f32_e32 v62, v77, v70
	v_mul_f32_e32 v63, v78, v70
	v_mul_f32_e32 v64, v79, v70
	v_mul_f32_e32 v65, v80, v70
	v_mul_f32_e32 v55, v70, v55
	v_mul_f32_e32 v54, v70, v54
	v_mul_f32_e32 v57, v70, v57
	v_mul_f32_e32 v56, v70, v56
	v_mul_f32_e32 v50, v50, v62
	v_mul_f32_e32 v51, v51, v63
	v_mul_f32_e32 v52, v52, v64
	v_mul_f32_e32 v53, v53, v65
	v_cvt_pk_bf16_f32 v50, v50, v51
	v_cvt_pk_bf16_f32 v51, v52, v53
	global_store_dwordx2 v[140:141], v[50:51], off offset:32
	v_mov_b64_e32 v[50:51], v[10:11]
	v_mov_b64_e32 v[52:53], v[12:13]
	v_mul_f32_e32 v62, v81, v70
	v_mul_f32_e32 v63, v82, v70
	v_mul_f32_e32 v64, v83, v70
	v_mul_f32_e32 v65, v84, v70
	v_mul_f32_e32 v50, v50, v62
	v_mul_f32_e32 v51, v51, v63
	v_mul_f32_e32 v52, v52, v64
	v_mul_f32_e32 v53, v53, v65
	v_cvt_pk_bf16_f32 v50, v50, v51
	v_cvt_pk_bf16_f32 v51, v52, v53
	global_store_dwordx2 v[140:141], v[50:51], off offset:64
	v_mov_b64_e32 v[50:51], v[14:15]
	v_mov_b64_e32 v[52:53], v[16:17]
	v_mul_f32_e32 v62, v85, v70
	v_mul_f32_e32 v63, v86, v70
	v_mul_f32_e32 v64, v87, v70
	v_mul_f32_e32 v65, v88, v70
	v_mul_f32_e32 v50, v50, v62
	v_mul_f32_e32 v51, v51, v63
	v_mul_f32_e32 v52, v52, v64
	v_mul_f32_e32 v53, v53, v65
	v_cvt_pk_bf16_f32 v50, v50, v51
	v_cvt_pk_bf16_f32 v51, v52, v53
	global_store_dwordx2 v[140:141], v[50:51], off offset:96
	v_mov_b64_e32 v[50:51], v[126:127]
	v_mov_b64_e32 v[52:53], v[128:129]
	v_mul_f32_e32 v50, v50, v55
	v_mul_f32_e32 v51, v51, v54
	v_mul_f32_e32 v52, v52, v57
	v_mul_f32_e32 v53, v53, v56
	ds_bpermute_b32 v56, v75, v51
	ds_bpermute_b32 v57, v75, v50
	ds_bpermute_b32 v54, v75, v53
	ds_bpermute_b32 v55, v75, v52
	s_waitcnt lgkmcnt(3)
	v_mul_f32_e32 v56, v208, v56
	s_waitcnt lgkmcnt(2)
	v_mul_f32_e32 v57, v210, v57
	s_waitcnt lgkmcnt(1)
	v_mul_f32_e32 v54, v204, v54
	s_waitcnt lgkmcnt(0)
	v_mul_f32_e32 v55, v206, v55
	v_cndmask_b32_e64 v56, v56, -v56, s[4:5]
	v_cndmask_b32_e64 v57, v57, -v57, s[4:5]
	v_cndmask_b32_e64 v54, v54, -v54, s[4:5]
	v_cndmask_b32_e64 v55, v55, -v55, s[4:5]
	v_fmac_f32_e32 v56, v207, v51
	v_fmac_f32_e32 v57, v209, v50
	v_fmac_f32_e32 v54, v203, v53
	v_fmac_f32_e32 v55, v205, v52
	v_cndmask_b32_e64 v51, v51, v56, s[12:13]
	v_cndmask_b32_e64 v50, v50, v57, s[12:13]
	v_cndmask_b32_e64 v53, v53, v54, s[12:13]
	v_cndmask_b32_e64 v52, v52, v55, s[12:13]
	v_cvt_pk_bf16_f32 v50, v50, v51
	v_cvt_pk_bf16_f32 v51, v52, v53
	global_store_dwordx2 v[140:141], v[50:51], off offset:128
	v_mov_b64_e32 v[50:51], v[130:131]
	v_mov_b64_e32 v[52:53], v[132:133]
	v_mul_f32_e32 v54, v70, v59
	v_mul_f32_e32 v55, v70, v58
	v_mul_f32_e32 v56, v70, v61
	v_mul_f32_e32 v57, v70, v60
	v_mul_f32_e32 v50, v50, v54
	v_mul_f32_e32 v51, v51, v55
	v_mul_f32_e32 v52, v52, v56
	v_mul_f32_e32 v53, v53, v57
	ds_bpermute_b32 v54, v75, v50
	ds_bpermute_b32 v55, v75, v51
	ds_bpermute_b32 v56, v75, v52
	ds_bpermute_b32 v57, v75, v53
	s_waitcnt lgkmcnt(3)
	v_mul_f32_e32 v54, v212, v54
	s_waitcnt lgkmcnt(2)
	v_mul_f32_e32 v55, v214, v55
	s_waitcnt lgkmcnt(1)
	v_mul_f32_e32 v56, v216, v56
	s_waitcnt lgkmcnt(0)
	v_mul_f32_e32 v57, v218, v57
	v_cndmask_b32_e64 v54, v54, -v54, s[4:5]
	v_cndmask_b32_e64 v55, v55, -v55, s[4:5]
	v_cndmask_b32_e64 v56, v56, -v56, s[4:5]
	v_cndmask_b32_e64 v57, v57, -v57, s[4:5]
	v_fmac_f32_e32 v54, v211, v50
	v_fmac_f32_e32 v55, v213, v51
	v_fmac_f32_e32 v56, v215, v52
	v_fmac_f32_e32 v57, v217, v53
	v_cndmask_b32_e64 v50, v50, v54, s[12:13]
	v_cndmask_b32_e64 v51, v51, v55, s[12:13]
	v_cndmask_b32_e64 v52, v52, v56, s[12:13]
	v_cndmask_b32_e64 v53, v53, v57, s[12:13]
	v_cvt_pk_bf16_f32 v50, v50, v51
	v_cvt_pk_bf16_f32 v51, v52, v53
	global_store_dwordx2 v[140:141], v[50:51], off offset:160

; #define LAS __attribute__((address_space(3)))
; __device__ __forceinline__ void ph_prep(bf16_t* Z, const bf16_t* WUQ, const bf16_t* WUKV, const bf16_t* D64, const float* qkq, const float* qkk,
;                                         bf16_t* Q, bf16_t* Kb, bf16_t* Vb, bf16_t* F1lat, bf16_t* F1ctx, unsigned char* lds_) { PH_IDS;
;     ...
;                     const int row = rowc[tt]; const bool lat = row < RL; const int b = row_batch(row), t = lat ? (row & 2047) : ((row - RL) & 255), ki = lat ? 256 + t : t;
;                     if (pass == 0) {
;                         float s1 = ssq[tt]; s1 += __shfl_xor(s1, 16); s1 += __shfl_xor(s1, 32);
;                         rstd[tt] = rsqrtf(s1 * (1.f / 128) + EPS);
;                         float kr[2][4];
; #pragma unroll
;                         for (int e = 0; e < 2; ++e) { const fa::u32x2 w = *(const LAS fa::u32x2*)(sm + O_KV + rl[tt] * P_KV + (128 + 16 * e + 4 * kq) * 2);
;                             kr[e][0] = __uint_as_float(w.x << 16); kr[e][1] = __uint_as_float(w.x & 0xffff0000u); kr[e][2] = __uint_as_float(w.y << 16); kr[e][3] = __uint_as_float(w.y & 0xffff0000u); }
;                         float ss = 0.f;
; #pragma unroll
;                         for (int nt = 0; nt < 4; ++nt)
; #pragma unroll
;                             for (int r = 0; r < 4; ++r) { acc[nt][tt][r] *= rstd[tt]; ss += acc[nt][tt][r] * acc[nt][tt][r]; }
; #pragma unroll
;                         for (int e = 0; e < 2; ++e)
; #pragma unroll
;                             for (int r = 0; r < 4; ++r) ss += kr[e][r] * kr[e][r];
;                         ss += __shfl_xor(ss, 16); ss += __shfl_xor(ss, 32);
;                         const float fac = rsqrtf(ss * (1.f / 96) + EPS);
;                         bf16_t* ko = Kb + ((size_t)(b * 4 + h) * 2304 + ki) * 96 + 4 * kq;
; #pragma unroll
;                         for (int nt = 0; nt < 6; ++nt) {
;                             const f32x4 w = *(const f32x4*)(qkk + 16 * nt + 4 * kq);
;                             float v[4];
; #pragma unroll
;                             for (int r = 0; r < 4; ++r) v[r] = (nt < 4 ? acc[nt < 4 ? nt : 0][tt][r] : kr[nt < 4 ? 0 : nt - 4][r]) * fac * w[r];
;                             if (nt >= 4) rope16(v, kq, nt == 4 ? (float)(t >> 6) : (float)(t & 63), lat);
;                             fa::u32x2 o; o.x = fa::pk2(v[0], v[1]); o.y = fa::pk2(v[2], v[3]);
.LBB0_2363:
	s_and_b64 vcc, exec, s[36:37]
	s_cbranch_vccz .LBB0_2384
	v_mov_b64_e32 v[58:59], v[2:3]
	v_mov_b64_e32 v[60:61], v[4:5]
	v_and_b32_e32 v51, 64, v1
	v_xor_b32_e32 v50, 16, v1
	v_add_u32_e32 v51, 64, v51
	v_cmp_lt_i32_e32 vcc, v50, v51
	v_xor_b32_e32 v52, 32, v1
	s_nop 0
	v_cndmask_b32_e32 v50, v1, v50, vcc
	v_lshlrev_b32_e32 v66, 2, v50
	ds_bpermute_b32 v50, v66, v251
	v_cmp_lt_i32_e32 vcc, v52, v51
	s_waitcnt lgkmcnt(0)
	v_add_f32_e32 v53, v251, v50
	v_cndmask_b32_e32 v50, v1, v52, vcc
	v_lshlrev_b32_e32 v50, 2, v50
	ds_bpermute_b32 v51, v50, v53
	s_waitcnt lgkmcnt(0)
	v_add_f32_e32 v51, v53, v51
	v_fmamk_f32 v51, v51, 0x3c000000, v175
	v_mul_f32_e32 v52, 0x4b800000, v51
	v_cmp_gt_f32_e32 vcc, s53, v51
	s_nop 1
	v_cndmask_b32_e32 v51, v51, v52, vcc
	v_rsq_f32_e32 v51, v51
	v_add_u32_e32 v52, v163, v201
	ds_read2_b64 v[62:65], v52 offset0:32 offset1:36
	v_mul_f32_e32 v52, 0x45800000, v51
	v_cndmask_b32_e32 v195, v51, v52, vcc
	v_mul_f32_e32 v68, v47, v195
	v_mul_f32_e32 v67, v46, v195
	v_mul_f32_e32 v69, v68, v68
	v_fmac_f32_e32 v69, v67, v67
	v_mul_f32_e32 v70, v48, v195
	v_fmac_f32_e32 v69, v70, v70
	v_mul_f32_e32 v71, v49, v195
	v_fmac_f32_e32 v69, v71, v71
	v_mul_f32_e32 v54, v42, v195
	v_fmac_f32_e32 v69, v54, v54
	v_mul_f32_e32 v55, v43, v195
	v_fmac_f32_e32 v69, v55, v55
	v_mul_f32_e32 v56, v44, v195
	v_fmac_f32_e32 v69, v56, v56
	v_mul_f32_e32 v57, v45, v195
	v_fmac_f32_e32 v69, v57, v57
	v_mul_f32_e32 v49, v38, v195
	v_fmac_f32_e32 v69, v49, v49
	v_mul_f32_e32 v51, v39, v195
	v_fmac_f32_e32 v69, v51, v51
	v_mul_f32_e32 v52, v40, v195
	v_fmac_f32_e32 v69, v52, v52
	v_mul_f32_e32 v53, v41, v195
	v_fmac_f32_e32 v69, v53, v53
	v_mul_f32_e32 v45, v34, v195
	v_fmac_f32_e32 v69, v45, v45
	v_mul_f32_e32 v46, v35, v195
	v_fmac_f32_e32 v69, v46, v46
	v_mul_f32_e32 v47, v36, v195
	v_fmac_f32_e32 v69, v47, v47
	v_mul_f32_e32 v48, v37, v195
	s_waitcnt lgkmcnt(0)
	v_and_b32_e32 v38, 0xffff0000, v62
	v_lshlrev_b32_e32 v39, 16, v62
	v_fmac_f32_e32 v69, v48, v48
	v_pk_mul_f32 v[34:35], v[38:39], v[38:39]
	v_and_b32_e32 v40, 0xffff0000, v63
	v_add_f32_e32 v35, v35, v69
	v_lshlrev_b32_e32 v41, 16, v63
	v_add_f32_e32 v36, v34, v35
	v_pk_mul_f32 v[34:35], v[40:41], v[40:41]
	s_nop 0
	v_add_f32_e32 v35, v35, v36
	v_add_f32_e32 v42, v34, v35
	v_and_b32_e32 v34, 0xffff0000, v64
	v_lshlrev_b32_e32 v35, 16, v64
	v_pk_mul_f32 v[36:37], v[34:35], v[34:35]
	s_nop 0
	v_add_f32_e32 v37, v37, v42
	v_add_f32_e32 v44, v36, v37
	v_and_b32_e32 v36, 0xffff0000, v65
	v_lshlrev_b32_e32 v37, 16, v65
	v_pk_mul_f32 v[42:43], v[36:37], v[36:37]
	s_nop 0
	v_add_f32_e32 v43, v43, v44
	v_add_f32_e32 v42, v42, v43
	ds_bpermute_b32 v43, v66, v42
	s_waitcnt lgkmcnt(0)
	v_add_f32_e32 v42, v42, v43
	ds_bpermute_b32 v43, v50, v42
	s_waitcnt lgkmcnt(0)
	v_add_f32_e32 v42, v42, v43
	v_fmamk_f32 v42, v42, 0x3c2aaaab, v175
	v_mul_f32_e32 v43, 0x4b800000, v42
	v_cmp_gt_f32_e32 vcc, s53, v42
	s_nop 1
	v_cndmask_b32_e32 v42, v42, v43, vcc
	v_rsq_f32_e32 v42, v42
	s_nop 0
	v_mul_f32_e32 v43, 0x45800000, v42
	v_cndmask_b32_e32 v44, v42, v43, vcc
	v_mul_f32_e32 v42, v67, v44
	v_mul_f32_e32 v43, v68, v44
	v_mul_f32_e32 v42, v58, v42
	v_mul_f32_e32 v43, v59, v43
	v_mul_f32_e32 v58, v70, v44
	v_mul_f32_e32 v59, v71, v44
	v_mul_f32_e32 v58, v60, v58
	v_mul_f32_e32 v59, v61, v59
	v_cvt_pk_bf16_f32 v42, v42, v43
	v_cvt_pk_bf16_f32 v43, v58, v59
	s_and_saveexec_b64 s[36:37], s[10:11]
	s_cbranch_execz .LBB0_2366
	global_store_dwordx2 v[144:145], v[42:43], off

; __device__ __forceinline__ unsigned pk2(float lo, float hi) { unsigned r; asm volatile("v_cvt_pk_bf16_f32 %0, %1, %2" : "=v"(r) : "v"(lo), "v"(hi)); return r; }
; __device__ __forceinline__ void ph_prep(bf16_t* Z, const bf16_t* WUQ, const bf16_t* WUKV, const bf16_t* D64, const float* qkq, const float* qkk,
;                                         bf16_t* Q, bf16_t* Kb, bf16_t* Vb, bf16_t* F1lat, bf16_t* F1ctx, unsigned char* lds_) { PH_IDS;
;     ...
; #pragma unroll
;                         for (int nt = 0; nt < 6; ++nt) {
;                             const f32x4 w = *(const f32x4*)(qkk + 16 * nt + 4 * kq);
;                             float v[4];
; #pragma unroll
;                             for (int r = 0; r < 4; ++r) v[r] = (nt < 4 ? acc[nt < 4 ? nt : 0][tt][r] : kr[nt < 4 ? 0 : nt - 4][r]) * fac * w[r];
;                             if (nt >= 4) rope16(v, kq, nt == 4 ? (float)(t >> 6) : (float)(t & 63), lat);
;                             fa::u32x2 o; o.x = fa::pk2(v[0], v[1]); o.y = fa::pk2(v[2], v[3]);
;                             if (valid[tt]) *(fa::u32x2*)(ko + 16 * nt) = o;
;                         }
.LBB0_2372:
	s_or_b64 exec, exec, s[36:37]
	v_mov_b64_e32 v[46:47], v[126:127]
	v_mov_b64_e32 v[48:49], v[128:129]
	v_mul_f32_e32 v39, v44, v39
	v_mul_f32_e32 v38, v44, v38
	v_mul_f32_e32 v41, v44, v41
	v_mul_f32_e32 v40, v44, v40
	v_mul_f32_e32 v39, v39, v46
	v_mul_f32_e32 v38, v38, v47
	v_mul_f32_e32 v41, v41, v48
	v_mul_f32_e32 v40, v40, v49
	ds_bpermute_b32 v45, v50, v38
	ds_bpermute_b32 v46, v50, v39
	ds_bpermute_b32 v42, v50, v40
	ds_bpermute_b32 v43, v50, v41
	s_waitcnt lgkmcnt(3)
	v_mul_f32_e32 v45, v224, v45
	s_waitcnt lgkmcnt(2)
	v_mul_f32_e32 v46, v226, v46
	s_waitcnt lgkmcnt(1)
	v_mul_f32_e32 v42, v220, v42
	s_waitcnt lgkmcnt(0)
	v_mul_f32_e32 v43, v222, v43
	v_cndmask_b32_e64 v45, v45, -v45, s[4:5]
	v_cndmask_b32_e64 v46, v46, -v46, s[4:5]
	v_cndmask_b32_e64 v42, v42, -v42, s[4:5]
	v_cndmask_b32_e64 v43, v43, -v43, s[4:5]
	v_fmac_f32_e32 v45, v223, v38
	v_fmac_f32_e32 v46, v225, v39
	v_fmac_f32_e32 v42, v219, v40
	v_fmac_f32_e32 v43, v221, v41
	v_cndmask_b32_e64 v38, v38, v45, s[14:15]
	v_cndmask_b32_e64 v39, v39, v46, s[14:15]
	v_cndmask_b32_e64 v40, v40, v42, s[14:15]
	v_cndmask_b32_e64 v41, v41, v43, s[14:15]
	v_cvt_pk_bf16_f32 v38, v39, v38
	v_cvt_pk_bf16_f32 v39, v41, v40
	s_and_saveexec_b64 s[36:37], s[10:11]
	s_cbranch_execz .LBB0_2374
	global_store_dwordx2 v[144:145], v[38:39], off offset:128
.LBB0_2374:
	s_or_b64 exec, exec, s[36:37]
	v_mov_b64_e32 v[38:39], v[130:131]
	v_mov_b64_e32 v[40:41], v[132:133]
	v_mul_f32_e32 v35, v44, v35
	v_mul_f32_e32 v34, v44, v34
	v_mul_f32_e32 v37, v44, v37
	v_mul_f32_e32 v36, v44, v36
	v_mul_f32_e32 v35, v35, v38
	v_mul_f32_e32 v34, v34, v39
	v_mul_f32_e32 v37, v37, v40
	v_mul_f32_e32 v36, v36, v41
	ds_bpermute_b32 v38, v50, v35
	ds_bpermute_b32 v39, v50, v34
	ds_bpermute_b32 v40, v50, v37
	ds_bpermute_b32 v41, v50, v36
	s_waitcnt lgkmcnt(3)
	v_mul_f32_e32 v38, v228, v38
	s_waitcnt lgkmcnt(2)
	v_mul_f32_e32 v39, v230, v39
	s_waitcnt lgkmcnt(1)
	v_mul_f32_e32 v40, v232, v40
	s_waitcnt lgkmcnt(0)
	v_mul_f32_e32 v41, v234, v41
	v_cndmask_b32_e64 v38, v38, -v38, s[4:5]
	v_cndmask_b32_e64 v39, v39, -v39, s[4:5]
	v_cndmask_b32_e64 v40, v40, -v40, s[4:5]
	v_cndmask_b32_e64 v41, v41, -v41, s[4:5]
	v_fmac_f32_e32 v38, v227, v35
	v_fmac_f32_e32 v39, v229, v34
	v_fmac_f32_e32 v40, v231, v37
	v_fmac_f32_e32 v41, v233, v36
	v_cndmask_b32_e64 v35, v35, v38, s[14:15]
	v_cndmask_b32_e64 v34, v34, v39, s[14:15]
	v_cndmask_b32_e64 v37, v37, v40, s[14:15]
	v_cndmask_b32_e64 v36, v36, v41, s[14:15]
	v_cvt_pk_bf16_f32 v34, v35, v34
	v_cvt_pk_bf16_f32 v35, v37, v36
	s_and_saveexec_b64 s[36:37], s[10:11]
	s_cbranch_execz .LBB0_2376
	global_store_dwordx2 v[144:145], v[34:35], off offset:160

; #define LAS __attribute__((address_space(3)))
; __device__ __forceinline__ void ph_prep(bf16_t* Z, const bf16_t* WUQ, const bf16_t* WUKV, const bf16_t* D64, const float* qkq, const float* qkk,
;                                         bf16_t* Q, bf16_t* Kb, bf16_t* Vb, bf16_t* F1lat, bf16_t* F1ctx, unsigned char* lds_) { PH_IDS;
;     ...
;                     const int row = rowc[tt]; const bool lat = row < RL; const int b = row_batch(row), t = lat ? (row & 2047) : ((row - RL) & 255), ki = lat ? 256 + t : t;
;                     if (pass == 0) {
;                         float s1 = ssq[tt]; s1 += __shfl_xor(s1, 16); s1 += __shfl_xor(s1, 32);
;                         rstd[tt] = rsqrtf(s1 * (1.f / 128) + EPS);
;                         float kr[2][4];
; #pragma unroll
;                         for (int e = 0; e < 2; ++e) { const fa::u32x2 w = *(const LAS fa::u32x2*)(sm + O_KV + rl[tt] * P_KV + (128 + 16 * e + 4 * kq) * 2);
;                             kr[e][0] = __uint_as_float(w.x << 16); kr[e][1] = __uint_as_float(w.x & 0xffff0000u); kr[e][2] = __uint_as_float(w.y << 16); kr[e][3] = __uint_as_float(w.y & 0xffff0000u); }
;                         float ss = 0.f;
; #pragma unroll
;                         for (int nt = 0; nt < 4; ++nt)
; #pragma unroll
;                             for (int r = 0; r < 4; ++r) { acc[nt][tt][r] *= rstd[tt]; ss += acc[nt][tt][r] * acc[nt][tt][r]; }
; #pragma unroll
;                         for (int e = 0; e < 2; ++e)
; #pragma unroll
;                             for (int r = 0; r < 4; ++r) ss += kr[e][r] * kr[e][r];
;                         ss += __shfl_xor(ss, 16); ss += __shfl_xor(ss, 32);
;                         const float fac = rsqrtf(ss * (1.f / 96) + EPS);
;                         bf16_t* ko = Kb + ((size_t)(b * 4 + h) * 2304 + ki) * 96 + 4 * kq;
; #pragma unroll
;                         for (int nt = 0; nt < 6; ++nt) {
;                             const f32x4 w = *(const f32x4*)(qkk + 16 * nt + 4 * kq);
;                             float v[4];
; #pragma unroll
;                             for (int r = 0; r < 4; ++r) v[r] = (nt < 4 ? acc[nt < 4 ? nt : 0][tt][r] : kr[nt < 4 ? 0 : nt - 4][r]) * fac * w[r];
;                             if (nt >= 4) rope16(v, kq, nt == 4 ? (float)(t >> 6) : (float)(t & 63), lat);
;                             fa::u32x2 o; o.x = fa::pk2(v[0], v[1]); o.y = fa::pk2(v[2], v[3]);
.LBB0_2394:
	v_mov_b64_e32 v[42:43], v[2:3]
	v_mov_b64_e32 v[44:45], v[4:5]
	v_and_b32_e32 v35, 64, v1
	v_xor_b32_e32 v34, 16, v1
	v_add_u32_e32 v35, 64, v35
	v_cmp_lt_i32_e32 vcc, v34, v35
	v_xor_b32_e32 v36, 32, v1
	s_nop 0
	v_cndmask_b32_e32 v34, v1, v34, vcc
	v_lshlrev_b32_e32 v50, 2, v34
	ds_bpermute_b32 v34, v50, v250
	v_cmp_lt_i32_e32 vcc, v36, v35
	s_waitcnt lgkmcnt(0)
	v_add_f32_e32 v37, v250, v34
	v_cndmask_b32_e32 v34, v1, v36, vcc
	v_lshlrev_b32_e32 v34, 2, v34
	ds_bpermute_b32 v35, v34, v37
	s_waitcnt lgkmcnt(0)
	v_add_f32_e32 v35, v37, v35
	v_fmamk_f32 v35, v35, 0x3c000000, v175
	v_mul_f32_e32 v36, 0x4b800000, v35
	v_cmp_gt_f32_e32 vcc, s53, v35
	s_nop 1
	v_cndmask_b32_e32 v35, v35, v36, vcc
	v_rsq_f32_e32 v35, v35
	v_add_u32_e32 v36, v163, v202
	ds_read2_b64 v[46:49], v36 offset0:32 offset1:36
	v_mul_f32_e32 v36, 0x45800000, v35
	v_cndmask_b32_e32 v196, v35, v36, vcc
	v_mul_f32_e32 v52, v31, v196
	v_mul_f32_e32 v51, v30, v196
	v_mul_f32_e32 v53, v52, v52
	v_fmac_f32_e32 v53, v51, v51
	v_mul_f32_e32 v54, v32, v196
	v_fmac_f32_e32 v53, v54, v54
	v_mul_f32_e32 v55, v33, v196
	v_fmac_f32_e32 v53, v55, v55
	v_mul_f32_e32 v38, v26, v196
	v_fmac_f32_e32 v53, v38, v38
	v_mul_f32_e32 v39, v27, v196
	v_fmac_f32_e32 v53, v39, v39
	v_mul_f32_e32 v40, v28, v196
	v_fmac_f32_e32 v53, v40, v40
	v_mul_f32_e32 v41, v29, v196
	v_fmac_f32_e32 v53, v41, v41
	v_mul_f32_e32 v33, v22, v196
	v_fmac_f32_e32 v53, v33, v33
	v_mul_f32_e32 v35, v23, v196
	v_fmac_f32_e32 v53, v35, v35
	v_mul_f32_e32 v36, v24, v196
	v_fmac_f32_e32 v53, v36, v36
	v_mul_f32_e32 v37, v25, v196
	v_fmac_f32_e32 v53, v37, v37
	v_mul_f32_e32 v29, v18, v196
	v_fmac_f32_e32 v53, v29, v29
	v_mul_f32_e32 v30, v19, v196
	v_fmac_f32_e32 v53, v30, v30
	v_mul_f32_e32 v31, v20, v196
	v_fmac_f32_e32 v53, v31, v31
	v_mul_f32_e32 v32, v21, v196
	s_waitcnt lgkmcnt(0)
	v_and_b32_e32 v22, 0xffff0000, v46
	v_lshlrev_b32_e32 v23, 16, v46
	v_fmac_f32_e32 v53, v32, v32
	v_pk_mul_f32 v[18:19], v[22:23], v[22:23]
	v_and_b32_e32 v24, 0xffff0000, v47
	v_add_f32_e32 v19, v19, v53
	v_lshlrev_b32_e32 v25, 16, v47
	v_add_f32_e32 v20, v18, v19
	v_pk_mul_f32 v[18:19], v[24:25], v[24:25]
	s_nop 0
	v_add_f32_e32 v19, v19, v20
	v_add_f32_e32 v26, v18, v19
	v_and_b32_e32 v18, 0xffff0000, v48
	v_lshlrev_b32_e32 v19, 16, v48
	v_pk_mul_f32 v[20:21], v[18:19], v[18:19]
	s_nop 0
	v_add_f32_e32 v21, v21, v26
	v_add_f32_e32 v28, v20, v21
	v_and_b32_e32 v20, 0xffff0000, v49
	v_lshlrev_b32_e32 v21, 16, v49
	v_pk_mul_f32 v[26:27], v[20:21], v[20:21]
	s_nop 0
	v_add_f32_e32 v27, v27, v28
	v_add_f32_e32 v26, v26, v27
	ds_bpermute_b32 v27, v50, v26
	s_waitcnt lgkmcnt(0)
	v_add_f32_e32 v26, v26, v27
	ds_bpermute_b32 v27, v34, v26
	s_waitcnt lgkmcnt(0)
	v_add_f32_e32 v26, v26, v27
	v_fmamk_f32 v26, v26, 0x3c2aaaab, v175
	v_mul_f32_e32 v27, 0x4b800000, v26
	v_cmp_gt_f32_e32 vcc, s53, v26
	s_nop 1
	v_cndmask_b32_e32 v26, v26, v27, vcc
	v_rsq_f32_e32 v26, v26
	s_nop 0
	v_mul_f32_e32 v27, 0x45800000, v26
	v_cndmask_b32_e32 v28, v26, v27, vcc
	v_mul_f32_e32 v26, v51, v28
	v_mul_f32_e32 v27, v52, v28
	v_mul_f32_e32 v26, v42, v26
	v_mul_f32_e32 v27, v43, v27
	v_mul_f32_e32 v42, v54, v28
	v_mul_f32_e32 v43, v55, v28
	v_mul_f32_e32 v42, v44, v42
	v_mul_f32_e32 v43, v45, v43
	v_cvt_pk_bf16_f32 v26, v26, v27
	v_cvt_pk_bf16_f32 v27, v42, v43
	s_and_saveexec_b64 s[18:19], s[8:9]
	s_cbranch_execz .LBB0_2396
	global_store_dwordx2 v[148:149], v[26:27], off

; __device__ __forceinline__ unsigned pk2(float lo, float hi) { unsigned r; asm volatile("v_cvt_pk_bf16_f32 %0, %1, %2" : "=v"(r) : "v"(lo), "v"(hi)); return r; }
; __device__ __forceinline__ void ph_prep(bf16_t* Z, const bf16_t* WUQ, const bf16_t* WUKV, const bf16_t* D64, const float* qkq, const float* qkk,
;                                         bf16_t* Q, bf16_t* Kb, bf16_t* Vb, bf16_t* F1lat, bf16_t* F1ctx, unsigned char* lds_) { PH_IDS;
;     ...
; #pragma unroll
;                         for (int nt = 0; nt < 6; ++nt) {
;                             const f32x4 w = *(const f32x4*)(qkk + 16 * nt + 4 * kq);
;                             float v[4];
; #pragma unroll
;                             for (int r = 0; r < 4; ++r) v[r] = (nt < 4 ? acc[nt < 4 ? nt : 0][tt][r] : kr[nt < 4 ? 0 : nt - 4][r]) * fac * w[r];
;                             if (nt >= 4) rope16(v, kq, nt == 4 ? (float)(t >> 6) : (float)(t & 63), lat);
;                             fa::u32x2 o; o.x = fa::pk2(v[0], v[1]); o.y = fa::pk2(v[2], v[3]);
;                             if (valid[tt]) *(fa::u32x2*)(ko + 16 * nt) = o;
;                         }
.LBB0_2402:
	s_or_b64 exec, exec, s[18:19]
	v_mov_b64_e32 v[30:31], v[126:127]
	v_mov_b64_e32 v[32:33], v[128:129]
	v_mul_f32_e32 v23, v28, v23
	v_mul_f32_e32 v22, v28, v22
	v_mul_f32_e32 v25, v28, v25
	v_mul_f32_e32 v24, v28, v24
	v_mul_f32_e32 v23, v23, v30
	v_mul_f32_e32 v22, v22, v31
	v_mul_f32_e32 v25, v25, v32
	v_mul_f32_e32 v24, v24, v33
	ds_bpermute_b32 v29, v34, v22
	ds_bpermute_b32 v30, v34, v23
	ds_bpermute_b32 v26, v34, v24
	ds_bpermute_b32 v27, v34, v25
	s_waitcnt lgkmcnt(3)
	v_mul_f32_e32 v29, v239, v29
	s_waitcnt lgkmcnt(2)
	v_mul_f32_e32 v30, v241, v30
	s_waitcnt lgkmcnt(1)
	v_mul_f32_e32 v26, v235, v26
	s_waitcnt lgkmcnt(0)
	v_mul_f32_e32 v27, v237, v27
	v_cndmask_b32_e64 v29, v29, -v29, s[4:5]
	v_cndmask_b32_e64 v30, v30, -v30, s[4:5]
	v_cndmask_b32_e64 v26, v26, -v26, s[4:5]
	v_cndmask_b32_e64 v27, v27, -v27, s[4:5]
	v_fmac_f32_e32 v29, v238, v22
	v_fmac_f32_e32 v30, v240, v23
	v_fmac_f32_e32 v26, v100, v24
	v_fmac_f32_e32 v27, v236, v25
	v_cndmask_b32_e64 v22, v22, v29, s[16:17]
	v_cndmask_b32_e64 v23, v23, v30, s[16:17]
	v_cndmask_b32_e64 v24, v24, v26, s[16:17]
	v_cndmask_b32_e64 v25, v25, v27, s[16:17]
	v_cvt_pk_bf16_f32 v22, v23, v22
	v_cvt_pk_bf16_f32 v23, v25, v24
	s_and_saveexec_b64 s[18:19], s[8:9]
	s_cbranch_execz .LBB0_2404
	global_store_dwordx2 v[148:149], v[22:23], off offset:128
.LBB0_2404:
	s_or_b64 exec, exec, s[18:19]
	v_mov_b64_e32 v[22:23], v[130:131]
	v_mov_b64_e32 v[24:25], v[132:133]
	v_mul_f32_e32 v19, v28, v19
	v_mul_f32_e32 v18, v28, v18
	v_mul_f32_e32 v21, v28, v21
	v_mul_f32_e32 v20, v28, v20
	v_mul_f32_e32 v19, v19, v22
	v_mul_f32_e32 v18, v18, v23
	v_mul_f32_e32 v21, v21, v24
	v_mul_f32_e32 v20, v20, v25
	ds_bpermute_b32 v22, v34, v19
	ds_bpermute_b32 v23, v34, v18
	ds_bpermute_b32 v24, v34, v21
	ds_bpermute_b32 v25, v34, v20
	s_waitcnt lgkmcnt(3)
	v_mul_f32_e32 v22, v243, v22
	s_waitcnt lgkmcnt(2)
	v_mul_f32_e32 v23, v245, v23
	s_waitcnt lgkmcnt(1)
	v_mul_f32_e32 v24, v247, v24
	s_waitcnt lgkmcnt(0)
	v_mul_f32_e32 v25, v249, v25
	v_cndmask_b32_e64 v22, v22, -v22, s[4:5]
	v_cndmask_b32_e64 v23, v23, -v23, s[4:5]
	v_cndmask_b32_e64 v24, v24, -v24, s[4:5]
	v_cndmask_b32_e64 v25, v25, -v25, s[4:5]
	v_fmac_f32_e32 v22, v242, v19
	v_fmac_f32_e32 v23, v244, v18
	v_fmac_f32_e32 v24, v246, v21
	v_fmac_f32_e32 v25, v248, v20
	v_cndmask_b32_e64 v19, v19, v22, s[16:17]
	v_cndmask_b32_e64 v18, v18, v23, s[16:17]
	v_cndmask_b32_e64 v21, v21, v24, s[16:17]
	v_cndmask_b32_e64 v20, v20, v25, s[16:17]
	v_cvt_pk_bf16_f32 v18, v19, v18
	v_cvt_pk_bf16_f32 v19, v21, v20
	s_and_saveexec_b64 s[18:19], s[8:9]
	s_cbranch_execz .LBB0_2329
	global_store_dwordx2 v[148:149], v[18:19], off offset:160
	s_branch .LBB0_2329

; __device__ __forceinline__ float bf2f(bf16_t v) { return __uint_as_float(((unsigned)v) << 16); }
; #define LAS __attribute__((address_space(3)))
; __device__ __forceinline__ void ph_prep(bf16_t* Z, const bf16_t* WUQ, const bf16_t* WUKV, const bf16_t* D64, const float* qkq, const float* qkk,
;                                         bf16_t* Q, bf16_t* Kb, bf16_t* Vb, bf16_t* F1lat, bf16_t* F1ctx, unsigned char* lds_) { PH_IDS;
;     ...
;             f32x4 acc[6][3]; float ssq[3];
; #pragma unroll
;             for (int tt = 0; tt < 3; ++tt) { ssq[tt] = 0.f;
; #pragma unroll
;                 for (int nt = 0; nt < 6; ++nt) acc[nt][tt] = (f32x4){0.f, 0.f, 0.f, 0.f}; }
; #pragma unroll 4
;             for (int ks = 0; ks < 8; ++ks) {
;                 bf16x8 bq[3], aw[6];
; #pragma unroll
;                 for (int tt = 0; tt < 3; ++tt) { bq[tt] = *(const LAS bf16x8*)(sm + O_QC + rl[tt] * P_QC + (32 * ks + 8 * kq) * 2);
; #pragma unroll
;                     for (int e = 0; e < 8; ++e) { const float f = bf2f((bf16_t)bq[tt][e]); ssq[tt] += f * f; } }
; #pragma unroll
;                 for (int nt = 0; nt < 6; ++nt) aw[nt] = *(const bf16x8*)(WUQ + (size_t)(h * 96 + 16 * nt + c16) * 256 + 32 * ks + 8 * kq);
; #pragma unroll
;                 for (int nt = 0; nt < 6; ++nt)
; #pragma unroll
;                     for (int tt = 0; tt < 3; ++tt) acc[nt][tt] = __builtin_amdgcn_mfma_f32_16x16x32_bf16(aw[nt], bq[tt], acc[nt][tt], 0, 0, 0);
;             }
;     ...
;                     const f32x4 w = *(const f32x4*)(qkq + 16 * nt + 4 * kq);
.LBB0_2407:
	s_and_b64 vcc, exec, s[18:19]
	s_cbranch_vccz .LBB0_2435
	global_load_dwordx4 v[224:227], v[112:113], off offset:384
	global_load_dwordx4 v[228:231], v[112:113], off offset:448
	global_load_dwordx4 v[232:235], v[112:113], off offset:512
	global_load_dwordx4 v[236:239], v[112:113], off offset:576
	global_load_dwordx4 v[240:243], v[112:113], off offset:640
	global_load_dwordx4 v[244:247], v[112:113], off offset:704
	v_mov_b32_e32 v143, 0
	v_mul_u32_u24_e32 v141, 0x210, v197
	v_mul_u32_u24_e32 v142, 0x210, v198
	v_mul_u32_u24_e32 v140, 0x210, v199
	s_mov_b64 s[12:13], 0
	v_mov_b32_e32 v100, v174
	v_mov_b32_e32 v70, 0
	v_mov_b32_e32 v71, v143
	v_mov_b32_e32 v72, v143
	v_mov_b32_e32 v73, v143
	v_mov_b32_e32 v22, 0
	v_mov_b32_e32 v23, v143
	v_mov_b32_e32 v24, v143
	v_mov_b32_e32 v25, v143
	v_mov_b32_e32 v46, 0
	v_mov_b32_e32 v47, v143
	v_mov_b32_e32 v48, v143
	v_mov_b32_e32 v49, v143
	v_mov_b32_e32 v74, 0
	v_mov_b32_e32 v75, v143
	v_mov_b32_e32 v76, v143
	v_mov_b32_e32 v77, v143
	v_mov_b32_e32 v30, 0
	v_mov_b32_e32 v31, v143
	v_mov_b32_e32 v32, v143
	v_mov_b32_e32 v33, v143
	v_mov_b32_e32 v54, 0
	v_mov_b32_e32 v55, v143
	v_mov_b32_e32 v56, v143
	v_mov_b32_e32 v57, v143
	v_mov_b32_e32 v78, 0
	v_mov_b32_e32 v79, v143
	v_mov_b32_e32 v80, v143
	v_mov_b32_e32 v81, v143
	v_mov_b32_e32 v34, 0
	v_mov_b32_e32 v35, v143
	v_mov_b32_e32 v36, v143
	v_mov_b32_e32 v37, v143
	v_mov_b32_e32 v58, 0
	v_mov_b32_e32 v59, v143
	v_mov_b32_e32 v60, v143
	v_mov_b32_e32 v61, v143
	v_mov_b32_e32 v82, 0
	v_mov_b32_e32 v83, v143
	v_mov_b32_e32 v84, v143
	v_mov_b32_e32 v85, v143
	v_mov_b32_e32 v38, 0
	v_mov_b32_e32 v39, v143
	v_mov_b32_e32 v40, v143
	v_mov_b32_e32 v41, v143
	v_mov_b32_e32 v62, 0
	v_mov_b32_e32 v63, v143
	v_mov_b32_e32 v64, v143
	v_mov_b32_e32 v65, v143
	v_mov_b32_e32 v86, 0
	v_mov_b32_e32 v87, v143
	v_mov_b32_e32 v88, v143
	v_mov_b32_e32 v89, v143
	v_mov_b32_e32 v50, 0
	v_mov_b32_e32 v51, v143
	v_mov_b32_e32 v52, v143
	v_mov_b32_e32 v53, v143
	v_mov_b32_e32 v26, 0
	v_mov_b32_e32 v27, v143
	v_mov_b32_e32 v28, v143
	v_mov_b32_e32 v29, v143
	v_mov_b32_e32 v66, 0
	v_mov_b32_e32 v67, v143
	v_mov_b32_e32 v68, v143
	v_mov_b32_e32 v69, v143
	v_mov_b32_e32 v42, 0
	v_mov_b32_e32 v43, v143
	v_mov_b32_e32 v44, v143
	v_mov_b32_e32 v45, v143
	v_mov_b32_e32 v18, 0
	v_mov_b32_e32 v19, v143
	v_mov_b32_e32 v20, v143
	v_mov_b32_e32 v21, v143
	v_mov_b32_e32 v94, 0
	v_mov_b32_e32 v95, v143
.LBB0_2409:
	v_add_u32_e32 v220, v100, v141
	ds_read_b128 v[90:93], v220
	v_add_u32_e32 v221, v100, v142
	ds_read_b128 v[144:147], v221
	v_add_u32_e32 v222, v100, v140
	ds_read_b128 v[148:151], v222
	s_waitcnt lgkmcnt(2)
	v_lshlrev_b32_e32 v96, 16, v90
	v_fmac_f32_e32 v143, v96, v96
	v_and_b32_e32 v96, 0xffff0000, v90
	v_lshlrev_b32_e32 v97, 16, v91
	v_pk_mul_f32 v[96:97], v[96:97], v[96:97]
	v_lshl_add_u64 v[156:157], v[132:133], 0, s[12:13]
	v_add_f32_e32 v96, v96, v143
	v_add_f32_e32 v138, v97, v96
	v_and_b32_e32 v96, 0xffff0000, v91
	v_lshlrev_b32_e32 v97, 16, v92
	v_pk_mul_f32 v[96:97], v[96:97], v[96:97]
	v_lshl_add_u64 v[202:203], v[130:131], 0, s[12:13]
	v_add_f32_e32 v96, v96, v138
	v_add_f32_e32 v138, v97, v96
	v_and_b32_e32 v96, 0xffff0000, v92
	v_lshlrev_b32_e32 v97, 16, v93
	v_pk_mul_f32 v[96:97], v[96:97], v[96:97]
	v_lshl_add_u64 v[206:207], v[128:129], 0, s[12:13]
	v_add_f32_e32 v96, v96, v138
	v_add_f32_e32 v143, v97, v96
	v_and_b32_e32 v96, 0xffff0000, v93
	v_fmac_f32_e32 v143, v96, v96
	s_waitcnt lgkmcnt(1)
	v_lshlrev_b32_e32 v97, 16, v144
	s_waitcnt lgkmcnt(0)
	v_lshlrev_b32_e32 v96, 16, v148
	v_pk_fma_f32 v[94:95], v[96:97], v[96:97], v[94:95]
	v_and_b32_e32 v97, 0xffff0000, v144
	v_and_b32_e32 v96, 0xffff0000, v148
	v_pk_fma_f32 v[94:95], v[96:97], v[96:97], v[94:95]
	v_lshlrev_b32_e32 v97, 16, v145
	v_lshlrev_b32_e32 v96, 16, v149
	v_pk_fma_f32 v[94:95], v[96:97], v[96:97], v[94:95]
	v_and_b32_e32 v97, 0xffff0000, v145
	v_and_b32_e32 v96, 0xffff0000, v149
	v_pk_fma_f32 v[94:95], v[96:97], v[96:97], v[94:95]
	v_lshlrev_b32_e32 v97, 16, v146
	v_lshlrev_b32_e32 v96, 16, v150
	v_pk_fma_f32 v[94:95], v[96:97], v[96:97], v[94:95]
	v_and_b32_e32 v97, 0xffff0000, v146
	v_and_b32_e32 v96, 0xffff0000, v150
	v_pk_fma_f32 v[94:95], v[96:97], v[96:97], v[94:95]
	v_lshlrev_b32_e32 v97, 16, v147
	v_lshlrev_b32_e32 v96, 16, v151
	v_pk_fma_f32 v[94:95], v[96:97], v[96:97], v[94:95]
	v_and_b32_e32 v97, 0xffff0000, v147
	v_and_b32_e32 v96, 0xffff0000, v151
	v_pk_fma_f32 v[94:95], v[96:97], v[96:97], v[94:95]
	v_lshl_add_u64 v[96:97], v[136:137], 0, s[12:13]
	v_add_co_u32_e32 v96, vcc, s54, v96
	v_lshl_add_u64 v[138:139], v[134:135], 0, s[12:13]
	s_nop 0
	v_addc_co_u32_e32 v97, vcc, 0, v97, vcc
	v_add_co_u32_e32 v138, vcc, s54, v138
	v_lshl_add_u64 v[210:211], v[126:127], 0, s[12:13]
	s_nop 0
	v_addc_co_u32_e32 v139, vcc, 0, v139, vcc
	v_add_co_u32_e32 v156, vcc, s54, v156
	global_load_dwordx4 v[152:155], v[96:97], off
	global_load_dwordx4 v[194:197], v[138:139], off
	v_addc_co_u32_e32 v157, vcc, 0, v157, vcc
	v_add_co_u32_e32 v214, vcc, s54, v202
	global_load_dwordx4 v[198:201], v[156:157], off
	s_nop 0
	v_addc_co_u32_e32 v215, vcc, 0, v203, vcc
	v_add_co_u32_e32 v216, vcc, s54, v206
	global_load_dwordx4 v[202:205], v[214:215], off
	s_nop 0
	v_addc_co_u32_e32 v217, vcc, 0, v207, vcc
	v_add_co_u32_e32 v218, vcc, s54, v210
	global_load_dwordx4 v[206:209], v[216:217], off
	s_nop 0
	v_addc_co_u32_e32 v219, vcc, 0, v211, vcc
	global_load_dwordx4 v[210:213], v[218:219], off
	s_add_u32 s12, s12, 0x100
	s_addc_u32 s13, s13, 0
	v_add_u32_e32 v100, 0x100, v100
	s_cmpk_eq_i32 s12, 0x200
	s_waitcnt vmcnt(5)
	v_mfma_f32_16x16x32_bf16 v[86:89], v[152:155], v[90:93], v[86:89]
	s_waitcnt vmcnt(4)
; __device__ __forceinline__ float bf2f(bf16_t v) { return __uint_as_float(((unsigned)v) << 16); }
; #define LAS __attribute__((address_space(3)))
; __device__ __forceinline__ void ph_prep(bf16_t* Z, const bf16_t* WUQ, const bf16_t* WUKV, const bf16_t* D64, const float* qkq, const float* qkk,
;                                         bf16_t* Q, bf16_t* Kb, bf16_t* Vb, bf16_t* F1lat, bf16_t* F1ctx, unsigned char* lds_) { PH_IDS;
;     ...
;             for (int ks = 0; ks < 8; ++ks) {
;                 bf16x8 bq[3], aw[6];
; #pragma unroll
;                 for (int tt = 0; tt < 3; ++tt) { bq[tt] = *(const LAS bf16x8*)(sm + O_QC + rl[tt] * P_QC + (32 * ks + 8 * kq) * 2);
; #pragma unroll
;                     for (int e = 0; e < 8; ++e) { const float f = bf2f((bf16_t)bq[tt][e]); ssq[tt] += f * f; } }
; #pragma unroll
;                 for (int nt = 0; nt < 6; ++nt) aw[nt] = *(const bf16x8*)(WUQ + (size_t)(h * 96 + 16 * nt + c16) * 256 + 32 * ks + 8 * kq);
; #pragma unroll
;                 for (int nt = 0; nt < 6; ++nt)
; #pragma unroll
;                     for (int tt = 0; tt < 3; ++tt) acc[nt][tt] = __builtin_amdgcn_mfma_f32_16x16x32_bf16(aw[nt], bq[tt], acc[nt][tt], 0, 0, 0);
;             }
	v_mfma_f32_16x16x32_bf16 v[82:85], v[194:197], v[90:93], v[82:85]
	s_waitcnt vmcnt(3)
	v_mfma_f32_16x16x32_bf16 v[78:81], v[198:201], v[90:93], v[78:81]
	s_waitcnt vmcnt(2)
	v_mfma_f32_16x16x32_bf16 v[74:77], v[202:205], v[90:93], v[74:77]
	s_waitcnt vmcnt(1)
	v_mfma_f32_16x16x32_bf16 v[70:73], v[206:209], v[90:93], v[70:73]
	s_waitcnt vmcnt(0)
	v_mfma_f32_16x16x32_bf16 v[66:69], v[210:213], v[90:93], v[66:69]
	ds_read_b128 v[90:93], v220 offset:64
	v_mfma_f32_16x16x32_bf16 v[62:65], v[152:155], v[144:147], v[62:65]
	v_mfma_f32_16x16x32_bf16 v[58:61], v[194:197], v[144:147], v[58:61]
	v_mfma_f32_16x16x32_bf16 v[54:57], v[198:201], v[144:147], v[54:57]
	v_mfma_f32_16x16x32_bf16 v[46:49], v[202:205], v[144:147], v[46:49]
	v_mfma_f32_16x16x32_bf16 v[50:53], v[206:209], v[144:147], v[50:53]
	v_mfma_f32_16x16x32_bf16 v[42:45], v[210:213], v[144:147], v[42:45]
	s_waitcnt lgkmcnt(0)
	v_lshlrev_b32_e32 v144, 16, v90
	v_fmac_f32_e32 v143, v144, v144
	v_and_b32_e32 v144, 0xffff0000, v90
	v_lshlrev_b32_e32 v145, 16, v91
	v_pk_mul_f32 v[144:145], v[144:145], v[144:145]
	v_mfma_f32_16x16x32_bf16 v[38:41], v[152:155], v[148:151], v[38:41]
	v_add_f32_e32 v143, v144, v143
	v_add_f32_e32 v143, v145, v143
	v_and_b32_e32 v144, 0xffff0000, v91
	v_lshlrev_b32_e32 v145, 16, v92
	v_pk_mul_f32 v[144:145], v[144:145], v[144:145]
	v_mfma_f32_16x16x32_bf16 v[34:37], v[194:197], v[148:151], v[34:37]
	v_add_f32_e32 v143, v144, v143
	v_add_f32_e32 v143, v145, v143
	v_and_b32_e32 v144, 0xffff0000, v92
	v_lshlrev_b32_e32 v145, 16, v93
	v_pk_mul_f32 v[144:145], v[144:145], v[144:145]
	v_mfma_f32_16x16x32_bf16 v[30:33], v[198:201], v[148:151], v[30:33]
	v_add_f32_e32 v143, v144, v143
	v_add_f32_e32 v143, v145, v143
	v_and_b32_e32 v144, 0xffff0000, v93
	v_mfma_f32_16x16x32_bf16 v[22:25], v[202:205], v[148:151], v[22:25]
	v_fmac_f32_e32 v143, v144, v144
	v_mfma_f32_16x16x32_bf16 v[26:29], v[206:209], v[148:151], v[26:29]
	v_mfma_f32_16x16x32_bf16 v[18:21], v[210:213], v[148:151], v[18:21]
	ds_read_b128 v[144:147], v221 offset:64
	ds_read_b128 v[148:151], v222 offset:64
	s_waitcnt lgkmcnt(1)
	v_lshlrev_b32_e32 v153, 16, v144
	s_waitcnt lgkmcnt(0)
	v_lshlrev_b32_e32 v152, 16, v148
	v_pk_fma_f32 v[94:95], v[152:153], v[152:153], v[94:95]
	v_and_b32_e32 v153, 0xffff0000, v144
	v_and_b32_e32 v152, 0xffff0000, v148
	v_pk_fma_f32 v[94:95], v[152:153], v[152:153], v[94:95]
	v_lshlrev_b32_e32 v153, 16, v145
	v_lshlrev_b32_e32 v152, 16, v149
	v_pk_fma_f32 v[94:95], v[152:153], v[152:153], v[94:95]
	v_and_b32_e32 v153, 0xffff0000, v145
	v_and_b32_e32 v152, 0xffff0000, v149
	v_pk_fma_f32 v[94:95], v[152:153], v[152:153], v[94:95]
	v_lshlrev_b32_e32 v153, 16, v146
	v_lshlrev_b32_e32 v152, 16, v150
	v_pk_fma_f32 v[94:95], v[152:153], v[152:153], v[94:95]
	v_and_b32_e32 v153, 0xffff0000, v146
	v_and_b32_e32 v152, 0xffff0000, v150
	v_pk_fma_f32 v[94:95], v[152:153], v[152:153], v[94:95]
	v_lshlrev_b32_e32 v153, 16, v147
	v_lshlrev_b32_e32 v152, 16, v151
	v_pk_fma_f32 v[94:95], v[152:153], v[152:153], v[94:95]
	v_and_b32_e32 v153, 0xffff0000, v147
	v_and_b32_e32 v152, 0xffff0000, v151
	v_pk_fma_f32 v[94:95], v[152:153], v[152:153], v[94:95]
	global_load_dwordx4 v[152:155], v[96:97], off offset:64
	global_load_dwordx4 v[194:197], v[138:139], off offset:64
	global_load_dwordx4 v[198:201], v[156:157], off offset:64
	global_load_dwordx4 v[202:205], v[214:215], off offset:64
	global_load_dwordx4 v[206:209], v[216:217], off offset:64
	global_load_dwordx4 v[210:213], v[218:219], off offset:64
	s_waitcnt vmcnt(5)
	v_mfma_f32_16x16x32_bf16 v[86:89], v[152:155], v[90:93], v[86:89]
	s_waitcnt vmcnt(4)
	v_mfma_f32_16x16x32_bf16 v[82:85], v[194:197], v[90:93], v[82:85]
	s_waitcnt vmcnt(3)
	v_mfma_f32_16x16x32_bf16 v[78:81], v[198:201], v[90:93], v[78:81]
	s_waitcnt vmcnt(2)
	v_mfma_f32_16x16x32_bf16 v[74:77], v[202:205], v[90:93], v[74:77]
	s_waitcnt vmcnt(1)
	v_mfma_f32_16x16x32_bf16 v[70:73], v[206:209], v[90:93], v[70:73]
	s_waitcnt vmcnt(0)
	v_mfma_f32_16x16x32_bf16 v[66:69], v[210:213], v[90:93], v[66:69]
	ds_read_b128 v[90:93], v220 offset:128
	v_mfma_f32_16x16x32_bf16 v[62:65], v[152:155], v[144:147], v[62:65]
	v_mfma_f32_16x16x32_bf16 v[58:61], v[194:197], v[144:147], v[58:61]
	v_mfma_f32_16x16x32_bf16 v[54:57], v[198:201], v[144:147], v[54:57]
	v_mfma_f32_16x16x32_bf16 v[46:49], v[202:205], v[144:147], v[46:49]
	v_mfma_f32_16x16x32_bf16 v[50:53], v[206:209], v[144:147], v[50:53]
	v_mfma_f32_16x16x32_bf16 v[42:45], v[210:213], v[144:147], v[42:45]
	s_waitcnt lgkmcnt(0)
	v_lshlrev_b32_e32 v144, 16, v90
	v_fmac_f32_e32 v143, v144, v144
	v_and_b32_e32 v144, 0xffff0000, v90
	v_lshlrev_b32_e32 v145, 16, v91
	v_pk_mul_f32 v[144:145], v[144:145], v[144:145]
	v_mfma_f32_16x16x32_bf16 v[38:41], v[152:155], v[148:151], v[38:41]
	v_add_f32_e32 v143, v144, v143
	v_add_f32_e32 v143, v145, v143
	v_and_b32_e32 v144, 0xffff0000, v91
	v_lshlrev_b32_e32 v145, 16, v92
	v_pk_mul_f32 v[144:145], v[144:145], v[144:145]
	v_mfma_f32_16x16x32_bf16 v[34:37], v[194:197], v[148:151], v[34:37]
	v_add_f32_e32 v143, v144, v143
	v_add_f32_e32 v143, v145, v143
	v_and_b32_e32 v144, 0xffff0000, v92
	v_lshlrev_b32_e32 v145, 16, v93
	v_pk_mul_f32 v[144:145], v[144:145], v[144:145]
	v_mfma_f32_16x16x32_bf16 v[30:33], v[198:201], v[148:151], v[30:33]
	v_add_f32_e32 v143, v144, v143
	v_add_f32_e32 v143, v145, v143
	v_and_b32_e32 v144, 0xffff0000, v93
	v_mfma_f32_16x16x32_bf16 v[22:25], v[202:205], v[148:151], v[22:25]
	v_fmac_f32_e32 v143, v144, v144
	v_mfma_f32_16x16x32_bf16 v[26:29], v[206:209], v[148:151], v[26:29]
	v_mfma_f32_16x16x32_bf16 v[18:21], v[210:213], v[148:151], v[18:21]
	ds_read_b128 v[144:147], v221 offset:128
	ds_read_b128 v[148:151], v222 offset:128
	s_waitcnt lgkmcnt(1)
; __device__ __forceinline__ float bf2f(bf16_t v) { return __uint_as_float(((unsigned)v) << 16); }
; #define LAS __attribute__((address_space(3)))
; __device__ __forceinline__ void ph_prep(bf16_t* Z, const bf16_t* WUQ, const bf16_t* WUKV, const bf16_t* D64, const float* qkq, const float* qkk,
;                                         bf16_t* Q, bf16_t* Kb, bf16_t* Vb, bf16_t* F1lat, bf16_t* F1ctx, unsigned char* lds_) { PH_IDS;
;     ...
;             for (int ks = 0; ks < 8; ++ks) {
;                 bf16x8 bq[3], aw[6];
; #pragma unroll
;                 for (int tt = 0; tt < 3; ++tt) { bq[tt] = *(const LAS bf16x8*)(sm + O_QC + rl[tt] * P_QC + (32 * ks + 8 * kq) * 2);
; #pragma unroll
;                     for (int e = 0; e < 8; ++e) { const float f = bf2f((bf16_t)bq[tt][e]); ssq[tt] += f * f; } }
; #pragma unroll
;                 for (int nt = 0; nt < 6; ++nt) aw[nt] = *(const bf16x8*)(WUQ + (size_t)(h * 96 + 16 * nt + c16) * 256 + 32 * ks + 8 * kq);
; #pragma unroll
;                 for (int nt = 0; nt < 6; ++nt)
; #pragma unroll
;                     for (int tt = 0; tt < 3; ++tt) acc[nt][tt] = __builtin_amdgcn_mfma_f32_16x16x32_bf16(aw[nt], bq[tt], acc[nt][tt], 0, 0, 0);
;             }
	v_lshlrev_b32_e32 v153, 16, v144
	s_waitcnt lgkmcnt(0)
	v_lshlrev_b32_e32 v152, 16, v148
	v_pk_fma_f32 v[94:95], v[152:153], v[152:153], v[94:95]
	v_and_b32_e32 v153, 0xffff0000, v144
	v_and_b32_e32 v152, 0xffff0000, v148
	v_pk_fma_f32 v[94:95], v[152:153], v[152:153], v[94:95]
	v_lshlrev_b32_e32 v153, 16, v145
	v_lshlrev_b32_e32 v152, 16, v149
	v_pk_fma_f32 v[94:95], v[152:153], v[152:153], v[94:95]
	v_and_b32_e32 v153, 0xffff0000, v145
	v_and_b32_e32 v152, 0xffff0000, v149
	v_pk_fma_f32 v[94:95], v[152:153], v[152:153], v[94:95]
	v_lshlrev_b32_e32 v153, 16, v146
	v_lshlrev_b32_e32 v152, 16, v150
	v_pk_fma_f32 v[94:95], v[152:153], v[152:153], v[94:95]
	v_and_b32_e32 v153, 0xffff0000, v146
	v_and_b32_e32 v152, 0xffff0000, v150
	v_pk_fma_f32 v[94:95], v[152:153], v[152:153], v[94:95]
	v_lshlrev_b32_e32 v153, 16, v147
	v_lshlrev_b32_e32 v152, 16, v151
	v_pk_fma_f32 v[94:95], v[152:153], v[152:153], v[94:95]
	v_and_b32_e32 v153, 0xffff0000, v147
	v_and_b32_e32 v152, 0xffff0000, v151
	v_pk_fma_f32 v[94:95], v[152:153], v[152:153], v[94:95]
	global_load_dwordx4 v[152:155], v[96:97], off offset:128
	global_load_dwordx4 v[194:197], v[138:139], off offset:128
	global_load_dwordx4 v[198:201], v[156:157], off offset:128
	global_load_dwordx4 v[202:205], v[214:215], off offset:128
	global_load_dwordx4 v[206:209], v[216:217], off offset:128
	global_load_dwordx4 v[210:213], v[218:219], off offset:128
	s_waitcnt vmcnt(5)
	v_mfma_f32_16x16x32_bf16 v[86:89], v[152:155], v[90:93], v[86:89]
	s_waitcnt vmcnt(4)
	v_mfma_f32_16x16x32_bf16 v[82:85], v[194:197], v[90:93], v[82:85]
	s_waitcnt vmcnt(3)
	v_mfma_f32_16x16x32_bf16 v[78:81], v[198:201], v[90:93], v[78:81]
	s_waitcnt vmcnt(2)
	v_mfma_f32_16x16x32_bf16 v[74:77], v[202:205], v[90:93], v[74:77]
	s_waitcnt vmcnt(1)
	v_mfma_f32_16x16x32_bf16 v[70:73], v[206:209], v[90:93], v[70:73]
	s_waitcnt vmcnt(0)
	v_mfma_f32_16x16x32_bf16 v[66:69], v[210:213], v[90:93], v[66:69]
	ds_read_b128 v[90:93], v220 offset:192
	v_mfma_f32_16x16x32_bf16 v[62:65], v[152:155], v[144:147], v[62:65]
	v_mfma_f32_16x16x32_bf16 v[58:61], v[194:197], v[144:147], v[58:61]
	v_mfma_f32_16x16x32_bf16 v[54:57], v[198:201], v[144:147], v[54:57]
	v_mfma_f32_16x16x32_bf16 v[46:49], v[202:205], v[144:147], v[46:49]
	v_mfma_f32_16x16x32_bf16 v[50:53], v[206:209], v[144:147], v[50:53]
	v_mfma_f32_16x16x32_bf16 v[42:45], v[210:213], v[144:147], v[42:45]
	s_waitcnt lgkmcnt(0)
	v_lshlrev_b32_e32 v144, 16, v90
	v_fmac_f32_e32 v143, v144, v144
	v_and_b32_e32 v144, 0xffff0000, v90
	v_lshlrev_b32_e32 v145, 16, v91
	v_pk_mul_f32 v[144:145], v[144:145], v[144:145]
	v_mfma_f32_16x16x32_bf16 v[38:41], v[152:155], v[148:151], v[38:41]
	v_add_f32_e32 v143, v144, v143
	v_add_f32_e32 v143, v145, v143
	v_and_b32_e32 v144, 0xffff0000, v91
	v_lshlrev_b32_e32 v145, 16, v92
	v_pk_mul_f32 v[144:145], v[144:145], v[144:145]
	v_mfma_f32_16x16x32_bf16 v[34:37], v[194:197], v[148:151], v[34:37]
	v_add_f32_e32 v143, v144, v143
	v_add_f32_e32 v143, v145, v143
	v_and_b32_e32 v144, 0xffff0000, v92
	v_lshlrev_b32_e32 v145, 16, v93
	v_pk_mul_f32 v[144:145], v[144:145], v[144:145]
	v_mfma_f32_16x16x32_bf16 v[30:33], v[198:201], v[148:151], v[30:33]
	v_add_f32_e32 v143, v144, v143
	v_add_f32_e32 v143, v145, v143
	v_and_b32_e32 v144, 0xffff0000, v93
	v_mfma_f32_16x16x32_bf16 v[22:25], v[202:205], v[148:151], v[22:25]
	v_fmac_f32_e32 v143, v144, v144
	v_mfma_f32_16x16x32_bf16 v[26:29], v[206:209], v[148:151], v[26:29]
	v_mfma_f32_16x16x32_bf16 v[18:21], v[210:213], v[148:151], v[18:21]
	ds_read_b128 v[144:147], v221 offset:192
	ds_read_b128 v[148:151], v222 offset:192
	s_waitcnt lgkmcnt(1)
	v_lshlrev_b32_e32 v153, 16, v144
	s_waitcnt lgkmcnt(0)
	v_lshlrev_b32_e32 v152, 16, v148
	v_pk_fma_f32 v[94:95], v[152:153], v[152:153], v[94:95]
	v_and_b32_e32 v153, 0xffff0000, v144
	v_and_b32_e32 v152, 0xffff0000, v148
	v_pk_fma_f32 v[94:95], v[152:153], v[152:153], v[94:95]
	v_lshlrev_b32_e32 v153, 16, v145
	v_lshlrev_b32_e32 v152, 16, v149
	v_pk_fma_f32 v[94:95], v[152:153], v[152:153], v[94:95]
	v_and_b32_e32 v153, 0xffff0000, v145
	v_and_b32_e32 v152, 0xffff0000, v149
	v_pk_fma_f32 v[94:95], v[152:153], v[152:153], v[94:95]
	v_lshlrev_b32_e32 v153, 16, v146
	v_lshlrev_b32_e32 v152, 16, v150
	v_pk_fma_f32 v[94:95], v[152:153], v[152:153], v[94:95]
	v_and_b32_e32 v153, 0xffff0000, v146
	v_and_b32_e32 v152, 0xffff0000, v150
	v_pk_fma_f32 v[94:95], v[152:153], v[152:153], v[94:95]
	v_lshlrev_b32_e32 v153, 16, v147
	v_lshlrev_b32_e32 v152, 16, v151
	v_pk_fma_f32 v[94:95], v[152:153], v[152:153], v[94:95]
	v_and_b32_e32 v153, 0xffff0000, v147
	v_and_b32_e32 v152, 0xffff0000, v151
	v_pk_fma_f32 v[94:95], v[152:153], v[152:153], v[94:95]
	global_load_dwordx4 v[152:155], v[96:97], off offset:192
	global_load_dwordx4 v[194:197], v[138:139], off offset:192
	global_load_dwordx4 v[198:201], v[156:157], off offset:192
	global_load_dwordx4 v[202:205], v[214:215], off offset:192
	global_load_dwordx4 v[206:209], v[216:217], off offset:192
	global_load_dwordx4 v[210:213], v[218:219], off offset:192
	s_waitcnt vmcnt(5)
	v_mfma_f32_16x16x32_bf16 v[86:89], v[152:155], v[90:93], v[86:89]
	v_mfma_f32_16x16x32_bf16 v[62:65], v[152:155], v[144:147], v[62:65]
	v_mfma_f32_16x16x32_bf16 v[38:41], v[152:155], v[148:151], v[38:41]
	s_waitcnt vmcnt(4)
	v_mfma_f32_16x16x32_bf16 v[82:85], v[194:197], v[90:93], v[82:85]
	v_mfma_f32_16x16x32_bf16 v[58:61], v[194:197], v[144:147], v[58:61]
	v_mfma_f32_16x16x32_bf16 v[34:37], v[194:197], v[148:151], v[34:37]
	s_waitcnt vmcnt(3)
	v_mfma_f32_16x16x32_bf16 v[78:81], v[198:201], v[90:93], v[78:81]
	v_mfma_f32_16x16x32_bf16 v[54:57], v[198:201], v[144:147], v[54:57]
	v_mfma_f32_16x16x32_bf16 v[30:33], v[198:201], v[148:151], v[30:33]
	s_waitcnt vmcnt(2)
	v_mfma_f32_16x16x32_bf16 v[74:77], v[202:205], v[90:93], v[74:77]
	v_mfma_f32_16x16x32_bf16 v[46:49], v[202:205], v[144:147], v[46:49]
	v_mfma_f32_16x16x32_bf16 v[22:25], v[202:205], v[148:151], v[22:25]
	s_waitcnt vmcnt(1)
	v_mfma_f32_16x16x32_bf16 v[70:73], v[206:209], v[90:93], v[70:73]
	v_mfma_f32_16x16x32_bf16 v[50:53], v[206:209], v[144:147], v[50:53]
	v_mfma_f32_16x16x32_bf16 v[26:29], v[206:209], v[148:151], v[26:29]
	s_waitcnt vmcnt(0)
	v_mfma_f32_16x16x32_bf16 v[66:69], v[210:213], v[90:93], v[66:69]
	v_mfma_f32_16x16x32_bf16 v[42:45], v[210:213], v[144:147], v[42:45]
	v_mfma_f32_16x16x32_bf16 v[18:21], v[210:213], v[148:151], v[18:21]
	s_cbranch_scc0 .LBB0_2409
; __device__ __forceinline__ unsigned pk2(float lo, float hi) { unsigned r; asm volatile("v_cvt_pk_bf16_f32 %0, %1, %2" : "=v"(r) : "v"(lo), "v"(hi)); return r; }
; __device__ __forceinline__ void ph_prep(bf16_t* Z, const bf16_t* WUQ, const bf16_t* WUKV, const bf16_t* D64, const float* qkq, const float* qkk,
;                                         bf16_t* Q, bf16_t* Kb, bf16_t* Vb, bf16_t* F1lat, bf16_t* F1ctx, unsigned char* lds_) { PH_IDS;
;     ...
;             for (int tt = 0; tt < 3; ++tt) {
;                 float s1 = ssq[tt]; s1 += __shfl_xor(s1, 16); s1 += __shfl_xor(s1, 32);
;                 const float rstd = rsqrtf(s1 * (1.f / 256) + EPS);
;                 float ss = 0.f;
; #pragma unroll
;                 for (int nt = 0; nt < 6; ++nt)
; #pragma unroll
;                     for (int r = 0; r < 4; ++r) ss += acc[nt][tt][r] * acc[nt][tt][r];
;                 ss += __shfl_xor(ss, 16); ss += __shfl_xor(ss, 32);
;                 const float fac = rstd * rsqrtf(rstd * rstd * ss * (1.f / 96) + EPS) * 0.14724727430627066f;
;                 const int row = rowc[tt]; const bool lat = row < RL; const int b = row_batch(row), t = lat ? (row & 2047) : ((row - RL) & 255), qi = lat ? t : 2048 + t;
;                 bf16_t* qo = Q + ((size_t)(b * 4 + h) * 2304 + qi) * 96 + 4 * kq;
; #pragma unroll
;                 for (int nt = 0; nt < 6; ++nt) {
;                     const f32x4 w = *(const f32x4*)(qkq + 16 * nt + 4 * kq);
;                     float v[4];
; #pragma unroll
;                     for (int r = 0; r < 4; ++r) v[r] = acc[nt][tt][r] * fac * w[r];
;                     if (nt >= 4) rope16(v, kq, nt == 4 ? (float)(t >> 6) : (float)(t & 63), lat);
;                     fa::u32x2 o; o.x = fa::pk2(v[0], v[1]); o.y = fa::pk2(v[2], v[3]);
;                     if (valid[tt]) *(fa::u32x2*)(qo + 16 * nt) = o;
	v_mov_b64_e32 v[144:145], v[224:225]
	v_mov_b64_e32 v[146:147], v[226:227]
	v_mul_f32_e32 v150, v87, v87
	v_fmac_f32_e32 v150, v86, v86
	v_fmac_f32_e32 v150, v88, v88
	v_fmac_f32_e32 v150, v89, v89
	v_fmac_f32_e32 v150, v82, v82
	v_fmac_f32_e32 v150, v83, v83
	v_fmac_f32_e32 v150, v84, v84
	v_fmac_f32_e32 v150, v85, v85
	v_fmac_f32_e32 v150, v78, v78
	v_and_b32_e32 v91, 64, v1
	v_fmac_f32_e32 v150, v79, v79
	v_xor_b32_e32 v90, 16, v1
	v_add_u32_e32 v91, 64, v91
	v_fmac_f32_e32 v150, v80, v80
	v_cmp_lt_i32_e64 s[12:13], v90, v91
	v_fmac_f32_e32 v150, v81, v81
	v_xor_b32_e32 v100, 32, v1
	v_cndmask_b32_e64 v90, v1, v90, s[12:13]
	v_fmac_f32_e32 v150, v74, v74
	v_cmp_lt_i32_e64 s[12:13], v100, v91
	v_lshlrev_b32_e32 v91, 2, v90
	v_fmac_f32_e32 v150, v75, v75
	ds_bpermute_b32 v153, v91, v143
	v_fmac_f32_e32 v150, v76, v76
	v_pk_mul_f32 v[96:97], v[70:71], v[70:71]
	v_fmac_f32_e32 v150, v77, v77
	v_add_f32_e32 v96, v96, v150
	v_pk_mul_f32 v[92:93], v[72:73], v[72:73]
	v_add_f32_e32 v96, v97, v96
	v_cndmask_b32_e64 v100, v1, v100, s[12:13]
	v_add_f32_e32 v92, v92, v96
	v_pk_mul_f32 v[148:149], v[66:67], v[66:67]
	v_lshlrev_b32_e32 v90, 2, v100
	s_waitcnt lgkmcnt(0)
	v_add_f32_e32 v143, v143, v153
	v_add_f32_e32 v92, v93, v92
	ds_bpermute_b32 v153, v90, v143
	v_add_f32_e32 v92, v148, v92
	v_pk_mul_f32 v[138:139], v[68:69], v[68:69]
	v_add_f32_e32 v92, v149, v92
	v_add_f32_e32 v92, v138, v92
	v_add_f32_e32 v92, v139, v92
	ds_bpermute_b32 v93, v91, v92
	s_waitcnt lgkmcnt(1)
	v_add_f32_e32 v143, v143, v153
	v_fmamk_f32 v143, v143, 0x3b800000, v175
	v_mul_f32_e32 v96, 0x4b800000, v143
	v_cmp_gt_f32_e64 s[12:13], s53, v143
	v_cmp_gt_i32_e32 vcc, s50, v191
	s_waitcnt lgkmcnt(0)
	v_add_f32_e32 v97, v92, v93
	v_cndmask_b32_e64 v96, v143, v96, s[12:13]
	v_cndmask_b32_e32 v152, v177, v178, vcc
	v_rsq_f32_e32 v96, v96
	v_and_b32_e32 v152, v152, v191
	ds_bpermute_b32 v138, v90, v97
	v_cndmask_b32_e32 v151, v193, v192, vcc
	v_or_b32_e32 v100, 0x800, v152
	v_lshl_add_u32 v151, v151, 2, s29
	v_cndmask_b32_e32 v100, v100, v152, vcc
	v_mad_i64_i32 v[92:93], s[14:15], v151, s51, v[100:101]
	v_mul_f32_e32 v100, 0x45800000, v96
	v_cndmask_b32_e64 v100, v96, v100, s[12:13]
	v_mul_f32_e32 v96, v100, v100
	s_waitcnt lgkmcnt(0)
	v_add_f32_e32 v97, v97, v138
	v_mul_f32_e32 v96, v97, v96
	v_fmamk_f32 v96, v96, 0x3c2aaaab, v175
	v_mul_f32_e32 v97, 0x4b800000, v96
	v_cmp_gt_f32_e64 s[12:13], s53, v96
	s_nop 1
	v_cndmask_b32_e64 v96, v96, v97, s[12:13]
	v_rsq_f32_e32 v138, v96
	v_mad_u64_u32 v[96:97], s[14:15], v92, s52, v[110:111]
	v_mad_i32_i24 v97, v93, s52, v97
	v_mul_f32_e32 v92, 0x45800000, v138
	v_cndmask_b32_e64 v92, v138, v92, s[12:13]
	v_mul_f32_e32 v92, v100, v92
	v_mul_f32_e32 v92, 0x3e16c7fd, v92
	v_mul_f32_e32 v86, v86, v92
	v_mul_f32_e32 v87, v87, v92
	v_mul_f32_e32 v86, v144, v86
	v_mul_f32_e32 v87, v145, v87
	v_mul_f32_e32 v88, v88, v92
	v_mul_f32_e32 v89, v89, v92
	v_mul_f32_e32 v88, v146, v88
	v_mul_f32_e32 v89, v147, v89
	v_cvt_pk_bf16_f32 v86, v86, v87
	v_cvt_pk_bf16_f32 v87, v88, v89
	global_store_dwordx2 v[96:97], v[86:87], off
	v_mov_b64_e32 v[86:87], v[228:229]
	v_mov_b64_e32 v[88:89], v[230:231]
	v_mul_f32_e32 v82, v82, v92
	v_mul_f32_e32 v83, v83, v92
	v_mul_f32_e32 v84, v84, v92
	v_mul_f32_e32 v85, v85, v92
	v_mul_f32_e32 v78, v78, v92
	v_mul_f32_e32 v79, v79, v92
	v_mul_f32_e32 v80, v80, v92
	v_mul_f32_e32 v81, v81, v92
	v_mul_f32_e32 v74, v74, v92
	v_mul_f32_e32 v75, v75, v92
	v_mul_f32_e32 v76, v76, v92
	v_mul_f32_e32 v77, v77, v92
	v_mul_f32_e32 v70, v70, v92
	v_mul_f32_e32 v71, v71, v92
	v_mul_f32_e32 v72, v72, v92
	v_mul_f32_e32 v73, v73, v92
	v_mul_f32_e32 v66, v66, v92
	v_mul_f32_e32 v67, v67, v92
	v_mul_f32_e32 v68, v68, v92
	v_mul_f32_e32 v69, v69, v92
	v_mul_f32_e32 v82, v86, v82
	v_mul_f32_e32 v83, v87, v83
	v_mul_f32_e32 v84, v88, v84
	v_mul_f32_e32 v85, v89, v85
	v_cvt_pk_bf16_f32 v82, v82, v83
	v_cvt_pk_bf16_f32 v83, v84, v85
	global_store_dwordx2 v[96:97], v[82:83], off offset:32
	v_mov_b64_e32 v[82:83], v[232:233]
	v_mov_b64_e32 v[84:85], v[234:235]
	v_mul_f32_e32 v78, v82, v78
	v_mul_f32_e32 v79, v83, v79
	v_mul_f32_e32 v80, v84, v80
	v_mul_f32_e32 v81, v85, v81
	v_cvt_pk_bf16_f32 v78, v78, v79
	v_cvt_pk_bf16_f32 v79, v80, v81
	global_store_dwordx2 v[96:97], v[78:79], off offset:64
	v_mov_b64_e32 v[78:79], v[236:237]
	v_mov_b64_e32 v[80:81], v[238:239]
	v_mul_f32_e32 v74, v78, v74
	v_mul_f32_e32 v75, v79, v75
	v_mul_f32_e32 v76, v80, v76
	v_mul_f32_e32 v77, v81, v77
	v_cvt_pk_bf16_f32 v74, v74, v75
	v_cvt_pk_bf16_f32 v75, v76, v77
	global_store_dwordx2 v[96:97], v[74:75], off offset:96
	v_mov_b64_e32 v[74:75], v[240:241]
	v_mov_b64_e32 v[76:77], v[242:243]
	v_lshrrev_b32_e32 v78, 6, v152
	v_cvt_f32_ubyte0_e32 v78, v78
	v_mul_f32_e32 v79, v167, v78
	v_mul_f32_e32 v80, v166, v78
	v_mul_f32_e32 v81, v165, v78
	v_mul_f32_e32 v78, v164, v78
	v_mul_f32_e32 v81, 0.15915494, v81
	v_mul_f32_e32 v78, 0.15915494, v78
	v_mul_f32_e32 v79, 0.15915494, v79
	v_mul_f32_e32 v80, 0.15915494, v80
	v_cos_f32_e32 v84, v81
	v_sin_f32_e32 v81, v81
	v_cos_f32_e32 v85, v78
	v_sin_f32_e32 v78, v78
	v_cos_f32_e32 v82, v79
	v_sin_f32_e32 v79, v79
	v_cos_f32_e32 v83, v80
	v_sin_f32_e32 v80, v80
	v_mul_f32_e32 v70, v74, v70
	v_mul_f32_e32 v71, v75, v71
	v_mul_f32_e32 v72, v76, v72
	v_mul_f32_e32 v73, v77, v73
	ds_bpermute_b32 v76, v90, v71
	ds_bpermute_b32 v77, v90, v70
	ds_bpermute_b32 v74, v90, v73
	ds_bpermute_b32 v75, v90, v72
	s_waitcnt lgkmcnt(3)
; __device__ __forceinline__ unsigned pk2(float lo, float hi) { unsigned r; asm volatile("v_cvt_pk_bf16_f32 %0, %1, %2" : "=v"(r) : "v"(lo), "v"(hi)); return r; }
; __device__ __forceinline__ void rope16(float (&v)[4], int kq, float pos, bool on) {
; #pragma unroll
;     for (int r = 0; r < 4; ++r) {
;         const int j = (4 * kq + r) & 7;
;         const float ang = pos * exp2f(-(float)j * (13.287712379549449f / 8.f)), cs = __cosf(ang), sn = __sinf(ang);
;         const float other = __shfl_xor(v[r], 32);
;         const float rot = kq < 2 ? v[r] * cs - other * sn : other * sn + v[r] * cs;
;         v[r] = on ? rot : v[r];
;     }
; }
; __device__ __forceinline__ void ph_prep(bf16_t* Z, const bf16_t* WUQ, const bf16_t* WUKV, const bf16_t* D64, const float* qkq, const float* qkk,
;                                         bf16_t* Q, bf16_t* Kb, bf16_t* Vb, bf16_t* F1lat, bf16_t* F1ctx, unsigned char* lds_) { PH_IDS;
;     ...
;                 const int row = rowc[tt]; const bool lat = row < RL; const int b = row_batch(row), t = lat ? (row & 2047) : ((row - RL) & 255), qi = lat ? t : 2048 + t;
;                 bf16_t* qo = Q + ((size_t)(b * 4 + h) * 2304 + qi) * 96 + 4 * kq;
; #pragma unroll
;                 for (int nt = 0; nt < 6; ++nt) {
;                     const f32x4 w = *(const f32x4*)(qkq + 16 * nt + 4 * kq);
;                     float v[4];
; #pragma unroll
;                     for (int r = 0; r < 4; ++r) v[r] = acc[nt][tt][r] * fac * w[r];
;                     if (nt >= 4) rope16(v, kq, nt == 4 ? (float)(t >> 6) : (float)(t & 63), lat);
;                     fa::u32x2 o; o.x = fa::pk2(v[0], v[1]); o.y = fa::pk2(v[2], v[3]);
;                     if (valid[tt]) *(fa::u32x2*)(qo + 16 * nt) = o;
;                 }
	v_mul_f32_e32 v76, v81, v76
	s_waitcnt lgkmcnt(2)
	v_mul_f32_e32 v77, v78, v77
	s_waitcnt lgkmcnt(1)
	v_mul_f32_e32 v74, v79, v74
	s_waitcnt lgkmcnt(0)
	v_mul_f32_e32 v75, v80, v75
	v_cndmask_b32_e64 v76, v76, -v76, s[4:5]
	v_cndmask_b32_e64 v77, v77, -v77, s[4:5]
	v_cndmask_b32_e64 v74, v74, -v74, s[4:5]
	v_cndmask_b32_e64 v75, v75, -v75, s[4:5]
	v_fmac_f32_e32 v76, v84, v71
	v_fmac_f32_e32 v77, v85, v70
	v_fmac_f32_e32 v74, v82, v73
	v_fmac_f32_e32 v75, v83, v72
	v_cndmask_b32_e32 v71, v71, v76, vcc
	v_cndmask_b32_e32 v70, v70, v77, vcc
	v_cndmask_b32_e32 v73, v73, v74, vcc
	v_cndmask_b32_e32 v72, v72, v75, vcc
	v_cvt_pk_bf16_f32 v70, v70, v71
	v_cvt_pk_bf16_f32 v71, v72, v73
	global_store_dwordx2 v[96:97], v[70:71], off offset:128
	v_mov_b64_e32 v[70:71], v[244:245]
	v_mov_b64_e32 v[72:73], v[246:247]
	v_mul_f32_e32 v76, v165, v190
	v_mul_f32_e32 v77, v164, v190
	v_mul_f32_e32 v74, v167, v190
	v_mul_f32_e32 v75, v166, v190
	v_mul_f32_e32 v76, 0.15915494, v76
	v_mul_f32_e32 v77, 0.15915494, v77
	v_mul_f32_e32 v74, 0.15915494, v74
	v_mul_f32_e32 v75, 0.15915494, v75
	v_cos_f32_e32 v80, v76
	v_sin_f32_e32 v76, v76
	v_cos_f32_e32 v81, v77
	v_sin_f32_e32 v77, v77
	v_cos_f32_e32 v78, v74
	v_sin_f32_e32 v74, v74
	v_cos_f32_e32 v79, v75
	v_sin_f32_e32 v75, v75
	ds_bpermute_b32 v82, v91, v95
	v_mul_f32_e32 v66, v66, v70
	v_mul_f32_e32 v67, v67, v71
	v_mul_f32_e32 v68, v68, v72
	v_mul_f32_e32 v69, v69, v73
	ds_bpermute_b32 v72, v90, v67
	ds_bpermute_b32 v73, v90, v66
	ds_bpermute_b32 v70, v90, v69
	ds_bpermute_b32 v71, v90, v68
	s_waitcnt lgkmcnt(3)
	v_mul_f32_e32 v72, v76, v72
	s_waitcnt lgkmcnt(2)
	v_mul_f32_e32 v73, v77, v73
	s_waitcnt lgkmcnt(1)
	v_mul_f32_e32 v70, v74, v70
	s_waitcnt lgkmcnt(0)
	v_mul_f32_e32 v71, v75, v71
	v_cndmask_b32_e64 v72, v72, -v72, s[4:5]
	v_cndmask_b32_e64 v73, v73, -v73, s[4:5]
	v_cndmask_b32_e64 v70, v70, -v70, s[4:5]
	v_cndmask_b32_e64 v71, v71, -v71, s[4:5]
	v_fmac_f32_e32 v72, v80, v67
	v_fmac_f32_e32 v73, v81, v66
	v_fmac_f32_e32 v70, v78, v69
	v_fmac_f32_e32 v71, v79, v68
	v_cndmask_b32_e32 v67, v67, v72, vcc
	v_cndmask_b32_e32 v66, v66, v73, vcc
	v_cndmask_b32_e32 v69, v69, v70, vcc
	v_cndmask_b32_e32 v68, v68, v71, vcc
	v_cvt_pk_bf16_f32 v66, v66, v67
	v_cvt_pk_bf16_f32 v67, v68, v69
	global_store_dwordx2 v[96:97], v[66:67], off offset:160
	v_mov_b64_e32 v[70:71], v[224:225]
	v_mov_b64_e32 v[72:73], v[226:227]
	v_mul_f32_e32 v68, v63, v63
	v_fmac_f32_e32 v68, v62, v62
	v_fmac_f32_e32 v68, v64, v64
	v_fmac_f32_e32 v68, v65, v65
	v_fmac_f32_e32 v68, v58, v58
	v_fmac_f32_e32 v68, v59, v59
	v_fmac_f32_e32 v68, v60, v60
	v_fmac_f32_e32 v68, v61, v61
	v_fmac_f32_e32 v68, v54, v54
	v_fmac_f32_e32 v68, v55, v55
	v_fmac_f32_e32 v68, v56, v56
	v_fmac_f32_e32 v68, v57, v57
	v_fmac_f32_e32 v68, v46, v46
	v_fmac_f32_e32 v68, v47, v47
	v_fmac_f32_e32 v68, v48, v48
	v_pk_mul_f32 v[74:75], v[50:51], v[50:51]
	v_cmp_gt_i32_e32 vcc, s50, v187
	v_fmac_f32_e32 v68, v49, v49
	v_add_f32_e32 v68, v74, v68
	v_cndmask_b32_e32 v69, v189, v188, vcc
	v_cndmask_b32_e32 v80, v177, v178, vcc
	v_pk_mul_f32 v[66:67], v[52:53], v[52:53]
	v_lshl_add_u32 v81, v69, 2, s29
	v_and_b32_e32 v69, v80, v187
	v_add_f32_e32 v68, v75, v68
	v_or_b32_e32 v80, 0x800, v69
	v_add_f32_e32 v66, v66, v68
	v_pk_mul_f32 v[78:79], v[42:43], v[42:43]
	v_cndmask_b32_e32 v100, v80, v69, vcc
	v_add_f32_e32 v80, v95, v82
	v_add_f32_e32 v66, v67, v66
	ds_bpermute_b32 v82, v90, v80
	v_add_f32_e32 v66, v78, v66
	v_pk_mul_f32 v[76:77], v[44:45], v[44:45]
	v_add_f32_e32 v66, v79, v66
	v_add_f32_e32 v66, v76, v66
	v_add_f32_e32 v66, v77, v66
	ds_bpermute_b32 v67, v91, v66
	s_waitcnt lgkmcnt(1)
	v_add_f32_e32 v80, v80, v82
	v_fmamk_f32 v80, v80, 0x3b800000, v175
	v_mul_f32_e32 v68, 0x4b800000, v80
	v_cmp_gt_f32_e64 s[12:13], s53, v80
	s_waitcnt lgkmcnt(0)
	v_add_f32_e32 v66, v66, v67
	ds_bpermute_b32 v67, v90, v66
	v_cndmask_b32_e64 v68, v80, v68, s[12:13]
	v_rsq_f32_e32 v68, v68
	v_mad_i64_i32 v[74:75], s[14:15], v81, s51, v[100:101]
	s_waitcnt lgkmcnt(0)
	v_add_f32_e32 v66, v66, v67
	v_mul_f32_e32 v76, 0x45800000, v68
	v_cndmask_b32_e64 v68, v68, v76, s[12:13]
	v_mul_f32_e32 v76, v68, v68
	v_mul_f32_e32 v66, v66, v76
	v_fmamk_f32 v66, v66, 0x3c2aaaab, v175
	v_mul_f32_e32 v67, 0x4b800000, v66
	v_cmp_gt_f32_e64 s[12:13], s53, v66
	s_nop 1
	v_cndmask_b32_e64 v66, v66, v67, s[12:13]
	v_rsq_f32_e32 v76, v66
	v_mad_u64_u32 v[66:67], s[14:15], v74, s52, v[110:111]
	v_mad_i32_i24 v67, v75, s52, v67
	v_mul_f32_e32 v74, 0x45800000, v76
	v_cndmask_b32_e64 v74, v76, v74, s[12:13]
	v_mul_f32_e32 v68, v68, v74
	v_mul_f32_e32 v68, 0x3e16c7fd, v68
	v_mul_f32_e32 v62, v62, v68
	v_mul_f32_e32 v63, v63, v68
	v_mul_f32_e32 v64, v64, v68
	v_mul_f32_e32 v65, v65, v68
	v_mul_f32_e32 v62, v70, v62
	v_mul_f32_e32 v63, v71, v63
	v_mul_f32_e32 v64, v72, v64
	v_mul_f32_e32 v65, v73, v65
	v_cvt_pk_bf16_f32 v62, v62, v63
	v_cvt_pk_bf16_f32 v63, v64, v65
	s_and_saveexec_b64 s[12:13], s[10:11]
	s_cbranch_execz .LBB0_2412
	global_store_dwordx2 v[66:67], v[62:63], off

; __device__ __forceinline__ unsigned pk2(float lo, float hi) { unsigned r; asm volatile("v_cvt_pk_bf16_f32 %0, %1, %2" : "=v"(r) : "v"(lo), "v"(hi)); return r; }
; __device__ __forceinline__ void rope16(float (&v)[4], int kq, float pos, bool on) {
; #pragma unroll
;     for (int r = 0; r < 4; ++r) {
;         const int j = (4 * kq + r) & 7;
;         const float ang = pos * exp2f(-(float)j * (13.287712379549449f / 8.f)), cs = __cosf(ang), sn = __sinf(ang);
;         const float other = __shfl_xor(v[r], 32);
;         const float rot = kq < 2 ? v[r] * cs - other * sn : other * sn + v[r] * cs;
;         v[r] = on ? rot : v[r];
;     }
; }
; __device__ __forceinline__ void ph_prep(bf16_t* Z, const bf16_t* WUQ, const bf16_t* WUKV, const bf16_t* D64, const float* qkq, const float* qkk,
;                                         bf16_t* Q, bf16_t* Kb, bf16_t* Vb, bf16_t* F1lat, bf16_t* F1ctx, unsigned char* lds_) { PH_IDS;
;     ...
;             for (int tt = 0; tt < 3; ++tt) {
;                 float s1 = ssq[tt]; s1 += __shfl_xor(s1, 16); s1 += __shfl_xor(s1, 32);
;                 const float rstd = rsqrtf(s1 * (1.f / 256) + EPS);
;                 float ss = 0.f;
; #pragma unroll
;                 for (int nt = 0; nt < 6; ++nt)
; #pragma unroll
;                     for (int r = 0; r < 4; ++r) ss += acc[nt][tt][r] * acc[nt][tt][r];
;                 ss += __shfl_xor(ss, 16); ss += __shfl_xor(ss, 32);
;                 const float fac = rstd * rsqrtf(rstd * rstd * ss * (1.f / 96) + EPS) * 0.14724727430627066f;
;                 const int row = rowc[tt]; const bool lat = row < RL; const int b = row_batch(row), t = lat ? (row & 2047) : ((row - RL) & 255), qi = lat ? t : 2048 + t;
;                 bf16_t* qo = Q + ((size_t)(b * 4 + h) * 2304 + qi) * 96 + 4 * kq;
; #pragma unroll
;                 for (int nt = 0; nt < 6; ++nt) {
;                     const f32x4 w = *(const f32x4*)(qkq + 16 * nt + 4 * kq);
;                     float v[4];
; #pragma unroll
;                     for (int r = 0; r < 4; ++r) v[r] = acc[nt][tt][r] * fac * w[r];
;                     if (nt >= 4) rope16(v, kq, nt == 4 ? (float)(t >> 6) : (float)(t & 63), lat);
;                     fa::u32x2 o; o.x = fa::pk2(v[0], v[1]); o.y = fa::pk2(v[2], v[3]);
;                     if (valid[tt]) *(fa::u32x2*)(qo + 16 * nt) = o;
;                 }
.LBB0_2420:
	s_or_b64 exec, exec, s[12:13]
	v_mov_b64_e32 v[46:47], v[244:245]
	v_mov_b64_e32 v[48:49], v[246:247]
	v_mul_f32_e32 v42, v42, v68
	v_mul_f32_e32 v43, v43, v68
	v_mul_f32_e32 v44, v44, v68
	v_mul_f32_e32 v45, v45, v68
	v_mul_f32_e32 v52, v165, v186
	v_mul_f32_e32 v53, v164, v186
	v_mul_f32_e32 v50, v167, v186
	v_mul_f32_e32 v51, v166, v186
	v_mul_f32_e32 v52, 0.15915494, v52
	v_mul_f32_e32 v53, 0.15915494, v53
	v_mul_f32_e32 v50, 0.15915494, v50
	v_mul_f32_e32 v51, 0.15915494, v51
	v_cos_f32_e32 v56, v52
	v_sin_f32_e32 v52, v52
	v_cos_f32_e32 v57, v53
	v_sin_f32_e32 v53, v53
	v_cos_f32_e32 v54, v50
	v_sin_f32_e32 v50, v50
	v_cos_f32_e32 v55, v51
	v_sin_f32_e32 v51, v51
	v_mul_f32_e32 v42, v42, v46
	v_mul_f32_e32 v43, v43, v47
	v_mul_f32_e32 v44, v44, v48
	v_mul_f32_e32 v45, v45, v49
	ds_bpermute_b32 v48, v90, v43
	ds_bpermute_b32 v49, v90, v42
	ds_bpermute_b32 v46, v90, v45
	ds_bpermute_b32 v47, v90, v44
	s_waitcnt lgkmcnt(3)
	v_mul_f32_e32 v48, v52, v48
	s_waitcnt lgkmcnt(2)
	v_mul_f32_e32 v49, v53, v49
	s_waitcnt lgkmcnt(1)
	v_mul_f32_e32 v46, v50, v46
	s_waitcnt lgkmcnt(0)
	v_mul_f32_e32 v47, v51, v47
	v_cndmask_b32_e64 v48, v48, -v48, s[4:5]
	v_cndmask_b32_e64 v49, v49, -v49, s[4:5]
	v_cndmask_b32_e64 v46, v46, -v46, s[4:5]
	v_cndmask_b32_e64 v47, v47, -v47, s[4:5]
	v_fmac_f32_e32 v48, v56, v43
	v_fmac_f32_e32 v49, v57, v42
	v_fmac_f32_e32 v46, v54, v45
	v_fmac_f32_e32 v47, v55, v44
	v_cndmask_b32_e32 v43, v43, v48, vcc
	v_cndmask_b32_e32 v42, v42, v49, vcc
	v_cndmask_b32_e32 v45, v45, v46, vcc
	v_cndmask_b32_e32 v44, v44, v47, vcc
	v_cvt_pk_bf16_f32 v42, v42, v43
	v_cvt_pk_bf16_f32 v43, v44, v45
	s_and_saveexec_b64 s[12:13], s[10:11]
	s_cbranch_execz .LBB0_2422
	global_store_dwordx2 v[66:67], v[42:43], off offset:160
.LBB0_2422:
	s_or_b64 exec, exec, s[12:13]
	v_mov_b64_e32 v[46:47], v[224:225]
	v_mov_b64_e32 v[48:49], v[226:227]
	v_mul_f32_e32 v56, v39, v39
	v_fmac_f32_e32 v56, v38, v38
	v_fmac_f32_e32 v56, v40, v40
	v_fmac_f32_e32 v56, v41, v41
	v_fmac_f32_e32 v56, v34, v34
	v_fmac_f32_e32 v56, v35, v35
	v_fmac_f32_e32 v56, v36, v36
	v_fmac_f32_e32 v56, v37, v37
	v_fmac_f32_e32 v56, v30, v30
	v_fmac_f32_e32 v56, v31, v31
	v_fmac_f32_e32 v56, v32, v32
	v_fmac_f32_e32 v56, v33, v33
	v_fmac_f32_e32 v56, v22, v22
	v_fmac_f32_e32 v56, v23, v23
	ds_bpermute_b32 v44, v91, v94
	v_fmac_f32_e32 v56, v24, v24
	v_pk_mul_f32 v[50:51], v[26:27], v[26:27]
	v_fmac_f32_e32 v56, v25, v25
	v_cmp_gt_i32_e32 vcc, s50, v183
	v_add_f32_e32 v50, v50, v56
	v_pk_mul_f32 v[42:43], v[28:29], v[28:29]
	v_cndmask_b32_e32 v45, v185, v184, vcc
	v_cndmask_b32_e32 v57, v177, v178, vcc
	v_add_f32_e32 v50, v51, v50
	v_lshl_add_u32 v58, v45, 2, s29
	v_and_b32_e32 v45, v57, v183
	v_add_f32_e32 v42, v42, v50
	v_pk_mul_f32 v[54:55], v[18:19], v[18:19]
	v_or_b32_e32 v57, 0x800, v45
	s_waitcnt lgkmcnt(0)
	v_add_f32_e32 v44, v94, v44
	v_add_f32_e32 v42, v43, v42
	v_cndmask_b32_e32 v100, v57, v45, vcc
	ds_bpermute_b32 v57, v90, v44
	v_add_f32_e32 v42, v54, v42
	v_pk_mul_f32 v[52:53], v[20:21], v[20:21]
	v_add_f32_e32 v42, v55, v42
	v_add_f32_e32 v42, v52, v42
	v_add_f32_e32 v42, v53, v42
	ds_bpermute_b32 v43, v91, v42
	s_waitcnt lgkmcnt(1)
	v_add_f32_e32 v44, v44, v57
	v_fmamk_f32 v44, v44, 0x3b800000, v175
	v_mul_f32_e32 v50, 0x4b800000, v44
	v_cmp_gt_f32_e64 s[10:11], s53, v44
	s_waitcnt lgkmcnt(0)
	v_add_f32_e32 v42, v42, v43
	ds_bpermute_b32 v43, v90, v42
	v_cndmask_b32_e64 v44, v44, v50, s[10:11]
	v_rsq_f32_e32 v44, v44
	v_mad_i64_i32 v[50:51], s[12:13], v58, s51, v[100:101]
	s_waitcnt lgkmcnt(0)
	v_add_f32_e32 v42, v42, v43
	v_mul_f32_e32 v52, 0x45800000, v44
	v_cndmask_b32_e64 v44, v44, v52, s[10:11]
	v_mul_f32_e32 v52, v44, v44
	v_mul_f32_e32 v42, v42, v52
	v_fmamk_f32 v42, v42, 0x3c2aaaab, v175
	v_mul_f32_e32 v43, 0x4b800000, v42
	v_cmp_gt_f32_e64 s[10:11], s53, v42
	s_nop 1
	v_cndmask_b32_e64 v42, v42, v43, s[10:11]
	v_rsq_f32_e32 v52, v42
	v_mad_u64_u32 v[42:43], s[12:13], v50, s52, v[110:111]
	v_mad_i32_i24 v43, v51, s52, v43
	v_mul_f32_e32 v50, 0x45800000, v52
	v_cndmask_b32_e64 v50, v52, v50, s[10:11]
	v_mul_f32_e32 v44, v44, v50
	v_mul_f32_e32 v44, 0x3e16c7fd, v44
	v_mul_f32_e32 v38, v38, v44
	v_mul_f32_e32 v39, v39, v44
	v_mul_f32_e32 v40, v40, v44
	v_mul_f32_e32 v41, v41, v44
	v_mul_f32_e32 v38, v46, v38
	v_mul_f32_e32 v39, v47, v39
	v_mul_f32_e32 v40, v48, v40
	v_mul_f32_e32 v41, v49, v41
	v_cvt_pk_bf16_f32 v38, v38, v39
	v_cvt_pk_bf16_f32 v39, v40, v41
	s_and_saveexec_b64 s[10:11], s[8:9]
	s_cbranch_execz .LBB0_2424
	global_store_dwordx2 v[42:43], v[38:39], off

; __device__ __forceinline__ unsigned pk2(float lo, float hi) { unsigned r; asm volatile("v_cvt_pk_bf16_f32 %0, %1, %2" : "=v"(r) : "v"(lo), "v"(hi)); return r; }
; __device__ __forceinline__ void rope16(float (&v)[4], int kq, float pos, bool on) {
; #pragma unroll
;     for (int r = 0; r < 4; ++r) {
;         const int j = (4 * kq + r) & 7;
;         const float ang = pos * exp2f(-(float)j * (13.287712379549449f / 8.f)), cs = __cosf(ang), sn = __sinf(ang);
;         const float other = __shfl_xor(v[r], 32);
;         const float rot = kq < 2 ? v[r] * cs - other * sn : other * sn + v[r] * cs;
;         v[r] = on ? rot : v[r];
;     }
; }
; __device__ __forceinline__ void ph_prep(bf16_t* Z, const bf16_t* WUQ, const bf16_t* WUKV, const bf16_t* D64, const float* qkq, const float* qkk,
;                                         bf16_t* Q, bf16_t* Kb, bf16_t* Vb, bf16_t* F1lat, bf16_t* F1ctx, unsigned char* lds_) { PH_IDS;
;     ...
;                 for (int nt = 0; nt < 6; ++nt) {
;                     const f32x4 w = *(const f32x4*)(qkq + 16 * nt + 4 * kq);
;                     float v[4];
; #pragma unroll
;                     for (int r = 0; r < 4; ++r) v[r] = acc[nt][tt][r] * fac * w[r];
;                     if (nt >= 4) rope16(v, kq, nt == 4 ? (float)(t >> 6) : (float)(t & 63), lat);
;                     fa::u32x2 o; o.x = fa::pk2(v[0], v[1]); o.y = fa::pk2(v[2], v[3]);
;                     if (valid[tt]) *(fa::u32x2*)(qo + 16 * nt) = o;
;                 }
.LBB0_2432:
	s_or_b64 exec, exec, s[10:11]
	v_mov_b64_e32 v[22:23], v[244:245]
	v_mov_b64_e32 v[24:25], v[246:247]
	v_mul_f32_e32 v18, v18, v44
	v_mul_f32_e32 v19, v19, v44
	v_mul_f32_e32 v20, v20, v44
	v_mul_f32_e32 v21, v21, v44
	v_mul_f32_e32 v26, v164, v182
	v_mul_f32_e32 v27, v165, v182
	v_mul_f32_e32 v28, v166, v182
	v_mul_f32_e32 v29, v167, v182
	v_mul_f32_e32 v26, 0.15915494, v26
	v_mul_f32_e32 v27, 0.15915494, v27
	v_mul_f32_e32 v28, 0.15915494, v28
	v_mul_f32_e32 v29, 0.15915494, v29
	v_cos_f32_e32 v30, v26
	v_sin_f32_e32 v26, v26
	v_cos_f32_e32 v31, v27
	v_sin_f32_e32 v27, v27
	v_cos_f32_e32 v32, v28
	v_sin_f32_e32 v28, v28
	v_cos_f32_e32 v33, v29
	v_sin_f32_e32 v29, v29
	v_mul_f32_e32 v18, v18, v22
	v_mul_f32_e32 v19, v19, v23
	v_mul_f32_e32 v20, v20, v24
	v_mul_f32_e32 v21, v21, v25
	ds_bpermute_b32 v22, v90, v18
	ds_bpermute_b32 v23, v90, v19
	ds_bpermute_b32 v24, v90, v20
	ds_bpermute_b32 v25, v90, v21
	s_waitcnt lgkmcnt(3)
	v_mul_f32_e32 v22, v26, v22
	s_waitcnt lgkmcnt(2)
	v_mul_f32_e32 v23, v27, v23
	s_waitcnt lgkmcnt(1)
	v_mul_f32_e32 v24, v28, v24
	s_waitcnt lgkmcnt(0)
	v_mul_f32_e32 v25, v29, v25
	v_cndmask_b32_e64 v22, v22, -v22, s[4:5]
	v_cndmask_b32_e64 v23, v23, -v23, s[4:5]
	v_cndmask_b32_e64 v24, v24, -v24, s[4:5]
	v_cndmask_b32_e64 v25, v25, -v25, s[4:5]
	v_fmac_f32_e32 v22, v30, v18
	v_fmac_f32_e32 v23, v31, v19
	v_fmac_f32_e32 v24, v32, v20
	v_fmac_f32_e32 v25, v33, v21
	v_cndmask_b32_e32 v18, v18, v22, vcc
	v_cndmask_b32_e32 v19, v19, v23, vcc
	v_cndmask_b32_e32 v20, v20, v24, vcc
	v_cndmask_b32_e32 v21, v21, v25, vcc
	v_cvt_pk_bf16_f32 v18, v18, v19
	v_cvt_pk_bf16_f32 v19, v20, v21
	s_and_saveexec_b64 s[10:11], s[8:9]
	s_cbranch_execz .LBB0_2434
	global_store_dwordx2 v[42:43], v[18:19], off offset:160
